# attention tile loop: hand-scheduled fast path for unmasked tiles (8-slot LDS prefetch ring, permlane32_swap row max, softmax-1 under PV0 MFMAs, SALU LDS-DMA issue in PV1 gaps), bit-identical math
# speedup vs baseline: 1.0341x; 1.0341x over previous
.LBB0_845:
	s_cmp_ge_u32 s42, s82
	s_cselect_b64 s[18:19], -1, 0
	v_mov_b32_e32 v203, v176
	s_and_b64 vcc, exec, s[18:19]
	s_cbranch_vccnz .LBB0_847
	s_add_i32 s100, s43, 63
	s_cmp_le_i32 s100, s83
	s_cbranch_scc1 .LBB0_847
	v_sub_co_u32_e64 v128, s[34:35], s88, 1
	s_nop 1
	v_cndmask_b32_e64 v130, v128, 2, s[34:35]
	v_lshlrev_b32_e32 v128, 14, v130
	v_add_u32_e32 v131, s85, v128
	v_lshl_add_u64 v[128:129], s[14:15], 0, v[178:179]
	s_add_u32 s34, s14, 0x1000
	v_readfirstlane_b32 s89, v131
	s_mov_b32 s90, m0
	s_mov_b32 m0, s89
	s_nop 0
	global_load_lds_dwordx4 v[128:129], off
	s_mov_b32 m0, s90
	v_lshl_add_u64 v[128:129], s[14:15], 0, v[180:181]
	s_addc_u32 s35, s15, 0
	s_addk_i32 s89, 0x400
	s_mov_b32 s90, m0
	s_mov_b32 m0, s89
	s_nop 0
	global_load_lds_dwordx4 v[128:129], off
	s_mov_b32 m0, s90
	v_lshlrev_b32_e32 v128, 15, v130
	v_add_u32_e32 v130, s86, v128
	v_lshl_add_u64 v[128:129], s[34:35], 0, v[182:183]
	v_readfirstlane_b32 s89, v130
	s_mov_b32 s90, m0
	s_mov_b32 m0, s89
	s_nop 0
	global_load_lds_dwordx4 v[128:129], off
	s_mov_b32 m0, s90
	v_lshl_add_u64 v[128:129], s[34:35], 0, v[184:185]
	s_add_i32 s90, s89, 0x400
	s_mov_b32 s91, m0
	s_mov_b32 m0, s90
	s_nop 0
	global_load_lds_dwordx4 v[128:129], off
	s_mov_b32 m0, s91
	v_lshl_add_u64 v[128:129], s[34:35], 0, v[186:187]
	s_add_i32 s90, s89, 0x800
	s_mov_b32 s91, m0
	s_mov_b32 m0, s90
	s_nop 0
	global_load_lds_dwordx4 v[128:129], off
	s_mov_b32 m0, s91
	v_lshl_add_u64 v[128:129], s[34:35], 0, v[188:189]
	s_add_i32 s34, s89, 0xc00
	s_mov_b32 s35, m0
	s_mov_b32 m0, s34
	s_nop 0
	global_load_lds_dwordx4 v[128:129], off
	s_mov_b32 m0, s35
.LBB0_847:
	s_cmp_gt_i32 s43, s84
	s_cbranch_scc1 .LBB0_858
	s_add_i32 s100, s43, 63
	s_cmp_le_i32 s100, s83
	s_cbranch_scc0 .Latt_slow_0
	s_lshl_b32 s98, s88, 14
	s_lshl_b32 s99, s88, 15
	s_add_i32 s99, s99, 0xc000
	v_add_u32_e32 v206, s98, v194
	ds_read_b128 v[206:209], v206
	v_add_u32_e32 v210, s98, v195
	ds_read_b128 v[210:213], v210
	v_add_u32_e32 v214, s98, v196
	ds_read_b128 v[214:217], v214
	v_add_u32_e32 v222, s98, v197
	ds_read_b128 v[222:225], v222
	v_add_u32_e32 v226, s98, v198
	ds_read_b128 v[226:229], v226
	v_add_u32_e32 v230, s98, v199
	ds_read_b128 v[230:233], v230
	v_add_u32_e32 v234, s98, v200
	ds_read_b128 v[234:237], v234
	v_add_u32_e32 v238, s98, v201
	ds_read_b128 v[238:241], v238
	v_bfe_u32 v246, v203, 2, 2
	v_bfe_u32 v247, v203, 5, 1
	v_lshl_or_b32 v247, v247, 2, v246
	v_and_b32_e32 v249, 3, v203
	v_and_b32_e32 v254, 16, v203
	v_lshl_or_b32 v249, v249, 2, v254
	v_lshlrev_b32_e32 v249, 1, v249
	v_lshl_add_u32 v247, v247, 9, v249
	v_add_u32_e32 v247, s99, v247
	v_lshlrev_b32_e32 v246, 6, v246
	v_add_u32_e32 v205, v247, v246
	v_xor_b32_e32 v249, 64, v246
	v_add_u32_e32 v218, v247, v249
	v_xor_b32_e32 v249, 0x80, v246
	v_add_u32_e32 v219, v247, v249
	v_xor_b32_e32 v249, 0xc0, v246
	v_add_u32_e32 v221, v247, v249
	s_waitcnt lgkmcnt(7)
	v_mfma_f32_32x32x16_bf16 v[128:143], v[206:209], v[144:147], 0
	v_add_u32_e32 v206, s98, v194
	ds_read_b128 v[206:209], v206 offset:8192
	s_waitcnt lgkmcnt(7)
	v_mfma_f32_32x32x16_bf16 v[128:143], v[210:213], v[148:151], v[128:143]
	v_add_u32_e32 v210, s98, v195
	ds_read_b128 v[210:213], v210 offset:8192
	s_waitcnt lgkmcnt(7)
	v_mfma_f32_32x32x16_bf16 v[128:143], v[214:217], v[152:155], v[128:143]
	v_add_u32_e32 v214, s98, v196
	ds_read_b128 v[214:217], v214 offset:8192
	s_waitcnt lgkmcnt(7)
	v_mfma_f32_32x32x16_bf16 v[128:143], v[222:225], v[156:159], v[128:143]
	v_add_u32_e32 v222, s98, v197
	ds_read_b128 v[222:225], v222 offset:8192
	s_waitcnt lgkmcnt(7)
	v_mfma_f32_32x32x16_bf16 v[128:143], v[226:229], v[160:163], v[128:143]
	v_add_u32_e32 v226, s98, v198
	ds_read_b128 v[226:229], v226 offset:8192
	s_waitcnt lgkmcnt(7)
	v_mfma_f32_32x32x16_bf16 v[128:143], v[230:233], v[164:167], v[128:143]
	v_add_u32_e32 v230, s98, v199
	ds_read_b128 v[230:233], v230 offset:8192
	s_waitcnt lgkmcnt(7)
	v_mfma_f32_32x32x16_bf16 v[128:143], v[234:237], v[168:171], v[128:143]
	v_add_u32_e32 v234, s98, v200
	ds_read_b128 v[234:237], v234 offset:8192
	s_waitcnt lgkmcnt(7)
	v_mfma_f32_32x32x16_bf16 v[128:143], v[238:241], v[172:175], v[128:143]
	v_add_u32_e32 v238, s98, v201
	ds_read_b128 v[238:241], v238 offset:8192
	s_nop 9
	v_max3_f32 v246, v128, v129, v130
	v_max3_f32 v247, v131, v132, v133
	v_max3_f32 v246, v246, v134, v135
	v_max3_f32 v247, v247, v136, v137
	v_max3_f32 v246, v246, v138, v139
	v_max3_f32 v247, v247, v140, v141
	v_max3_f32 v246, v246, v142, v143
	v_max_f32_e32 v246, v246, v247
	v_mov_b32_e32 v247, v246
	v_add_f32_e32 v249, 0x41000000, v190
	s_nop 1
	v_permlane32_swap_b32_e32 v246, v247
	v_max_f32_e32 v246, v246, v247
	v_cmp_gt_f32_e32 vcc, v246, v249
	s_cbranch_vccz .Latt_nr0_0
	v_max_f32_e32 v246, v190, v246
	v_sub_f32_e32 v190, v190, v246
	v_exp_f32_e32 v190, v190
	s_nop 0
	v_pk_mul_f32 v[126:127], v[126:127], v[190:191] op_sel_hi:[1,0]
	v_pk_mul_f32 v[124:125], v[124:125], v[190:191] op_sel_hi:[1,0]
	v_pk_mul_f32 v[122:123], v[122:123], v[190:191] op_sel_hi:[1,0]
	v_pk_mul_f32 v[120:121], v[120:121], v[190:191] op_sel_hi:[1,0]
	v_pk_mul_f32 v[118:119], v[118:119], v[190:191] op_sel_hi:[1,0]
	v_pk_mul_f32 v[116:117], v[116:117], v[190:191] op_sel_hi:[1,0]
	v_pk_mul_f32 v[114:115], v[114:115], v[190:191] op_sel_hi:[1,0]
	v_pk_mul_f32 v[112:113], v[112:113], v[190:191] op_sel_hi:[1,0]
	v_pk_mul_f32 v[110:111], v[110:111], v[190:191] op_sel_hi:[1,0]
	v_pk_mul_f32 v[108:109], v[108:109], v[190:191] op_sel_hi:[1,0]
	v_pk_mul_f32 v[106:107], v[106:107], v[190:191] op_sel_hi:[1,0]
	v_pk_mul_f32 v[104:105], v[104:105], v[190:191] op_sel_hi:[1,0]
	v_pk_mul_f32 v[102:103], v[102:103], v[190:191] op_sel_hi:[1,0]
	v_pk_mul_f32 v[100:101], v[100:101], v[190:191] op_sel_hi:[1,0]
	v_pk_mul_f32 v[98:99], v[98:99], v[190:191] op_sel_hi:[1,0]
	v_pk_mul_f32 v[96:97], v[96:97], v[190:191] op_sel_hi:[1,0]
	v_pk_mul_f32 v[94:95], v[94:95], v[190:191] op_sel_hi:[1,0]
	v_pk_mul_f32 v[92:93], v[92:93], v[190:191] op_sel_hi:[1,0]
	v_pk_mul_f32 v[90:91], v[90:91], v[190:191] op_sel_hi:[1,0]
	v_pk_mul_f32 v[88:89], v[88:89], v[190:191] op_sel_hi:[1,0]
	v_pk_mul_f32 v[86:87], v[86:87], v[190:191] op_sel_hi:[1,0]
	v_pk_mul_f32 v[84:85], v[84:85], v[190:191] op_sel_hi:[1,0]
	v_pk_mul_f32 v[82:83], v[82:83], v[190:191] op_sel_hi:[1,0]
	v_pk_mul_f32 v[80:81], v[80:81], v[190:191] op_sel_hi:[1,0]
	v_pk_mul_f32 v[78:79], v[78:79], v[190:191] op_sel_hi:[1,0]
	v_pk_mul_f32 v[76:77], v[76:77], v[190:191] op_sel_hi:[1,0]
	v_pk_mul_f32 v[74:75], v[74:75], v[190:191] op_sel_hi:[1,0]
	v_pk_mul_f32 v[72:73], v[72:73], v[190:191] op_sel_hi:[1,0]
	v_pk_mul_f32 v[70:71], v[70:71], v[190:191] op_sel_hi:[1,0]
	v_pk_mul_f32 v[68:69], v[68:69], v[190:191] op_sel_hi:[1,0]
	v_pk_mul_f32 v[66:67], v[66:67], v[190:191] op_sel_hi:[1,0]
	v_pk_mul_f32 v[64:65], v[64:65], v[190:191] op_sel_hi:[1,0]
	v_pk_mul_f32 v[62:63], v[62:63], v[190:191] op_sel_hi:[1,0]
	v_pk_mul_f32 v[60:61], v[60:61], v[190:191] op_sel_hi:[1,0]
	v_pk_mul_f32 v[58:59], v[58:59], v[190:191] op_sel_hi:[1,0]
	v_pk_mul_f32 v[56:57], v[56:57], v[190:191] op_sel_hi:[1,0]
	v_pk_mul_f32 v[54:55], v[54:55], v[190:191] op_sel_hi:[1,0]
	v_pk_mul_f32 v[52:53], v[52:53], v[190:191] op_sel_hi:[1,0]
	v_pk_mul_f32 v[50:51], v[50:51], v[190:191] op_sel_hi:[1,0]
	v_pk_mul_f32 v[48:49], v[48:49], v[190:191] op_sel_hi:[1,0]
	v_pk_mul_f32 v[46:47], v[46:47], v[190:191] op_sel_hi:[1,0]
	v_pk_mul_f32 v[44:45], v[44:45], v[190:191] op_sel_hi:[1,0]
	v_pk_mul_f32 v[42:43], v[42:43], v[190:191] op_sel_hi:[1,0]
	v_pk_mul_f32 v[40:41], v[40:41], v[190:191] op_sel_hi:[1,0]
	v_pk_mul_f32 v[38:39], v[38:39], v[190:191] op_sel_hi:[1,0]
	v_pk_mul_f32 v[36:37], v[36:37], v[190:191] op_sel_hi:[1,0]
	v_pk_mul_f32 v[34:35], v[34:35], v[190:191] op_sel_hi:[1,0]
	v_pk_mul_f32 v[32:33], v[32:33], v[190:191] op_sel_hi:[1,0]
	v_pk_mul_f32 v[30:31], v[30:31], v[190:191] op_sel_hi:[1,0]
	v_pk_mul_f32 v[28:29], v[28:29], v[190:191] op_sel_hi:[1,0]
	v_pk_mul_f32 v[26:27], v[26:27], v[190:191] op_sel_hi:[1,0]
	v_pk_mul_f32 v[24:25], v[24:25], v[190:191] op_sel_hi:[1,0]
	v_pk_mul_f32 v[22:23], v[22:23], v[190:191] op_sel_hi:[1,0]
	v_pk_mul_f32 v[20:21], v[20:21], v[190:191] op_sel_hi:[1,0]
	v_pk_mul_f32 v[18:19], v[18:19], v[190:191] op_sel_hi:[1,0]
	v_pk_mul_f32 v[16:17], v[16:17], v[190:191] op_sel_hi:[1,0]
	v_pk_mul_f32 v[14:15], v[14:15], v[190:191] op_sel_hi:[1,0]
	v_pk_mul_f32 v[12:13], v[12:13], v[190:191] op_sel_hi:[1,0]
	v_pk_mul_f32 v[10:11], v[10:11], v[190:191] op_sel_hi:[1,0]
	v_pk_mul_f32 v[8:9], v[8:9], v[190:191] op_sel_hi:[1,0]
	v_pk_mul_f32 v[6:7], v[6:7], v[190:191] op_sel_hi:[1,0]
	v_pk_mul_f32 v[4:5], v[4:5], v[190:191] op_sel_hi:[1,0]
	v_pk_mul_f32 v[2:3], v[2:3], v[190:191] op_sel_hi:[1,0]
	v_pk_mul_f32 v[0:1], v[0:1], v[190:191] op_sel_hi:[1,0]
	v_mul_f32_e32 v202, v202, v190
	v_mov_b32_e32 v190, v246
.Latt_nr0_0:
	v_sub_f32_e32 v128, v128, v190
	v_exp_f32_e32 v128, v128
	v_sub_f32_e32 v129, v129, v190
	v_exp_f32_e32 v129, v129
	v_sub_f32_e32 v130, v130, v190
	v_add_f32_e32 v254, 0, v128
	v_exp_f32_e32 v130, v130
	v_sub_f32_e32 v131, v131, v190
	v_add_f32_e32 v254, v129, v254
	v_exp_f32_e32 v131, v131
	v_sub_f32_e32 v132, v132, v190
	v_add_f32_e32 v254, v130, v254
	v_exp_f32_e32 v132, v132
	v_sub_f32_e32 v133, v133, v190
	v_add_f32_e32 v254, v131, v254
	v_exp_f32_e32 v133, v133
	v_sub_f32_e32 v134, v134, v190
	v_add_f32_e32 v254, v132, v254
	v_exp_f32_e32 v134, v134
	v_sub_f32_e32 v135, v135, v190
	v_add_f32_e32 v254, v133, v254
	v_exp_f32_e32 v135, v135
	v_sub_f32_e32 v136, v136, v190
	v_add_f32_e32 v254, v134, v254
	v_exp_f32_e32 v136, v136
	v_sub_f32_e32 v137, v137, v190
	v_add_f32_e32 v254, v135, v254
	v_exp_f32_e32 v137, v137
	v_sub_f32_e32 v138, v138, v190
	v_add_f32_e32 v254, v136, v254
	v_exp_f32_e32 v138, v138
	v_sub_f32_e32 v139, v139, v190
	v_add_f32_e32 v254, v137, v254
	v_exp_f32_e32 v139, v139
	v_sub_f32_e32 v140, v140, v190
	v_add_f32_e32 v254, v138, v254
	v_exp_f32_e32 v140, v140
	v_sub_f32_e32 v141, v141, v190
	v_add_f32_e32 v254, v139, v254
	v_exp_f32_e32 v141, v141
	v_sub_f32_e32 v142, v142, v190
	v_add_f32_e32 v254, v140, v254
	v_exp_f32_e32 v142, v142
	v_sub_f32_e32 v143, v143, v190
	v_add_f32_e32 v254, v141, v254
	v_exp_f32_e32 v143, v143
	v_add_f32_e32 v254, v142, v254
	v_add_f32_e32 v254, v143, v254
	v_cvt_pk_bf16_f32 v242, v128, v129
	v_cvt_pk_bf16_f32 v243, v130, v131
	v_cvt_pk_bf16_f32 v244, v132, v133
	v_cvt_pk_bf16_f32 v245, v134, v135
	v_cvt_pk_bf16_f32 v250, v136, v137
	v_cvt_pk_bf16_f32 v251, v138, v139
	v_cvt_pk_bf16_f32 v252, v140, v141
	v_cvt_pk_bf16_f32 v253, v142, v143
	v_add_f32_e32 v202, v202, v254
	s_nop 1
	s_waitcnt lgkmcnt(7)
	v_mfma_f32_32x32x16_bf16 v[128:143], v[206:209], v[144:147], 0
	ds_read_b64_tr_b16 v[206:207], v205
	ds_read_b64_tr_b16 v[208:209], v205 offset:4096
	s_waitcnt lgkmcnt(8)
	v_mfma_f32_32x32x16_bf16 v[128:143], v[210:213], v[148:151], v[128:143]
	ds_read_b64_tr_b16 v[210:211], v218
	ds_read_b64_tr_b16 v[212:213], v218 offset:4096
	s_waitcnt lgkmcnt(9)
	v_mfma_f32_32x32x16_bf16 v[128:143], v[214:217], v[152:155], v[128:143]
	ds_read_b64_tr_b16 v[214:215], v219
	ds_read_b64_tr_b16 v[216:217], v219 offset:4096
	s_waitcnt lgkmcnt(10)
	v_mfma_f32_32x32x16_bf16 v[128:143], v[222:225], v[156:159], v[128:143]
	ds_read_b64_tr_b16 v[222:223], v221
	ds_read_b64_tr_b16 v[224:225], v221 offset:4096
	s_waitcnt lgkmcnt(11)
	v_mfma_f32_32x32x16_bf16 v[128:143], v[226:229], v[160:163], v[128:143]
	ds_read_b64_tr_b16 v[226:227], v205 offset:256
	ds_read_b64_tr_b16 v[228:229], v205 offset:4352
	s_waitcnt lgkmcnt(12)
	v_mfma_f32_32x32x16_bf16 v[128:143], v[230:233], v[164:167], v[128:143]
	ds_read_b64_tr_b16 v[230:231], v218 offset:256
	ds_read_b64_tr_b16 v[232:233], v218 offset:4352
	s_waitcnt lgkmcnt(13)
	v_mfma_f32_32x32x16_bf16 v[128:143], v[234:237], v[168:171], v[128:143]
	s_waitcnt lgkmcnt(12)
	v_mfma_f32_32x32x16_bf16 v[128:143], v[238:241], v[172:175], v[128:143]
	ds_read_b64_tr_b16 v[234:235], v219 offset:256
	ds_read_b64_tr_b16 v[236:237], v219 offset:4352
	s_waitcnt lgkmcnt(12)
	v_mfma_f32_32x32x16_bf16 v[112:127], v[206:209], v[242:245], v[112:127]
	ds_read_b64_tr_b16 v[238:239], v221 offset:256
	ds_read_b64_tr_b16 v[240:241], v221 offset:4352
	s_waitcnt lgkmcnt(12)
	v_mfma_f32_32x32x16_bf16 v[96:111], v[210:213], v[242:245], v[96:111]
	ds_read_b64_tr_b16 v[206:207], v205 offset:8192
	ds_read_b64_tr_b16 v[208:209], v205 offset:12288
	s_waitcnt lgkmcnt(12)
	v_mfma_f32_32x32x16_bf16 v[80:95], v[214:217], v[242:245], v[80:95]
	ds_read_b64_tr_b16 v[210:211], v218 offset:8192
	ds_read_b64_tr_b16 v[212:213], v218 offset:12288
	v_max3_f32 v246, v128, v129, v130
	v_max3_f32 v247, v131, v132, v133
	v_max3_f32 v246, v246, v134, v135
	v_max3_f32 v247, v247, v136, v137
	v_max3_f32 v246, v246, v138, v139
	v_max3_f32 v247, v247, v140, v141
	s_waitcnt lgkmcnt(12)
	v_mfma_f32_32x32x16_bf16 v[64:79], v[222:225], v[242:245], v[64:79]
	ds_read_b64_tr_b16 v[214:215], v219 offset:8192
	ds_read_b64_tr_b16 v[216:217], v219 offset:12288
	v_max3_f32 v246, v246, v142, v143
	v_max_f32_e32 v246, v246, v247
	v_mov_b32_e32 v247, v246
	v_add_f32_e32 v249, 0x41000000, v190
	s_nop 1
	s_waitcnt lgkmcnt(12)
	v_mfma_f32_32x32x16_bf16 v[48:63], v[226:229], v[242:245], v[48:63]
	ds_read_b64_tr_b16 v[222:223], v221 offset:8192
	ds_read_b64_tr_b16 v[224:225], v221 offset:12288
	v_permlane32_swap_b32_e32 v246, v247
	v_max_f32_e32 v246, v246, v247
	v_cmp_gt_f32_e32 vcc, v246, v249
	s_cbranch_vccnz .Latt_rs1_0
	s_waitcnt lgkmcnt(12)
	v_mfma_f32_32x32x16_bf16 v[32:47], v[230:233], v[242:245], v[32:47]
	ds_read_b64_tr_b16 v[226:227], v205 offset:8448
	ds_read_b64_tr_b16 v[228:229], v205 offset:12544
	v_sub_f32_e32 v128, v128, v190
	v_exp_f32_e32 v128, v128
	v_sub_f32_e32 v129, v129, v190
	v_exp_f32_e32 v129, v129
	v_sub_f32_e32 v130, v130, v190
	s_waitcnt lgkmcnt(12)
	v_mfma_f32_32x32x16_bf16 v[16:31], v[234:237], v[242:245], v[16:31]
	ds_read_b64_tr_b16 v[230:231], v218 offset:8448
	ds_read_b64_tr_b16 v[232:233], v218 offset:12544
	v_add_f32_e32 v254, 0, v128
	v_exp_f32_e32 v130, v130
	v_sub_f32_e32 v131, v131, v190
	v_add_f32_e32 v254, v129, v254
	v_exp_f32_e32 v131, v131
	s_waitcnt lgkmcnt(12)
	v_mfma_f32_32x32x16_bf16 v[0:15], v[238:241], v[242:245], v[0:15]
	ds_read_b64_tr_b16 v[234:235], v219 offset:8448
	ds_read_b64_tr_b16 v[236:237], v219 offset:12544
	v_sub_f32_e32 v132, v132, v190
	v_add_f32_e32 v254, v130, v254
	v_exp_f32_e32 v132, v132
	v_sub_f32_e32 v133, v133, v190
	v_add_f32_e32 v254, v131, v254
	s_waitcnt lgkmcnt(12)
	v_mfma_f32_32x32x16_bf16 v[112:127], v[206:209], v[250:253], v[112:127]
	ds_read_b64_tr_b16 v[238:239], v221 offset:8448
	ds_read_b64_tr_b16 v[240:241], v221 offset:12544
	v_exp_f32_e32 v133, v133
	v_sub_f32_e32 v134, v134, v190
	v_add_f32_e32 v254, v132, v254
	v_exp_f32_e32 v134, v134
	v_sub_f32_e32 v135, v135, v190
	s_waitcnt lgkmcnt(12)
	v_mfma_f32_32x32x16_bf16 v[96:111], v[210:213], v[250:253], v[96:111]
	ds_read_b64_tr_b16 v[206:207], v205 offset:16384
	ds_read_b64_tr_b16 v[208:209], v205 offset:20480
	v_add_f32_e32 v254, v133, v254
	v_exp_f32_e32 v135, v135
	v_sub_f32_e32 v136, v136, v190
	v_add_f32_e32 v254, v134, v254
	s_waitcnt lgkmcnt(12)
	v_mfma_f32_32x32x16_bf16 v[80:95], v[214:217], v[250:253], v[80:95]
	ds_read_b64_tr_b16 v[210:211], v218 offset:16384
	ds_read_b64_tr_b16 v[212:213], v218 offset:20480
	v_exp_f32_e32 v136, v136
	v_sub_f32_e32 v137, v137, v190
	v_add_f32_e32 v254, v135, v254
	v_exp_f32_e32 v137, v137
	s_waitcnt lgkmcnt(12)
	v_mfma_f32_32x32x16_bf16 v[64:79], v[222:225], v[250:253], v[64:79]
	ds_read_b64_tr_b16 v[214:215], v219 offset:16384
	ds_read_b64_tr_b16 v[216:217], v219 offset:20480
	v_sub_f32_e32 v138, v138, v190
	v_add_f32_e32 v254, v136, v254
	v_exp_f32_e32 v138, v138
	v_sub_f32_e32 v139, v139, v190
	s_waitcnt lgkmcnt(12)
	v_mfma_f32_32x32x16_bf16 v[48:63], v[226:229], v[250:253], v[48:63]
	ds_read_b64_tr_b16 v[222:223], v221 offset:16384
	ds_read_b64_tr_b16 v[224:225], v221 offset:20480
	v_add_f32_e32 v254, v137, v254
	v_exp_f32_e32 v139, v139
	v_sub_f32_e32 v140, v140, v190
	v_add_f32_e32 v254, v138, v254
	s_waitcnt lgkmcnt(12)
	v_mfma_f32_32x32x16_bf16 v[32:47], v[230:233], v[250:253], v[32:47]
	ds_read_b64_tr_b16 v[226:227], v205 offset:16640
	ds_read_b64_tr_b16 v[228:229], v205 offset:20736
	v_exp_f32_e32 v140, v140
	v_sub_f32_e32 v141, v141, v190
	v_add_f32_e32 v254, v139, v254
	v_exp_f32_e32 v141, v141
	s_waitcnt lgkmcnt(12)
	v_mfma_f32_32x32x16_bf16 v[16:31], v[234:237], v[250:253], v[16:31]
	ds_read_b64_tr_b16 v[230:231], v218 offset:16640
	ds_read_b64_tr_b16 v[232:233], v218 offset:20736
	v_sub_f32_e32 v142, v142, v190
	v_add_f32_e32 v254, v140, v254
	v_exp_f32_e32 v142, v142
	v_sub_f32_e32 v143, v143, v190
	s_waitcnt lgkmcnt(12)
	v_mfma_f32_32x32x16_bf16 v[0:15], v[238:241], v[250:253], v[0:15]
	ds_read_b64_tr_b16 v[234:235], v219 offset:16640
	ds_read_b64_tr_b16 v[236:237], v219 offset:20736
	v_add_f32_e32 v254, v141, v254
	v_exp_f32_e32 v143, v143
	v_add_f32_e32 v254, v142, v254
	v_add_f32_e32 v254, v143, v254
	v_cvt_pk_bf16_f32 v242, v128, v129
	v_cvt_pk_bf16_f32 v243, v130, v131
	v_cvt_pk_bf16_f32 v244, v132, v133
	v_cvt_pk_bf16_f32 v245, v134, v135
	v_cvt_pk_bf16_f32 v250, v136, v137
	v_cvt_pk_bf16_f32 v251, v138, v139
	v_cvt_pk_bf16_f32 v252, v140, v141
	v_cvt_pk_bf16_f32 v253, v142, v143
	v_add_f32_e32 v202, v202, v254
	s_nop 1
.Latt_pv1_0:
	s_waitcnt lgkmcnt(12)
	v_mfma_f32_32x32x16_bf16 v[112:127], v[206:209], v[242:245], v[112:127]
	ds_read_b64_tr_b16 v[238:239], v221 offset:16640
	ds_read_b64_tr_b16 v[240:241], v221 offset:20736
	s_waitcnt lgkmcnt(12)
	v_mfma_f32_32x32x16_bf16 v[96:111], v[210:213], v[242:245], v[96:111]
	ds_read_b64_tr_b16 v[206:207], v205 offset:24576
	ds_read_b64_tr_b16 v[208:209], v205 offset:28672
	s_cmp_lg_u64 s[18:19], 0
	s_cbranch_scc1 .Latt_nd0_0
	s_sub_i32 s100, s88, 1
	s_cmp_eq_u32 s88, 0
	s_cselect_b32 s100, 2, s100
	s_lshl_b32 s101, s100, 14
	s_add_i32 m0, s85, s101
	s_nop 0
	global_load_lds_dwordx4 v178, s[14:15]
.Latt_nd0_0:
	s_waitcnt lgkmcnt(12)
	v_mfma_f32_32x32x16_bf16 v[80:95], v[214:217], v[242:245], v[80:95]
	ds_read_b64_tr_b16 v[210:211], v218 offset:24576
	ds_read_b64_tr_b16 v[212:213], v218 offset:28672
	s_waitcnt lgkmcnt(12)
	v_mfma_f32_32x32x16_bf16 v[64:79], v[222:225], v[242:245], v[64:79]
	ds_read_b64_tr_b16 v[214:215], v219 offset:24576
	ds_read_b64_tr_b16 v[216:217], v219 offset:28672
	s_cmp_lg_u64 s[18:19], 0
	s_cbranch_scc1 .Latt_nd1_0
	s_add_i32 m0, m0, 0x400
	s_nop 0
	global_load_lds_dwordx4 v180, s[14:15]
.Latt_nd1_0:
	s_waitcnt lgkmcnt(12)
	v_mfma_f32_32x32x16_bf16 v[48:63], v[226:229], v[242:245], v[48:63]
	ds_read_b64_tr_b16 v[222:223], v221 offset:24576
	ds_read_b64_tr_b16 v[224:225], v221 offset:28672
	s_waitcnt lgkmcnt(12)
	v_mfma_f32_32x32x16_bf16 v[32:47], v[230:233], v[242:245], v[32:47]
	ds_read_b64_tr_b16 v[226:227], v205 offset:24832
	ds_read_b64_tr_b16 v[228:229], v205 offset:28928
	s_cmp_lg_u64 s[18:19], 0
	s_cbranch_scc1 .Latt_nd2_0
	s_lshl_b32 s101, s100, 15
	s_add_i32 m0, s86, s101
	s_add_u32 s100, s14, 0x1000
	s_addc_u32 s101, s15, 0
	global_load_lds_dwordx4 v182, s[100:101]
.Latt_nd2_0:
	s_waitcnt lgkmcnt(12)
	v_mfma_f32_32x32x16_bf16 v[16:31], v[234:237], v[242:245], v[16:31]
	ds_read_b64_tr_b16 v[230:231], v218 offset:24832
	ds_read_b64_tr_b16 v[232:233], v218 offset:28928
	s_waitcnt lgkmcnt(12)
	v_mfma_f32_32x32x16_bf16 v[0:15], v[238:241], v[242:245], v[0:15]
	ds_read_b64_tr_b16 v[234:235], v219 offset:24832
	ds_read_b64_tr_b16 v[236:237], v219 offset:28928
	s_cmp_lg_u64 s[18:19], 0
	s_cbranch_scc1 .Latt_nd3_0
	s_add_i32 m0, m0, 0x400
	s_nop 0
	global_load_lds_dwordx4 v184, s[100:101]
.Latt_nd3_0:
	s_waitcnt lgkmcnt(12)
	v_mfma_f32_32x32x16_bf16 v[112:127], v[206:209], v[250:253], v[112:127]
	ds_read_b64_tr_b16 v[238:239], v221 offset:24832
	ds_read_b64_tr_b16 v[240:241], v221 offset:28928
	s_waitcnt lgkmcnt(12)
	v_mfma_f32_32x32x16_bf16 v[96:111], v[210:213], v[250:253], v[96:111]
	s_cmp_lg_u64 s[18:19], 0
	s_cbranch_scc1 .Latt_nd4_0
	s_add_i32 m0, m0, 0x400
	s_nop 0
	global_load_lds_dwordx4 v186, s[100:101]
.Latt_nd4_0:
	s_waitcnt lgkmcnt(10)
	v_mfma_f32_32x32x16_bf16 v[80:95], v[214:217], v[250:253], v[80:95]
	s_waitcnt lgkmcnt(8)
	v_mfma_f32_32x32x16_bf16 v[64:79], v[222:225], v[250:253], v[64:79]
	s_cmp_lg_u64 s[18:19], 0
	s_cbranch_scc1 .Latt_nd5_0
	s_add_i32 m0, m0, 0x400
	s_nop 0
	global_load_lds_dwordx4 v188, s[100:101]
.Latt_nd5_0:
	s_waitcnt lgkmcnt(6)
	v_mfma_f32_32x32x16_bf16 v[48:63], v[226:229], v[250:253], v[48:63]
	s_waitcnt lgkmcnt(4)
	v_mfma_f32_32x32x16_bf16 v[32:47], v[230:233], v[250:253], v[32:47]
	s_waitcnt lgkmcnt(2)
	v_mfma_f32_32x32x16_bf16 v[16:31], v[234:237], v[250:253], v[16:31]
	s_waitcnt lgkmcnt(0)
	v_mfma_f32_32x32x16_bf16 v[0:15], v[238:241], v[250:253], v[0:15]
	s_branch .LBB0_858
.Latt_rs1_0:
	s_waitcnt lgkmcnt(12)
	v_mfma_f32_32x32x16_bf16 v[32:47], v[230:233], v[242:245], v[32:47]
	ds_read_b64_tr_b16 v[226:227], v205 offset:8448
	ds_read_b64_tr_b16 v[228:229], v205 offset:12544
	s_waitcnt lgkmcnt(12)
	v_mfma_f32_32x32x16_bf16 v[16:31], v[234:237], v[242:245], v[16:31]
	ds_read_b64_tr_b16 v[230:231], v218 offset:8448
	ds_read_b64_tr_b16 v[232:233], v218 offset:12544
	s_waitcnt lgkmcnt(12)
	v_mfma_f32_32x32x16_bf16 v[0:15], v[238:241], v[242:245], v[0:15]
	ds_read_b64_tr_b16 v[234:235], v219 offset:8448
	ds_read_b64_tr_b16 v[236:237], v219 offset:12544
	s_waitcnt lgkmcnt(12)
	v_mfma_f32_32x32x16_bf16 v[112:127], v[206:209], v[250:253], v[112:127]
	ds_read_b64_tr_b16 v[238:239], v221 offset:8448
	ds_read_b64_tr_b16 v[240:241], v221 offset:12544
	s_waitcnt lgkmcnt(12)
	v_mfma_f32_32x32x16_bf16 v[96:111], v[210:213], v[250:253], v[96:111]
	ds_read_b64_tr_b16 v[206:207], v205 offset:16384
	ds_read_b64_tr_b16 v[208:209], v205 offset:20480
	s_waitcnt lgkmcnt(12)
	v_mfma_f32_32x32x16_bf16 v[80:95], v[214:217], v[250:253], v[80:95]
	ds_read_b64_tr_b16 v[210:211], v218 offset:16384
	ds_read_b64_tr_b16 v[212:213], v218 offset:20480
	s_waitcnt lgkmcnt(12)
	v_mfma_f32_32x32x16_bf16 v[64:79], v[222:225], v[250:253], v[64:79]
	ds_read_b64_tr_b16 v[214:215], v219 offset:16384
	ds_read_b64_tr_b16 v[216:217], v219 offset:20480
	s_waitcnt lgkmcnt(12)
	v_mfma_f32_32x32x16_bf16 v[48:63], v[226:229], v[250:253], v[48:63]
	ds_read_b64_tr_b16 v[222:223], v221 offset:16384
	ds_read_b64_tr_b16 v[224:225], v221 offset:20480
	s_waitcnt lgkmcnt(12)
	v_mfma_f32_32x32x16_bf16 v[32:47], v[230:233], v[250:253], v[32:47]
	ds_read_b64_tr_b16 v[226:227], v205 offset:16640
	ds_read_b64_tr_b16 v[228:229], v205 offset:20736
	s_waitcnt lgkmcnt(12)
	v_mfma_f32_32x32x16_bf16 v[16:31], v[234:237], v[250:253], v[16:31]
	ds_read_b64_tr_b16 v[230:231], v218 offset:16640
	ds_read_b64_tr_b16 v[232:233], v218 offset:20736
	s_waitcnt lgkmcnt(12)
	v_mfma_f32_32x32x16_bf16 v[0:15], v[238:241], v[250:253], v[0:15]
	ds_read_b64_tr_b16 v[234:235], v219 offset:16640
	ds_read_b64_tr_b16 v[236:237], v219 offset:20736
	s_nop 11
	v_max_f32_e32 v246, v190, v246
	v_sub_f32_e32 v190, v190, v246
	v_exp_f32_e32 v190, v190
	s_nop 0
	v_pk_mul_f32 v[126:127], v[126:127], v[190:191] op_sel_hi:[1,0]
	v_pk_mul_f32 v[124:125], v[124:125], v[190:191] op_sel_hi:[1,0]
	v_pk_mul_f32 v[122:123], v[122:123], v[190:191] op_sel_hi:[1,0]
	v_pk_mul_f32 v[120:121], v[120:121], v[190:191] op_sel_hi:[1,0]
	v_pk_mul_f32 v[118:119], v[118:119], v[190:191] op_sel_hi:[1,0]
	v_pk_mul_f32 v[116:117], v[116:117], v[190:191] op_sel_hi:[1,0]
	v_pk_mul_f32 v[114:115], v[114:115], v[190:191] op_sel_hi:[1,0]
	v_pk_mul_f32 v[112:113], v[112:113], v[190:191] op_sel_hi:[1,0]
	v_pk_mul_f32 v[110:111], v[110:111], v[190:191] op_sel_hi:[1,0]
	v_pk_mul_f32 v[108:109], v[108:109], v[190:191] op_sel_hi:[1,0]
	v_pk_mul_f32 v[106:107], v[106:107], v[190:191] op_sel_hi:[1,0]
	v_pk_mul_f32 v[104:105], v[104:105], v[190:191] op_sel_hi:[1,0]
	v_pk_mul_f32 v[102:103], v[102:103], v[190:191] op_sel_hi:[1,0]
	v_pk_mul_f32 v[100:101], v[100:101], v[190:191] op_sel_hi:[1,0]
	v_pk_mul_f32 v[98:99], v[98:99], v[190:191] op_sel_hi:[1,0]
	v_pk_mul_f32 v[96:97], v[96:97], v[190:191] op_sel_hi:[1,0]
	v_pk_mul_f32 v[94:95], v[94:95], v[190:191] op_sel_hi:[1,0]
	v_pk_mul_f32 v[92:93], v[92:93], v[190:191] op_sel_hi:[1,0]
	v_pk_mul_f32 v[90:91], v[90:91], v[190:191] op_sel_hi:[1,0]
	v_pk_mul_f32 v[88:89], v[88:89], v[190:191] op_sel_hi:[1,0]
	v_pk_mul_f32 v[86:87], v[86:87], v[190:191] op_sel_hi:[1,0]
	v_pk_mul_f32 v[84:85], v[84:85], v[190:191] op_sel_hi:[1,0]
	v_pk_mul_f32 v[82:83], v[82:83], v[190:191] op_sel_hi:[1,0]
	v_pk_mul_f32 v[80:81], v[80:81], v[190:191] op_sel_hi:[1,0]
	v_pk_mul_f32 v[78:79], v[78:79], v[190:191] op_sel_hi:[1,0]
	v_pk_mul_f32 v[76:77], v[76:77], v[190:191] op_sel_hi:[1,0]
	v_pk_mul_f32 v[74:75], v[74:75], v[190:191] op_sel_hi:[1,0]
	v_pk_mul_f32 v[72:73], v[72:73], v[190:191] op_sel_hi:[1,0]
	v_pk_mul_f32 v[70:71], v[70:71], v[190:191] op_sel_hi:[1,0]
	v_pk_mul_f32 v[68:69], v[68:69], v[190:191] op_sel_hi:[1,0]
	v_pk_mul_f32 v[66:67], v[66:67], v[190:191] op_sel_hi:[1,0]
	v_pk_mul_f32 v[64:65], v[64:65], v[190:191] op_sel_hi:[1,0]
	v_pk_mul_f32 v[62:63], v[62:63], v[190:191] op_sel_hi:[1,0]
	v_pk_mul_f32 v[60:61], v[60:61], v[190:191] op_sel_hi:[1,0]
	v_pk_mul_f32 v[58:59], v[58:59], v[190:191] op_sel_hi:[1,0]
	v_pk_mul_f32 v[56:57], v[56:57], v[190:191] op_sel_hi:[1,0]
	v_pk_mul_f32 v[54:55], v[54:55], v[190:191] op_sel_hi:[1,0]
	v_pk_mul_f32 v[52:53], v[52:53], v[190:191] op_sel_hi:[1,0]
	v_pk_mul_f32 v[50:51], v[50:51], v[190:191] op_sel_hi:[1,0]
	v_pk_mul_f32 v[48:49], v[48:49], v[190:191] op_sel_hi:[1,0]
	v_pk_mul_f32 v[46:47], v[46:47], v[190:191] op_sel_hi:[1,0]
	v_pk_mul_f32 v[44:45], v[44:45], v[190:191] op_sel_hi:[1,0]
	v_pk_mul_f32 v[42:43], v[42:43], v[190:191] op_sel_hi:[1,0]
	v_pk_mul_f32 v[40:41], v[40:41], v[190:191] op_sel_hi:[1,0]
	v_pk_mul_f32 v[38:39], v[38:39], v[190:191] op_sel_hi:[1,0]
	v_pk_mul_f32 v[36:37], v[36:37], v[190:191] op_sel_hi:[1,0]
	v_pk_mul_f32 v[34:35], v[34:35], v[190:191] op_sel_hi:[1,0]
	v_pk_mul_f32 v[32:33], v[32:33], v[190:191] op_sel_hi:[1,0]
	v_pk_mul_f32 v[30:31], v[30:31], v[190:191] op_sel_hi:[1,0]
	v_pk_mul_f32 v[28:29], v[28:29], v[190:191] op_sel_hi:[1,0]
	v_pk_mul_f32 v[26:27], v[26:27], v[190:191] op_sel_hi:[1,0]
	v_pk_mul_f32 v[24:25], v[24:25], v[190:191] op_sel_hi:[1,0]
	v_pk_mul_f32 v[22:23], v[22:23], v[190:191] op_sel_hi:[1,0]
	v_pk_mul_f32 v[20:21], v[20:21], v[190:191] op_sel_hi:[1,0]
	v_pk_mul_f32 v[18:19], v[18:19], v[190:191] op_sel_hi:[1,0]
	v_pk_mul_f32 v[16:17], v[16:17], v[190:191] op_sel_hi:[1,0]
	v_pk_mul_f32 v[14:15], v[14:15], v[190:191] op_sel_hi:[1,0]
	v_pk_mul_f32 v[12:13], v[12:13], v[190:191] op_sel_hi:[1,0]
	v_pk_mul_f32 v[10:11], v[10:11], v[190:191] op_sel_hi:[1,0]
	v_pk_mul_f32 v[8:9], v[8:9], v[190:191] op_sel_hi:[1,0]
	v_pk_mul_f32 v[6:7], v[6:7], v[190:191] op_sel_hi:[1,0]
	v_pk_mul_f32 v[4:5], v[4:5], v[190:191] op_sel_hi:[1,0]
	v_pk_mul_f32 v[2:3], v[2:3], v[190:191] op_sel_hi:[1,0]
	v_pk_mul_f32 v[0:1], v[0:1], v[190:191] op_sel_hi:[1,0]
	v_mul_f32_e32 v202, v202, v190
	v_mov_b32_e32 v190, v246
	v_sub_f32_e32 v128, v128, v190
	v_exp_f32_e32 v128, v128
	v_sub_f32_e32 v129, v129, v190
	v_exp_f32_e32 v129, v129
	v_sub_f32_e32 v130, v130, v190
	v_add_f32_e32 v254, 0, v128
	v_exp_f32_e32 v130, v130
	v_sub_f32_e32 v131, v131, v190
	v_add_f32_e32 v254, v129, v254
	v_exp_f32_e32 v131, v131
	v_sub_f32_e32 v132, v132, v190
	v_add_f32_e32 v254, v130, v254
	v_exp_f32_e32 v132, v132
	v_sub_f32_e32 v133, v133, v190
	v_add_f32_e32 v254, v131, v254
	v_exp_f32_e32 v133, v133
	v_sub_f32_e32 v134, v134, v190
	v_add_f32_e32 v254, v132, v254
	v_exp_f32_e32 v134, v134
	v_sub_f32_e32 v135, v135, v190
	v_add_f32_e32 v254, v133, v254
	v_exp_f32_e32 v135, v135
	v_sub_f32_e32 v136, v136, v190
	v_add_f32_e32 v254, v134, v254
	v_exp_f32_e32 v136, v136
	v_sub_f32_e32 v137, v137, v190
	v_add_f32_e32 v254, v135, v254
	v_exp_f32_e32 v137, v137
	v_sub_f32_e32 v138, v138, v190
	v_add_f32_e32 v254, v136, v254
	v_exp_f32_e32 v138, v138
	v_sub_f32_e32 v139, v139, v190
	v_add_f32_e32 v254, v137, v254
	v_exp_f32_e32 v139, v139
	v_sub_f32_e32 v140, v140, v190
	v_add_f32_e32 v254, v138, v254
	v_exp_f32_e32 v140, v140
	v_sub_f32_e32 v141, v141, v190
	v_add_f32_e32 v254, v139, v254
	v_exp_f32_e32 v141, v141
	v_sub_f32_e32 v142, v142, v190
	v_add_f32_e32 v254, v140, v254
	v_exp_f32_e32 v142, v142
	v_sub_f32_e32 v143, v143, v190
	v_add_f32_e32 v254, v141, v254
	v_exp_f32_e32 v143, v143
	v_add_f32_e32 v254, v142, v254
	v_add_f32_e32 v254, v143, v254
	v_cvt_pk_bf16_f32 v242, v128, v129
	v_cvt_pk_bf16_f32 v243, v130, v131
	v_cvt_pk_bf16_f32 v244, v132, v133
	v_cvt_pk_bf16_f32 v245, v134, v135
	v_cvt_pk_bf16_f32 v250, v136, v137
	v_cvt_pk_bf16_f32 v251, v138, v139
	v_cvt_pk_bf16_f32 v252, v140, v141
	v_cvt_pk_bf16_f32 v253, v142, v143
	v_add_f32_e32 v202, v202, v254
	s_nop 1
	s_branch .Latt_pv1_0
.Latt_slow_0:
	s_lshl_b32 s34, s88, 14
	s_add_i32 s35, s34, 0
	v_add_u32_e32 v206, s35, v194
	ds_read_b128 v[128:131], v206
	v_add_u32_e32 v207, s35, v195
	ds_read_b128 v[210:213], v207
	v_add_u32_e32 v208, s35, v196
	v_add_u32_e32 v209, s35, v197
	v_lshrrev_b32_e32 v204, 3, v203
	s_add_i32 s89, s43, 31
	v_and_or_b32 v205, v203, 31, s83
	s_cmp_le_i32 s89, s83
	s_waitcnt lgkmcnt(1)
	v_mfma_f32_32x32x16_bf16 v[128:143], v[128:131], v[144:147], 0
	ds_read_b128 v[214:217], v209
	s_waitcnt lgkmcnt(1)
	v_mfma_f32_32x32x16_bf16 v[128:143], v[210:213], v[148:151], v[128:143]
	ds_read_b128 v[210:213], v208
	s_waitcnt lgkmcnt(0)
	v_mfma_f32_32x32x16_bf16 v[128:143], v[210:213], v[152:155], v[128:143]
	v_add_u32_e32 v210, s35, v198
	v_add_u32_e32 v212, s35, v199
	v_add_u32_e32 v213, s35, v200
	v_and_b32_e32 v211, 4, v204
	ds_read_b128 v[222:225], v212
	v_mfma_f32_32x32x16_bf16 v[128:143], v[214:217], v[156:159], v[128:143]
	ds_read_b128 v[214:217], v210
	s_waitcnt lgkmcnt(0)
	v_mfma_f32_32x32x16_bf16 v[128:143], v[214:217], v[160:163], v[128:143]
	ds_read_b128 v[216:219], v213
	v_add_u32_e32 v214, s35, v201
	v_mfma_f32_32x32x16_bf16 v[128:143], v[222:225], v[164:167], v[128:143]
	ds_read_b128 v[222:225], v214
	s_waitcnt lgkmcnt(1)
	v_mfma_f32_32x32x16_bf16 v[128:143], v[216:219], v[168:171], v[128:143]
	s_waitcnt lgkmcnt(0)
	v_mfma_f32_32x32x16_bf16 v[128:143], v[222:225], v[172:175], v[128:143]
	s_cbranch_scc1 .LBB0_850
	v_add_u32_e32 v204, s43, v211
	v_cmp_lt_i32_e32 vcc, v204, v205
	v_add_u32_e32 v215, 2, v204
	s_nop 7
	v_cndmask_b32_e32 v129, v192, v129, vcc
	v_cmp_le_i32_e32 vcc, v204, v205
	s_nop 1
	v_cndmask_b32_e32 v128, v192, v128, vcc
	v_cmp_le_i32_e32 vcc, v215, v205
	v_add_u32_e32 v215, 3, v204
	s_nop 0
	v_cndmask_b32_e32 v130, v192, v130, vcc
	v_cmp_le_i32_e32 vcc, v215, v205
	v_add_u32_e32 v215, 8, v204
	s_nop 0
	v_cndmask_b32_e32 v131, v192, v131, vcc
	v_cmp_le_i32_e32 vcc, v215, v205
	v_add_u32_e32 v215, 9, v204
	s_nop 0
	v_cndmask_b32_e32 v132, v192, v132, vcc
	v_cmp_le_i32_e32 vcc, v215, v205
	v_add_u32_e32 v215, 10, v204
	s_nop 0
	v_cndmask_b32_e32 v133, v192, v133, vcc
	v_cmp_le_i32_e32 vcc, v215, v205
	v_add_u32_e32 v215, 11, v204
	s_nop 0
	v_cndmask_b32_e32 v134, v192, v134, vcc
	v_cmp_le_i32_e32 vcc, v215, v205
	v_add_u32_e32 v215, 16, v204
	s_nop 0
	v_cndmask_b32_e32 v135, v192, v135, vcc
	v_cmp_le_i32_e32 vcc, v215, v205
	v_add_u32_e32 v215, 17, v204
	s_nop 0
	v_cndmask_b32_e32 v136, v192, v136, vcc
	v_cmp_le_i32_e32 vcc, v215, v205
	v_add_u32_e32 v215, 18, v204
	s_nop 0
	v_cndmask_b32_e32 v137, v192, v137, vcc
	v_cmp_le_i32_e32 vcc, v215, v205
	v_add_u32_e32 v215, 19, v204
	s_nop 0
	v_cndmask_b32_e32 v138, v192, v138, vcc
	v_cmp_le_i32_e32 vcc, v215, v205
	v_add_u32_e32 v215, 24, v204
	s_nop 0
	v_cndmask_b32_e32 v139, v192, v139, vcc
	v_cmp_le_i32_e32 vcc, v215, v205
	v_add_u32_e32 v215, 25, v204
	s_nop 0
	v_cndmask_b32_e32 v140, v192, v140, vcc
	v_cmp_le_i32_e32 vcc, v215, v205
	v_add_u32_e32 v215, 26, v204
	v_add_u32_e32 v204, 27, v204
	v_cndmask_b32_e32 v141, v192, v141, vcc
	v_cmp_le_i32_e32 vcc, v215, v205
	s_nop 1
	v_cndmask_b32_e32 v142, v192, v142, vcc
	v_cmp_le_i32_e32 vcc, v204, v205
	s_nop 1
	v_cndmask_b32_e32 v143, v192, v143, vcc

.LBB0_864:
	s_cmp_ge_u32 s88, s82
	s_cselect_b64 s[18:19], -1, 0
	v_mov_b32_e32 v204, v176
	s_and_b64 vcc, exec, s[18:19]
	s_cbranch_vccnz .LBB0_866
	s_add_i32 s100, s4, 63
	s_cmp_le_i32 s100, s83
	s_cbranch_scc1 .LBB0_866
	v_sub_co_u32_e64 v128, s[90:91], s33, 1
	s_nop 1
	v_cndmask_b32_e64 v130, v128, 2, s[90:91]
	v_lshlrev_b32_e32 v128, 14, v130
	v_add_u32_e32 v131, s85, v128
	v_lshl_add_u64 v[128:129], s[12:13], 0, v[178:179]
	s_add_u32 s90, s12, 0xf00
	v_readfirstlane_b32 s89, v131
	s_mov_b32 s92, m0
	s_mov_b32 m0, s89
	s_nop 0
	global_load_lds_dwordx4 v[128:129], off
	s_mov_b32 m0, s92
	v_lshl_add_u64 v[128:129], s[12:13], 0, v[180:181]
	s_addc_u32 s91, s13, 0
	s_addk_i32 s89, 0x400
	s_mov_b32 s92, m0
	s_mov_b32 m0, s89
	s_nop 0
	global_load_lds_dwordx4 v[128:129], off
	s_mov_b32 m0, s92
	v_lshlrev_b32_e32 v128, 15, v130
	v_add_u32_e32 v130, s86, v128
	v_lshl_add_u64 v[128:129], s[90:91], 0, v[182:183]
	v_readfirstlane_b32 s89, v130
	s_mov_b32 s92, m0
	s_mov_b32 m0, s89
	s_nop 0
	global_load_lds_dwordx4 v[128:129], off
	s_mov_b32 m0, s92
	v_lshl_add_u64 v[128:129], s[90:91], 0, v[184:185]
	s_add_i32 s92, s89, 0x400
	s_mov_b32 s93, m0
	s_mov_b32 m0, s92
	s_nop 0
	global_load_lds_dwordx4 v[128:129], off
	s_mov_b32 m0, s93
	v_lshl_add_u64 v[128:129], s[90:91], 0, v[186:187]
	s_add_i32 s92, s89, 0x800
	s_mov_b32 s93, m0
	s_mov_b32 m0, s92
	s_nop 0
	global_load_lds_dwordx4 v[128:129], off
	s_mov_b32 m0, s93
	v_lshl_add_u64 v[128:129], s[90:91], 0, v[188:189]
	s_addk_i32 s89, 0xc00
	s_mov_b32 s90, m0
	s_mov_b32 m0, s89
	s_nop 0
	global_load_lds_dwordx4 v[128:129], off
	s_mov_b32 m0, s90
.LBB0_866:
	s_cmp_gt_i32 s4, s84
	s_cbranch_scc1 .LBB0_877
	s_add_i32 s100, s4, 63
	s_cmp_le_i32 s100, s83
	s_cbranch_scc0 .Latt_slow_1
	s_lshl_b32 s98, s33, 14
	s_lshl_b32 s99, s33, 15
	s_add_i32 s99, s99, 0xc000
	v_add_u32_e32 v206, s98, v196
	ds_read_b128 v[206:209], v206
	v_add_u32_e32 v210, s98, v197
	ds_read_b128 v[210:213], v210
	v_add_u32_e32 v214, s98, v198
	ds_read_b128 v[214:217], v214
	v_add_u32_e32 v222, s98, v199
	ds_read_b128 v[222:225], v222
	v_add_u32_e32 v226, s98, v200
	ds_read_b128 v[226:229], v226
	v_add_u32_e32 v230, s98, v201
	ds_read_b128 v[230:233], v230
	v_add_u32_e32 v234, s98, v202
	ds_read_b128 v[234:237], v234
	v_add_u32_e32 v238, s98, v203
	ds_read_b128 v[238:241], v238
	v_bfe_u32 v246, v204, 2, 2
	v_bfe_u32 v247, v204, 5, 1
	v_lshl_or_b32 v247, v247, 2, v246
	v_and_b32_e32 v249, 3, v204
	v_and_b32_e32 v254, 16, v204
	v_lshl_or_b32 v249, v249, 2, v254
	v_lshlrev_b32_e32 v249, 1, v249
	v_lshl_add_u32 v247, v247, 9, v249
	v_add_u32_e32 v247, s99, v247
	v_lshlrev_b32_e32 v246, 6, v246
	v_add_u32_e32 v205, v247, v246
	v_xor_b32_e32 v249, 64, v246
	v_add_u32_e32 v218, v247, v249
	v_xor_b32_e32 v249, 0x80, v246
	v_add_u32_e32 v219, v247, v249
	v_xor_b32_e32 v249, 0xc0, v246
	v_add_u32_e32 v221, v247, v249
	s_waitcnt lgkmcnt(7)
	v_mfma_f32_32x32x16_bf16 v[128:143], v[206:209], v[144:147], 0
	v_add_u32_e32 v206, s98, v196
	ds_read_b128 v[206:209], v206 offset:8192
	s_waitcnt lgkmcnt(7)
	v_mfma_f32_32x32x16_bf16 v[128:143], v[210:213], v[148:151], v[128:143]
	v_add_u32_e32 v210, s98, v197
	ds_read_b128 v[210:213], v210 offset:8192
	s_waitcnt lgkmcnt(7)
	v_mfma_f32_32x32x16_bf16 v[128:143], v[214:217], v[152:155], v[128:143]
	v_add_u32_e32 v214, s98, v198
	ds_read_b128 v[214:217], v214 offset:8192
	s_waitcnt lgkmcnt(7)
	v_mfma_f32_32x32x16_bf16 v[128:143], v[222:225], v[156:159], v[128:143]
	v_add_u32_e32 v222, s98, v199
	ds_read_b128 v[222:225], v222 offset:8192
	s_waitcnt lgkmcnt(7)
	v_mfma_f32_32x32x16_bf16 v[128:143], v[226:229], v[160:163], v[128:143]
	v_add_u32_e32 v226, s98, v200
	ds_read_b128 v[226:229], v226 offset:8192
	s_waitcnt lgkmcnt(7)
	v_mfma_f32_32x32x16_bf16 v[128:143], v[230:233], v[164:167], v[128:143]
	v_add_u32_e32 v230, s98, v201
	ds_read_b128 v[230:233], v230 offset:8192
	s_waitcnt lgkmcnt(7)
	v_mfma_f32_32x32x16_bf16 v[128:143], v[234:237], v[168:171], v[128:143]
	v_add_u32_e32 v234, s98, v202
	ds_read_b128 v[234:237], v234 offset:8192
	s_waitcnt lgkmcnt(7)
	v_mfma_f32_32x32x16_bf16 v[128:143], v[238:241], v[172:175], v[128:143]
	v_add_u32_e32 v238, s98, v203
	ds_read_b128 v[238:241], v238 offset:8192
	s_nop 9
	v_max3_f32 v246, v128, v129, v130
	v_max3_f32 v247, v131, v132, v133
	v_max3_f32 v246, v246, v134, v135
	v_max3_f32 v247, v247, v136, v137
	v_max3_f32 v246, v246, v138, v139
	v_max3_f32 v247, v247, v140, v141
	v_max3_f32 v246, v246, v142, v143
	v_max_f32_e32 v246, v246, v247
	v_mov_b32_e32 v247, v246
	v_add_f32_e32 v249, 0x41000000, v190
	s_nop 1
	v_permlane32_swap_b32_e32 v246, v247
	v_max_f32_e32 v246, v246, v247
	v_cmp_gt_f32_e32 vcc, v246, v249
	s_cbranch_vccz .Latt_nr0_1
	v_max_f32_e32 v246, v190, v246
	v_sub_f32_e32 v190, v190, v246
	v_exp_f32_e32 v190, v190
	s_nop 0
	v_pk_mul_f32 v[126:127], v[126:127], v[190:191] op_sel_hi:[1,0]
	v_pk_mul_f32 v[124:125], v[124:125], v[190:191] op_sel_hi:[1,0]
	v_pk_mul_f32 v[122:123], v[122:123], v[190:191] op_sel_hi:[1,0]
	v_pk_mul_f32 v[120:121], v[120:121], v[190:191] op_sel_hi:[1,0]
	v_pk_mul_f32 v[118:119], v[118:119], v[190:191] op_sel_hi:[1,0]
	v_pk_mul_f32 v[116:117], v[116:117], v[190:191] op_sel_hi:[1,0]
	v_pk_mul_f32 v[114:115], v[114:115], v[190:191] op_sel_hi:[1,0]
	v_pk_mul_f32 v[112:113], v[112:113], v[190:191] op_sel_hi:[1,0]
	v_pk_mul_f32 v[110:111], v[110:111], v[190:191] op_sel_hi:[1,0]
	v_pk_mul_f32 v[108:109], v[108:109], v[190:191] op_sel_hi:[1,0]
	v_pk_mul_f32 v[106:107], v[106:107], v[190:191] op_sel_hi:[1,0]
	v_pk_mul_f32 v[104:105], v[104:105], v[190:191] op_sel_hi:[1,0]
	v_pk_mul_f32 v[102:103], v[102:103], v[190:191] op_sel_hi:[1,0]
	v_pk_mul_f32 v[100:101], v[100:101], v[190:191] op_sel_hi:[1,0]
	v_pk_mul_f32 v[98:99], v[98:99], v[190:191] op_sel_hi:[1,0]
	v_pk_mul_f32 v[96:97], v[96:97], v[190:191] op_sel_hi:[1,0]
	v_pk_mul_f32 v[94:95], v[94:95], v[190:191] op_sel_hi:[1,0]
	v_pk_mul_f32 v[92:93], v[92:93], v[190:191] op_sel_hi:[1,0]
	v_pk_mul_f32 v[90:91], v[90:91], v[190:191] op_sel_hi:[1,0]
	v_pk_mul_f32 v[88:89], v[88:89], v[190:191] op_sel_hi:[1,0]
	v_pk_mul_f32 v[86:87], v[86:87], v[190:191] op_sel_hi:[1,0]
	v_pk_mul_f32 v[84:85], v[84:85], v[190:191] op_sel_hi:[1,0]
	v_pk_mul_f32 v[82:83], v[82:83], v[190:191] op_sel_hi:[1,0]
	v_pk_mul_f32 v[80:81], v[80:81], v[190:191] op_sel_hi:[1,0]
	v_pk_mul_f32 v[78:79], v[78:79], v[190:191] op_sel_hi:[1,0]
	v_pk_mul_f32 v[76:77], v[76:77], v[190:191] op_sel_hi:[1,0]
	v_pk_mul_f32 v[74:75], v[74:75], v[190:191] op_sel_hi:[1,0]
	v_pk_mul_f32 v[72:73], v[72:73], v[190:191] op_sel_hi:[1,0]
	v_pk_mul_f32 v[70:71], v[70:71], v[190:191] op_sel_hi:[1,0]
	v_pk_mul_f32 v[68:69], v[68:69], v[190:191] op_sel_hi:[1,0]
	v_pk_mul_f32 v[66:67], v[66:67], v[190:191] op_sel_hi:[1,0]
	v_pk_mul_f32 v[64:65], v[64:65], v[190:191] op_sel_hi:[1,0]
	v_pk_mul_f32 v[62:63], v[62:63], v[190:191] op_sel_hi:[1,0]
	v_pk_mul_f32 v[60:61], v[60:61], v[190:191] op_sel_hi:[1,0]
	v_pk_mul_f32 v[58:59], v[58:59], v[190:191] op_sel_hi:[1,0]
	v_pk_mul_f32 v[56:57], v[56:57], v[190:191] op_sel_hi:[1,0]
	v_pk_mul_f32 v[54:55], v[54:55], v[190:191] op_sel_hi:[1,0]
	v_pk_mul_f32 v[52:53], v[52:53], v[190:191] op_sel_hi:[1,0]
	v_pk_mul_f32 v[50:51], v[50:51], v[190:191] op_sel_hi:[1,0]
	v_pk_mul_f32 v[48:49], v[48:49], v[190:191] op_sel_hi:[1,0]
	v_pk_mul_f32 v[46:47], v[46:47], v[190:191] op_sel_hi:[1,0]
	v_pk_mul_f32 v[44:45], v[44:45], v[190:191] op_sel_hi:[1,0]
	v_pk_mul_f32 v[42:43], v[42:43], v[190:191] op_sel_hi:[1,0]
	v_pk_mul_f32 v[40:41], v[40:41], v[190:191] op_sel_hi:[1,0]
	v_pk_mul_f32 v[38:39], v[38:39], v[190:191] op_sel_hi:[1,0]
	v_pk_mul_f32 v[36:37], v[36:37], v[190:191] op_sel_hi:[1,0]
	v_pk_mul_f32 v[34:35], v[34:35], v[190:191] op_sel_hi:[1,0]
	v_pk_mul_f32 v[32:33], v[32:33], v[190:191] op_sel_hi:[1,0]
	v_pk_mul_f32 v[30:31], v[30:31], v[190:191] op_sel_hi:[1,0]
	v_pk_mul_f32 v[28:29], v[28:29], v[190:191] op_sel_hi:[1,0]
	v_pk_mul_f32 v[26:27], v[26:27], v[190:191] op_sel_hi:[1,0]
	v_pk_mul_f32 v[24:25], v[24:25], v[190:191] op_sel_hi:[1,0]
	v_pk_mul_f32 v[22:23], v[22:23], v[190:191] op_sel_hi:[1,0]
	v_pk_mul_f32 v[20:21], v[20:21], v[190:191] op_sel_hi:[1,0]
	v_pk_mul_f32 v[18:19], v[18:19], v[190:191] op_sel_hi:[1,0]
	v_pk_mul_f32 v[16:17], v[16:17], v[190:191] op_sel_hi:[1,0]
	v_pk_mul_f32 v[14:15], v[14:15], v[190:191] op_sel_hi:[1,0]
	v_pk_mul_f32 v[12:13], v[12:13], v[190:191] op_sel_hi:[1,0]
	v_pk_mul_f32 v[10:11], v[10:11], v[190:191] op_sel_hi:[1,0]
	v_pk_mul_f32 v[8:9], v[8:9], v[190:191] op_sel_hi:[1,0]
	v_pk_mul_f32 v[6:7], v[6:7], v[190:191] op_sel_hi:[1,0]
	v_pk_mul_f32 v[4:5], v[4:5], v[190:191] op_sel_hi:[1,0]
	v_pk_mul_f32 v[2:3], v[2:3], v[190:191] op_sel_hi:[1,0]
	v_pk_mul_f32 v[0:1], v[0:1], v[190:191] op_sel_hi:[1,0]
	v_mul_f32_e32 v195, v195, v190
	v_mov_b32_e32 v190, v246
.Latt_nr0_1:
	v_sub_f32_e32 v128, v128, v190
	v_exp_f32_e32 v128, v128
	v_sub_f32_e32 v129, v129, v190
	v_exp_f32_e32 v129, v129
	v_sub_f32_e32 v130, v130, v190
	v_add_f32_e32 v254, 0, v128
	v_exp_f32_e32 v130, v130
	v_sub_f32_e32 v131, v131, v190
	v_add_f32_e32 v254, v129, v254
	v_exp_f32_e32 v131, v131
	v_sub_f32_e32 v132, v132, v190
	v_add_f32_e32 v254, v130, v254
	v_exp_f32_e32 v132, v132
	v_sub_f32_e32 v133, v133, v190
	v_add_f32_e32 v254, v131, v254
	v_exp_f32_e32 v133, v133
	v_sub_f32_e32 v134, v134, v190
	v_add_f32_e32 v254, v132, v254
	v_exp_f32_e32 v134, v134
	v_sub_f32_e32 v135, v135, v190
	v_add_f32_e32 v254, v133, v254
	v_exp_f32_e32 v135, v135
	v_sub_f32_e32 v136, v136, v190
	v_add_f32_e32 v254, v134, v254
	v_exp_f32_e32 v136, v136
	v_sub_f32_e32 v137, v137, v190
	v_add_f32_e32 v254, v135, v254
	v_exp_f32_e32 v137, v137
	v_sub_f32_e32 v138, v138, v190
	v_add_f32_e32 v254, v136, v254
	v_exp_f32_e32 v138, v138
	v_sub_f32_e32 v139, v139, v190
	v_add_f32_e32 v254, v137, v254
	v_exp_f32_e32 v139, v139
	v_sub_f32_e32 v140, v140, v190
	v_add_f32_e32 v254, v138, v254
	v_exp_f32_e32 v140, v140
	v_sub_f32_e32 v141, v141, v190
	v_add_f32_e32 v254, v139, v254
	v_exp_f32_e32 v141, v141
	v_sub_f32_e32 v142, v142, v190
	v_add_f32_e32 v254, v140, v254
	v_exp_f32_e32 v142, v142
	v_sub_f32_e32 v143, v143, v190
	v_add_f32_e32 v254, v141, v254
	v_exp_f32_e32 v143, v143
	v_add_f32_e32 v254, v142, v254
	v_add_f32_e32 v254, v143, v254
	v_cvt_pk_bf16_f32 v242, v128, v129
	v_cvt_pk_bf16_f32 v243, v130, v131
	v_cvt_pk_bf16_f32 v244, v132, v133
	v_cvt_pk_bf16_f32 v245, v134, v135
	v_cvt_pk_bf16_f32 v250, v136, v137
	v_cvt_pk_bf16_f32 v251, v138, v139
	v_cvt_pk_bf16_f32 v252, v140, v141
	v_cvt_pk_bf16_f32 v253, v142, v143
	v_add_f32_e32 v195, v195, v254
	s_nop 1
	s_waitcnt lgkmcnt(7)
	v_mfma_f32_32x32x16_bf16 v[128:143], v[206:209], v[144:147], 0
	ds_read_b64_tr_b16 v[206:207], v205
	ds_read_b64_tr_b16 v[208:209], v205 offset:4096
	s_waitcnt lgkmcnt(8)
	v_mfma_f32_32x32x16_bf16 v[128:143], v[210:213], v[148:151], v[128:143]
	ds_read_b64_tr_b16 v[210:211], v218
	ds_read_b64_tr_b16 v[212:213], v218 offset:4096
	s_waitcnt lgkmcnt(9)
	v_mfma_f32_32x32x16_bf16 v[128:143], v[214:217], v[152:155], v[128:143]
	ds_read_b64_tr_b16 v[214:215], v219
	ds_read_b64_tr_b16 v[216:217], v219 offset:4096
	s_waitcnt lgkmcnt(10)
	v_mfma_f32_32x32x16_bf16 v[128:143], v[222:225], v[156:159], v[128:143]
	ds_read_b64_tr_b16 v[222:223], v221
	ds_read_b64_tr_b16 v[224:225], v221 offset:4096
	s_waitcnt lgkmcnt(11)
	v_mfma_f32_32x32x16_bf16 v[128:143], v[226:229], v[160:163], v[128:143]
	ds_read_b64_tr_b16 v[226:227], v205 offset:256
	ds_read_b64_tr_b16 v[228:229], v205 offset:4352
	s_waitcnt lgkmcnt(12)
	v_mfma_f32_32x32x16_bf16 v[128:143], v[230:233], v[164:167], v[128:143]
	ds_read_b64_tr_b16 v[230:231], v218 offset:256
	ds_read_b64_tr_b16 v[232:233], v218 offset:4352
	s_waitcnt lgkmcnt(13)
	v_mfma_f32_32x32x16_bf16 v[128:143], v[234:237], v[168:171], v[128:143]
	s_waitcnt lgkmcnt(12)
	v_mfma_f32_32x32x16_bf16 v[128:143], v[238:241], v[172:175], v[128:143]
	ds_read_b64_tr_b16 v[234:235], v219 offset:256
	ds_read_b64_tr_b16 v[236:237], v219 offset:4352
	s_waitcnt lgkmcnt(12)
	v_mfma_f32_32x32x16_bf16 v[112:127], v[206:209], v[242:245], v[112:127]
	ds_read_b64_tr_b16 v[238:239], v221 offset:256
	ds_read_b64_tr_b16 v[240:241], v221 offset:4352
	s_waitcnt lgkmcnt(12)
	v_mfma_f32_32x32x16_bf16 v[96:111], v[210:213], v[242:245], v[96:111]
	ds_read_b64_tr_b16 v[206:207], v205 offset:8192
	ds_read_b64_tr_b16 v[208:209], v205 offset:12288
	s_waitcnt lgkmcnt(12)
	v_mfma_f32_32x32x16_bf16 v[80:95], v[214:217], v[242:245], v[80:95]
	ds_read_b64_tr_b16 v[210:211], v218 offset:8192
	ds_read_b64_tr_b16 v[212:213], v218 offset:12288
	v_max3_f32 v246, v128, v129, v130
	v_max3_f32 v247, v131, v132, v133
	v_max3_f32 v246, v246, v134, v135
	v_max3_f32 v247, v247, v136, v137
	v_max3_f32 v246, v246, v138, v139
	v_max3_f32 v247, v247, v140, v141
	s_waitcnt lgkmcnt(12)
	v_mfma_f32_32x32x16_bf16 v[64:79], v[222:225], v[242:245], v[64:79]
	ds_read_b64_tr_b16 v[214:215], v219 offset:8192
	ds_read_b64_tr_b16 v[216:217], v219 offset:12288
	v_max3_f32 v246, v246, v142, v143
	v_max_f32_e32 v246, v246, v247
	v_mov_b32_e32 v247, v246
	v_add_f32_e32 v249, 0x41000000, v190
	s_nop 1
	s_waitcnt lgkmcnt(12)
	v_mfma_f32_32x32x16_bf16 v[48:63], v[226:229], v[242:245], v[48:63]
	ds_read_b64_tr_b16 v[222:223], v221 offset:8192
	ds_read_b64_tr_b16 v[224:225], v221 offset:12288
	v_permlane32_swap_b32_e32 v246, v247
	v_max_f32_e32 v246, v246, v247
	v_cmp_gt_f32_e32 vcc, v246, v249
	s_cbranch_vccnz .Latt_rs1_1
	s_waitcnt lgkmcnt(12)
	v_mfma_f32_32x32x16_bf16 v[32:47], v[230:233], v[242:245], v[32:47]
	ds_read_b64_tr_b16 v[226:227], v205 offset:8448
	ds_read_b64_tr_b16 v[228:229], v205 offset:12544
	v_sub_f32_e32 v128, v128, v190
	v_exp_f32_e32 v128, v128
	v_sub_f32_e32 v129, v129, v190
	v_exp_f32_e32 v129, v129
	v_sub_f32_e32 v130, v130, v190
	s_waitcnt lgkmcnt(12)
	v_mfma_f32_32x32x16_bf16 v[16:31], v[234:237], v[242:245], v[16:31]
	ds_read_b64_tr_b16 v[230:231], v218 offset:8448
	ds_read_b64_tr_b16 v[232:233], v218 offset:12544
	v_add_f32_e32 v254, 0, v128
	v_exp_f32_e32 v130, v130
	v_sub_f32_e32 v131, v131, v190
	v_add_f32_e32 v254, v129, v254
	v_exp_f32_e32 v131, v131
	s_waitcnt lgkmcnt(12)
	v_mfma_f32_32x32x16_bf16 v[0:15], v[238:241], v[242:245], v[0:15]
	ds_read_b64_tr_b16 v[234:235], v219 offset:8448
	ds_read_b64_tr_b16 v[236:237], v219 offset:12544
	v_sub_f32_e32 v132, v132, v190
	v_add_f32_e32 v254, v130, v254
	v_exp_f32_e32 v132, v132
	v_sub_f32_e32 v133, v133, v190
	v_add_f32_e32 v254, v131, v254
	s_waitcnt lgkmcnt(12)
	v_mfma_f32_32x32x16_bf16 v[112:127], v[206:209], v[250:253], v[112:127]
	ds_read_b64_tr_b16 v[238:239], v221 offset:8448
	ds_read_b64_tr_b16 v[240:241], v221 offset:12544
	v_exp_f32_e32 v133, v133
	v_sub_f32_e32 v134, v134, v190
	v_add_f32_e32 v254, v132, v254
	v_exp_f32_e32 v134, v134
	v_sub_f32_e32 v135, v135, v190
	s_waitcnt lgkmcnt(12)
	v_mfma_f32_32x32x16_bf16 v[96:111], v[210:213], v[250:253], v[96:111]
	ds_read_b64_tr_b16 v[206:207], v205 offset:16384
	ds_read_b64_tr_b16 v[208:209], v205 offset:20480
	v_add_f32_e32 v254, v133, v254
	v_exp_f32_e32 v135, v135
	v_sub_f32_e32 v136, v136, v190
	v_add_f32_e32 v254, v134, v254
	s_waitcnt lgkmcnt(12)
	v_mfma_f32_32x32x16_bf16 v[80:95], v[214:217], v[250:253], v[80:95]
	ds_read_b64_tr_b16 v[210:211], v218 offset:16384
	ds_read_b64_tr_b16 v[212:213], v218 offset:20480
	v_exp_f32_e32 v136, v136
	v_sub_f32_e32 v137, v137, v190
	v_add_f32_e32 v254, v135, v254
	v_exp_f32_e32 v137, v137
	s_waitcnt lgkmcnt(12)
	v_mfma_f32_32x32x16_bf16 v[64:79], v[222:225], v[250:253], v[64:79]
	ds_read_b64_tr_b16 v[214:215], v219 offset:16384
	ds_read_b64_tr_b16 v[216:217], v219 offset:20480
	v_sub_f32_e32 v138, v138, v190
	v_add_f32_e32 v254, v136, v254
	v_exp_f32_e32 v138, v138
	v_sub_f32_e32 v139, v139, v190
	s_waitcnt lgkmcnt(12)
	v_mfma_f32_32x32x16_bf16 v[48:63], v[226:229], v[250:253], v[48:63]
	ds_read_b64_tr_b16 v[222:223], v221 offset:16384
	ds_read_b64_tr_b16 v[224:225], v221 offset:20480
	v_add_f32_e32 v254, v137, v254
	v_exp_f32_e32 v139, v139
	v_sub_f32_e32 v140, v140, v190
	v_add_f32_e32 v254, v138, v254
	s_waitcnt lgkmcnt(12)
	v_mfma_f32_32x32x16_bf16 v[32:47], v[230:233], v[250:253], v[32:47]
	ds_read_b64_tr_b16 v[226:227], v205 offset:16640
	ds_read_b64_tr_b16 v[228:229], v205 offset:20736
	v_exp_f32_e32 v140, v140
	v_sub_f32_e32 v141, v141, v190
	v_add_f32_e32 v254, v139, v254
	v_exp_f32_e32 v141, v141
	s_waitcnt lgkmcnt(12)
	v_mfma_f32_32x32x16_bf16 v[16:31], v[234:237], v[250:253], v[16:31]
	ds_read_b64_tr_b16 v[230:231], v218 offset:16640
	ds_read_b64_tr_b16 v[232:233], v218 offset:20736
	v_sub_f32_e32 v142, v142, v190
	v_add_f32_e32 v254, v140, v254
	v_exp_f32_e32 v142, v142
	v_sub_f32_e32 v143, v143, v190
	s_waitcnt lgkmcnt(12)
	v_mfma_f32_32x32x16_bf16 v[0:15], v[238:241], v[250:253], v[0:15]
	ds_read_b64_tr_b16 v[234:235], v219 offset:16640
	ds_read_b64_tr_b16 v[236:237], v219 offset:20736
	v_add_f32_e32 v254, v141, v254
	v_exp_f32_e32 v143, v143
	v_add_f32_e32 v254, v142, v254
	v_add_f32_e32 v254, v143, v254
	v_cvt_pk_bf16_f32 v242, v128, v129
	v_cvt_pk_bf16_f32 v243, v130, v131
	v_cvt_pk_bf16_f32 v244, v132, v133
	v_cvt_pk_bf16_f32 v245, v134, v135
	v_cvt_pk_bf16_f32 v250, v136, v137
	v_cvt_pk_bf16_f32 v251, v138, v139
	v_cvt_pk_bf16_f32 v252, v140, v141
	v_cvt_pk_bf16_f32 v253, v142, v143
	v_add_f32_e32 v195, v195, v254
	s_nop 1
.Latt_pv1_1:
	s_waitcnt lgkmcnt(12)
	v_mfma_f32_32x32x16_bf16 v[112:127], v[206:209], v[242:245], v[112:127]
	ds_read_b64_tr_b16 v[238:239], v221 offset:16640
	ds_read_b64_tr_b16 v[240:241], v221 offset:20736
	s_waitcnt lgkmcnt(12)
	v_mfma_f32_32x32x16_bf16 v[96:111], v[210:213], v[242:245], v[96:111]
	ds_read_b64_tr_b16 v[206:207], v205 offset:24576
	ds_read_b64_tr_b16 v[208:209], v205 offset:28672
	s_cmp_lg_u64 s[18:19], 0
	s_cbranch_scc1 .Latt_nd0_1
	s_sub_i32 s100, s33, 1
	s_cmp_eq_u32 s33, 0
	s_cselect_b32 s100, 2, s100
	s_lshl_b32 s101, s100, 14
	s_add_i32 m0, s85, s101
	s_nop 0
	global_load_lds_dwordx4 v178, s[12:13]
.Latt_nd0_1:
	s_waitcnt lgkmcnt(12)
	v_mfma_f32_32x32x16_bf16 v[80:95], v[214:217], v[242:245], v[80:95]
	ds_read_b64_tr_b16 v[210:211], v218 offset:24576
	ds_read_b64_tr_b16 v[212:213], v218 offset:28672
	s_waitcnt lgkmcnt(12)
	v_mfma_f32_32x32x16_bf16 v[64:79], v[222:225], v[242:245], v[64:79]
	ds_read_b64_tr_b16 v[214:215], v219 offset:24576
	ds_read_b64_tr_b16 v[216:217], v219 offset:28672
	s_cmp_lg_u64 s[18:19], 0
	s_cbranch_scc1 .Latt_nd1_1
	s_add_i32 m0, m0, 0x400
	s_nop 0
	global_load_lds_dwordx4 v180, s[12:13]
.Latt_nd1_1:
	s_waitcnt lgkmcnt(12)
	v_mfma_f32_32x32x16_bf16 v[48:63], v[226:229], v[242:245], v[48:63]
	ds_read_b64_tr_b16 v[222:223], v221 offset:24576
	ds_read_b64_tr_b16 v[224:225], v221 offset:28672
	s_waitcnt lgkmcnt(12)
	v_mfma_f32_32x32x16_bf16 v[32:47], v[230:233], v[242:245], v[32:47]
	ds_read_b64_tr_b16 v[226:227], v205 offset:24832
	ds_read_b64_tr_b16 v[228:229], v205 offset:28928
	s_cmp_lg_u64 s[18:19], 0
	s_cbranch_scc1 .Latt_nd2_1
	s_lshl_b32 s101, s100, 15
	s_add_i32 m0, s86, s101
	s_add_u32 s100, s12, 0xf00
	s_addc_u32 s101, s13, 0
	global_load_lds_dwordx4 v182, s[100:101]

.Latt_rs1_1:
	s_waitcnt lgkmcnt(12)
	v_mfma_f32_32x32x16_bf16 v[32:47], v[230:233], v[242:245], v[32:47]
	ds_read_b64_tr_b16 v[226:227], v205 offset:8448
	ds_read_b64_tr_b16 v[228:229], v205 offset:12544
	s_waitcnt lgkmcnt(12)
	v_mfma_f32_32x32x16_bf16 v[16:31], v[234:237], v[242:245], v[16:31]
	ds_read_b64_tr_b16 v[230:231], v218 offset:8448
	ds_read_b64_tr_b16 v[232:233], v218 offset:12544
	s_waitcnt lgkmcnt(12)
	v_mfma_f32_32x32x16_bf16 v[0:15], v[238:241], v[242:245], v[0:15]
	ds_read_b64_tr_b16 v[234:235], v219 offset:8448
	ds_read_b64_tr_b16 v[236:237], v219 offset:12544
	s_waitcnt lgkmcnt(12)
	v_mfma_f32_32x32x16_bf16 v[112:127], v[206:209], v[250:253], v[112:127]
	ds_read_b64_tr_b16 v[238:239], v221 offset:8448
	ds_read_b64_tr_b16 v[240:241], v221 offset:12544
	s_waitcnt lgkmcnt(12)
	v_mfma_f32_32x32x16_bf16 v[96:111], v[210:213], v[250:253], v[96:111]
	ds_read_b64_tr_b16 v[206:207], v205 offset:16384
	ds_read_b64_tr_b16 v[208:209], v205 offset:20480
	s_waitcnt lgkmcnt(12)
	v_mfma_f32_32x32x16_bf16 v[80:95], v[214:217], v[250:253], v[80:95]
	ds_read_b64_tr_b16 v[210:211], v218 offset:16384
	ds_read_b64_tr_b16 v[212:213], v218 offset:20480
	s_waitcnt lgkmcnt(12)
	v_mfma_f32_32x32x16_bf16 v[64:79], v[222:225], v[250:253], v[64:79]
	ds_read_b64_tr_b16 v[214:215], v219 offset:16384
	ds_read_b64_tr_b16 v[216:217], v219 offset:20480
	s_waitcnt lgkmcnt(12)
	v_mfma_f32_32x32x16_bf16 v[48:63], v[226:229], v[250:253], v[48:63]
	ds_read_b64_tr_b16 v[222:223], v221 offset:16384
	ds_read_b64_tr_b16 v[224:225], v221 offset:20480
	s_waitcnt lgkmcnt(12)
	v_mfma_f32_32x32x16_bf16 v[32:47], v[230:233], v[250:253], v[32:47]
	ds_read_b64_tr_b16 v[226:227], v205 offset:16640
	ds_read_b64_tr_b16 v[228:229], v205 offset:20736
	s_waitcnt lgkmcnt(12)
	v_mfma_f32_32x32x16_bf16 v[16:31], v[234:237], v[250:253], v[16:31]
	ds_read_b64_tr_b16 v[230:231], v218 offset:16640
	ds_read_b64_tr_b16 v[232:233], v218 offset:20736
	s_waitcnt lgkmcnt(12)
	v_mfma_f32_32x32x16_bf16 v[0:15], v[238:241], v[250:253], v[0:15]
	ds_read_b64_tr_b16 v[234:235], v219 offset:16640
	ds_read_b64_tr_b16 v[236:237], v219 offset:20736
	s_nop 11
	v_max_f32_e32 v246, v190, v246
	v_sub_f32_e32 v190, v190, v246
	v_exp_f32_e32 v190, v190
	s_nop 0
	v_pk_mul_f32 v[126:127], v[126:127], v[190:191] op_sel_hi:[1,0]
	v_pk_mul_f32 v[124:125], v[124:125], v[190:191] op_sel_hi:[1,0]
	v_pk_mul_f32 v[122:123], v[122:123], v[190:191] op_sel_hi:[1,0]
	v_pk_mul_f32 v[120:121], v[120:121], v[190:191] op_sel_hi:[1,0]
	v_pk_mul_f32 v[118:119], v[118:119], v[190:191] op_sel_hi:[1,0]
	v_pk_mul_f32 v[116:117], v[116:117], v[190:191] op_sel_hi:[1,0]
	v_pk_mul_f32 v[114:115], v[114:115], v[190:191] op_sel_hi:[1,0]
	v_pk_mul_f32 v[112:113], v[112:113], v[190:191] op_sel_hi:[1,0]
	v_pk_mul_f32 v[110:111], v[110:111], v[190:191] op_sel_hi:[1,0]
	v_pk_mul_f32 v[108:109], v[108:109], v[190:191] op_sel_hi:[1,0]
	v_pk_mul_f32 v[106:107], v[106:107], v[190:191] op_sel_hi:[1,0]
	v_pk_mul_f32 v[104:105], v[104:105], v[190:191] op_sel_hi:[1,0]
	v_pk_mul_f32 v[102:103], v[102:103], v[190:191] op_sel_hi:[1,0]
	v_pk_mul_f32 v[100:101], v[100:101], v[190:191] op_sel_hi:[1,0]
	v_pk_mul_f32 v[98:99], v[98:99], v[190:191] op_sel_hi:[1,0]
	v_pk_mul_f32 v[96:97], v[96:97], v[190:191] op_sel_hi:[1,0]
	v_pk_mul_f32 v[94:95], v[94:95], v[190:191] op_sel_hi:[1,0]
	v_pk_mul_f32 v[92:93], v[92:93], v[190:191] op_sel_hi:[1,0]
	v_pk_mul_f32 v[90:91], v[90:91], v[190:191] op_sel_hi:[1,0]
	v_pk_mul_f32 v[88:89], v[88:89], v[190:191] op_sel_hi:[1,0]
	v_pk_mul_f32 v[86:87], v[86:87], v[190:191] op_sel_hi:[1,0]
	v_pk_mul_f32 v[84:85], v[84:85], v[190:191] op_sel_hi:[1,0]
	v_pk_mul_f32 v[82:83], v[82:83], v[190:191] op_sel_hi:[1,0]
	v_pk_mul_f32 v[80:81], v[80:81], v[190:191] op_sel_hi:[1,0]
	v_pk_mul_f32 v[78:79], v[78:79], v[190:191] op_sel_hi:[1,0]
	v_pk_mul_f32 v[76:77], v[76:77], v[190:191] op_sel_hi:[1,0]
	v_pk_mul_f32 v[74:75], v[74:75], v[190:191] op_sel_hi:[1,0]
	v_pk_mul_f32 v[72:73], v[72:73], v[190:191] op_sel_hi:[1,0]
	v_pk_mul_f32 v[70:71], v[70:71], v[190:191] op_sel_hi:[1,0]
	v_pk_mul_f32 v[68:69], v[68:69], v[190:191] op_sel_hi:[1,0]
	v_pk_mul_f32 v[66:67], v[66:67], v[190:191] op_sel_hi:[1,0]
	v_pk_mul_f32 v[64:65], v[64:65], v[190:191] op_sel_hi:[1,0]
	v_pk_mul_f32 v[62:63], v[62:63], v[190:191] op_sel_hi:[1,0]
	v_pk_mul_f32 v[60:61], v[60:61], v[190:191] op_sel_hi:[1,0]
	v_pk_mul_f32 v[58:59], v[58:59], v[190:191] op_sel_hi:[1,0]
	v_pk_mul_f32 v[56:57], v[56:57], v[190:191] op_sel_hi:[1,0]
	v_pk_mul_f32 v[54:55], v[54:55], v[190:191] op_sel_hi:[1,0]
	v_pk_mul_f32 v[52:53], v[52:53], v[190:191] op_sel_hi:[1,0]
	v_pk_mul_f32 v[50:51], v[50:51], v[190:191] op_sel_hi:[1,0]
	v_pk_mul_f32 v[48:49], v[48:49], v[190:191] op_sel_hi:[1,0]
	v_pk_mul_f32 v[46:47], v[46:47], v[190:191] op_sel_hi:[1,0]
	v_pk_mul_f32 v[44:45], v[44:45], v[190:191] op_sel_hi:[1,0]
	v_pk_mul_f32 v[42:43], v[42:43], v[190:191] op_sel_hi:[1,0]
	v_pk_mul_f32 v[40:41], v[40:41], v[190:191] op_sel_hi:[1,0]
	v_pk_mul_f32 v[38:39], v[38:39], v[190:191] op_sel_hi:[1,0]
	v_pk_mul_f32 v[36:37], v[36:37], v[190:191] op_sel_hi:[1,0]
	v_pk_mul_f32 v[34:35], v[34:35], v[190:191] op_sel_hi:[1,0]
	v_pk_mul_f32 v[32:33], v[32:33], v[190:191] op_sel_hi:[1,0]
	v_pk_mul_f32 v[30:31], v[30:31], v[190:191] op_sel_hi:[1,0]
	v_pk_mul_f32 v[28:29], v[28:29], v[190:191] op_sel_hi:[1,0]
	v_pk_mul_f32 v[26:27], v[26:27], v[190:191] op_sel_hi:[1,0]
	v_pk_mul_f32 v[24:25], v[24:25], v[190:191] op_sel_hi:[1,0]
	v_pk_mul_f32 v[22:23], v[22:23], v[190:191] op_sel_hi:[1,0]
	v_pk_mul_f32 v[20:21], v[20:21], v[190:191] op_sel_hi:[1,0]
	v_pk_mul_f32 v[18:19], v[18:19], v[190:191] op_sel_hi:[1,0]
	v_pk_mul_f32 v[16:17], v[16:17], v[190:191] op_sel_hi:[1,0]
	v_pk_mul_f32 v[14:15], v[14:15], v[190:191] op_sel_hi:[1,0]
	v_pk_mul_f32 v[12:13], v[12:13], v[190:191] op_sel_hi:[1,0]
	v_pk_mul_f32 v[10:11], v[10:11], v[190:191] op_sel_hi:[1,0]
	v_pk_mul_f32 v[8:9], v[8:9], v[190:191] op_sel_hi:[1,0]
	v_pk_mul_f32 v[6:7], v[6:7], v[190:191] op_sel_hi:[1,0]
	v_pk_mul_f32 v[4:5], v[4:5], v[190:191] op_sel_hi:[1,0]
	v_pk_mul_f32 v[2:3], v[2:3], v[190:191] op_sel_hi:[1,0]
	v_pk_mul_f32 v[0:1], v[0:1], v[190:191] op_sel_hi:[1,0]
	v_mul_f32_e32 v195, v195, v190
	v_mov_b32_e32 v190, v246
	v_sub_f32_e32 v128, v128, v190
	v_exp_f32_e32 v128, v128
	v_sub_f32_e32 v129, v129, v190
	v_exp_f32_e32 v129, v129
	v_sub_f32_e32 v130, v130, v190
	v_add_f32_e32 v254, 0, v128
	v_exp_f32_e32 v130, v130
	v_sub_f32_e32 v131, v131, v190
	v_add_f32_e32 v254, v129, v254
	v_exp_f32_e32 v131, v131
	v_sub_f32_e32 v132, v132, v190
	v_add_f32_e32 v254, v130, v254
	v_exp_f32_e32 v132, v132
	v_sub_f32_e32 v133, v133, v190
	v_add_f32_e32 v254, v131, v254
	v_exp_f32_e32 v133, v133
	v_sub_f32_e32 v134, v134, v190
	v_add_f32_e32 v254, v132, v254
	v_exp_f32_e32 v134, v134
	v_sub_f32_e32 v135, v135, v190
	v_add_f32_e32 v254, v133, v254
	v_exp_f32_e32 v135, v135
	v_sub_f32_e32 v136, v136, v190
	v_add_f32_e32 v254, v134, v254
	v_exp_f32_e32 v136, v136
	v_sub_f32_e32 v137, v137, v190
	v_add_f32_e32 v254, v135, v254
	v_exp_f32_e32 v137, v137
	v_sub_f32_e32 v138, v138, v190
	v_add_f32_e32 v254, v136, v254
	v_exp_f32_e32 v138, v138
	v_sub_f32_e32 v139, v139, v190
	v_add_f32_e32 v254, v137, v254
	v_exp_f32_e32 v139, v139
	v_sub_f32_e32 v140, v140, v190
	v_add_f32_e32 v254, v138, v254
	v_exp_f32_e32 v140, v140
	v_sub_f32_e32 v141, v141, v190
	v_add_f32_e32 v254, v139, v254
	v_exp_f32_e32 v141, v141
	v_sub_f32_e32 v142, v142, v190
	v_add_f32_e32 v254, v140, v254
	v_exp_f32_e32 v142, v142
	v_sub_f32_e32 v143, v143, v190
	v_add_f32_e32 v254, v141, v254
	v_exp_f32_e32 v143, v143
	v_add_f32_e32 v254, v142, v254
	v_add_f32_e32 v254, v143, v254
	v_cvt_pk_bf16_f32 v242, v128, v129
	v_cvt_pk_bf16_f32 v243, v130, v131
	v_cvt_pk_bf16_f32 v244, v132, v133
	v_cvt_pk_bf16_f32 v245, v134, v135
	v_cvt_pk_bf16_f32 v250, v136, v137
	v_cvt_pk_bf16_f32 v251, v138, v139
	v_cvt_pk_bf16_f32 v252, v140, v141
	v_cvt_pk_bf16_f32 v253, v142, v143
	v_add_f32_e32 v195, v195, v254
	s_nop 1
	s_branch .Latt_pv1_1
.Latt_slow_1:
	s_lshl_b32 s89, s33, 14
	s_add_i32 s90, s89, 0
	v_add_u32_e32 v207, s90, v196
	ds_read_b128 v[128:131], v207
	v_add_u32_e32 v208, s90, v197
	ds_read_b128 v[210:213], v208
	v_add_u32_e32 v209, s90, v198
	v_lshrrev_b32_e32 v205, 3, v204
	s_add_i32 s91, s4, 31
	v_and_or_b32 v206, v204, 31, s83
	s_cmp_le_i32 s91, s83
	s_waitcnt lgkmcnt(1)
	v_mfma_f32_32x32x16_bf16 v[128:143], v[128:131], v[144:147], 0
	s_waitcnt lgkmcnt(0)
	v_mfma_f32_32x32x16_bf16 v[128:143], v[210:213], v[148:151], v[128:143]
	ds_read_b128 v[212:215], v209
	v_add_u32_e32 v210, s90, v199
	v_add_u32_e32 v211, s90, v200
	s_waitcnt lgkmcnt(0)
	v_mfma_f32_32x32x16_bf16 v[128:143], v[212:215], v[152:155], v[128:143]
	ds_read_b128 v[212:215], v210
	s_waitcnt lgkmcnt(0)
	v_mfma_f32_32x32x16_bf16 v[128:143], v[212:215], v[156:159], v[128:143]
	ds_read_b128 v[214:217], v211
	v_add_u32_e32 v212, s90, v201
	v_add_u32_e32 v213, s90, v202
	s_waitcnt lgkmcnt(0)
	v_mfma_f32_32x32x16_bf16 v[128:143], v[214:217], v[160:163], v[128:143]
	ds_read_b128 v[214:217], v212
	s_waitcnt lgkmcnt(0)
	v_mfma_f32_32x32x16_bf16 v[128:143], v[214:217], v[164:167], v[128:143]
	ds_read_b128 v[216:219], v213
	v_add_u32_e32 v215, s90, v203
	v_and_b32_e32 v214, 4, v205
	s_waitcnt lgkmcnt(0)
	v_mfma_f32_32x32x16_bf16 v[128:143], v[216:219], v[168:171], v[128:143]
	ds_read_b128 v[216:219], v215
	s_waitcnt lgkmcnt(0)
	v_mfma_f32_32x32x16_bf16 v[128:143], v[216:219], v[172:175], v[128:143]
	s_cbranch_scc1 .LBB0_869
	v_add_u32_e32 v205, s4, v214
	v_cmp_lt_i32_e32 vcc, v205, v206
	v_add_u32_e32 v216, 2, v205
	s_nop 7
	v_cndmask_b32_e32 v129, v192, v129, vcc
	v_cmp_le_i32_e32 vcc, v205, v206
	s_nop 1
	v_cndmask_b32_e32 v128, v192, v128, vcc
	v_cmp_le_i32_e32 vcc, v216, v206
	v_add_u32_e32 v216, 3, v205
	s_nop 0
	v_cndmask_b32_e32 v130, v192, v130, vcc
	v_cmp_le_i32_e32 vcc, v216, v206
	v_add_u32_e32 v216, 8, v205
	s_nop 0
	v_cndmask_b32_e32 v131, v192, v131, vcc
	v_cmp_le_i32_e32 vcc, v216, v206
	v_add_u32_e32 v216, 9, v205
	s_nop 0
	v_cndmask_b32_e32 v132, v192, v132, vcc
	v_cmp_le_i32_e32 vcc, v216, v206
	v_add_u32_e32 v216, 10, v205
	s_nop 0
	v_cndmask_b32_e32 v133, v192, v133, vcc
	v_cmp_le_i32_e32 vcc, v216, v206
	v_add_u32_e32 v216, 11, v205
	s_nop 0
	v_cndmask_b32_e32 v134, v192, v134, vcc
	v_cmp_le_i32_e32 vcc, v216, v206
	v_add_u32_e32 v216, 16, v205
	s_nop 0
	v_cndmask_b32_e32 v135, v192, v135, vcc
	v_cmp_le_i32_e32 vcc, v216, v206
	v_add_u32_e32 v216, 17, v205
	s_nop 0
	v_cndmask_b32_e32 v136, v192, v136, vcc
	v_cmp_le_i32_e32 vcc, v216, v206
	v_add_u32_e32 v216, 18, v205
	s_nop 0
	v_cndmask_b32_e32 v137, v192, v137, vcc
	v_cmp_le_i32_e32 vcc, v216, v206
	v_add_u32_e32 v216, 19, v205
	s_nop 0
	v_cndmask_b32_e32 v138, v192, v138, vcc
	v_cmp_le_i32_e32 vcc, v216, v206
	v_add_u32_e32 v216, 24, v205
	s_nop 0
	v_cndmask_b32_e32 v139, v192, v139, vcc
	v_cmp_le_i32_e32 vcc, v216, v206
	v_add_u32_e32 v216, 25, v205
	s_nop 0
	v_cndmask_b32_e32 v140, v192, v140, vcc
	v_cmp_le_i32_e32 vcc, v216, v206
	v_add_u32_e32 v216, 26, v205
	v_add_u32_e32 v205, 27, v205
	v_cndmask_b32_e32 v141, v192, v141, vcc
	v_cmp_le_i32_e32 vcc, v216, v206
	s_nop 1
	v_cndmask_b32_e32 v142, v192, v142, vcc
	v_cmp_le_i32_e32 vcc, v205, v206
	s_nop 1
	v_cndmask_b32_e32 v143, v192, v143, vcc

.LBB0_883:
	s_cmp_ge_u32 s85, s78
	s_cselect_b64 s[12:13], -1, 0
	v_mov_b32_e32 v204, v176
	s_and_b64 vcc, exec, s[12:13]
	s_cbranch_vccnz .LBB0_885
	s_add_i32 s100, s84, 63
	s_cmp_le_i32 s100, s80
	s_cbranch_scc1 .LBB0_885
	v_sub_co_u32_e64 v128, s[14:15], s38, 1
	s_nop 1
	v_cndmask_b32_e64 v130, v128, 2, s[14:15]
	v_lshlrev_b32_e32 v128, 14, v130
	v_add_u32_e32 v131, s40, v128
	v_lshl_add_u64 v[128:129], s[22:23], 0, v[178:179]
	s_add_u32 s14, s22, 0x1000
	v_readfirstlane_b32 s39, v131
	s_mov_b32 s52, m0
	s_mov_b32 m0, s39
	s_nop 0
	global_load_lds_dwordx4 v[128:129], off
	s_mov_b32 m0, s52
	v_lshl_add_u64 v[128:129], s[22:23], 0, v[180:181]
	s_addc_u32 s15, s23, 0
	s_addk_i32 s39, 0x400
	s_mov_b32 s52, m0
	s_mov_b32 m0, s39
	s_nop 0
	global_load_lds_dwordx4 v[128:129], off
	s_mov_b32 m0, s52
	v_lshlrev_b32_e32 v128, 15, v130
	v_add_u32_e32 v130, s41, v128
	v_lshl_add_u64 v[128:129], s[14:15], 0, v[182:183]
	v_readfirstlane_b32 s39, v130
	s_mov_b32 s52, m0
	s_mov_b32 m0, s39
	s_nop 0
	global_load_lds_dwordx4 v[128:129], off
	s_mov_b32 m0, s52
	v_lshl_add_u64 v[128:129], s[14:15], 0, v[184:185]
	s_add_i32 s52, s39, 0x400
	s_mov_b32 s53, m0
	s_mov_b32 m0, s52
	s_nop 0
	global_load_lds_dwordx4 v[128:129], off
	s_mov_b32 m0, s53
	v_lshl_add_u64 v[128:129], s[14:15], 0, v[186:187]
	s_add_i32 s52, s39, 0x800
	s_mov_b32 s53, m0
	s_mov_b32 m0, s52
	s_nop 0
	global_load_lds_dwordx4 v[128:129], off
	s_mov_b32 m0, s53
	v_lshl_add_u64 v[128:129], s[14:15], 0, v[188:189]
	s_add_i32 s14, s39, 0xc00
	s_mov_b32 s15, m0
	s_mov_b32 m0, s14
	s_nop 0
	global_load_lds_dwordx4 v[128:129], off
	s_mov_b32 m0, s15
.LBB0_885:
	s_cmp_gt_i32 s84, s81
	s_cbranch_scc1 .LBB0_896
	s_add_i32 s100, s84, 63
	s_cmp_le_i32 s100, s80
	s_cbranch_scc0 .Latt_slow_2
	s_lshl_b32 s98, s38, 14
	s_lshl_b32 s99, s38, 15
	s_add_i32 s99, s99, 0xc000
	v_add_u32_e32 v206, s98, v195
	ds_read_b128 v[206:209], v206
	v_add_u32_e32 v210, s98, v196
	ds_read_b128 v[210:213], v210
	v_add_u32_e32 v214, s98, v197
	ds_read_b128 v[214:217], v214
	v_add_u32_e32 v222, s98, v198
	ds_read_b128 v[222:225], v222
	v_add_u32_e32 v226, s98, v199
	ds_read_b128 v[226:229], v226
	v_add_u32_e32 v230, s98, v200
	ds_read_b128 v[230:233], v230
	v_add_u32_e32 v234, s98, v201
	ds_read_b128 v[234:237], v234
	v_add_u32_e32 v238, s98, v202
	ds_read_b128 v[238:241], v238
	v_bfe_u32 v246, v204, 2, 2
	v_bfe_u32 v247, v204, 5, 1
	v_lshl_or_b32 v247, v247, 2, v246
	v_and_b32_e32 v249, 3, v204
	v_and_b32_e32 v254, 16, v204
	v_lshl_or_b32 v249, v249, 2, v254
	v_lshlrev_b32_e32 v249, 1, v249
	v_lshl_add_u32 v247, v247, 9, v249
	v_add_u32_e32 v247, s99, v247
	v_lshlrev_b32_e32 v246, 6, v246
	v_add_u32_e32 v205, v247, v246
	v_xor_b32_e32 v249, 64, v246
	v_add_u32_e32 v218, v247, v249
	v_xor_b32_e32 v249, 0x80, v246
	v_add_u32_e32 v219, v247, v249
	v_xor_b32_e32 v249, 0xc0, v246
	v_add_u32_e32 v221, v247, v249
	s_waitcnt lgkmcnt(7)
	v_mfma_f32_32x32x16_bf16 v[128:143], v[206:209], v[144:147], 0
	v_add_u32_e32 v206, s98, v195
	ds_read_b128 v[206:209], v206 offset:8192
	s_waitcnt lgkmcnt(7)
	v_mfma_f32_32x32x16_bf16 v[128:143], v[210:213], v[148:151], v[128:143]
	v_add_u32_e32 v210, s98, v196
	ds_read_b128 v[210:213], v210 offset:8192
	s_waitcnt lgkmcnt(7)
	v_mfma_f32_32x32x16_bf16 v[128:143], v[214:217], v[152:155], v[128:143]
	v_add_u32_e32 v214, s98, v197
	ds_read_b128 v[214:217], v214 offset:8192
	s_waitcnt lgkmcnt(7)
	v_mfma_f32_32x32x16_bf16 v[128:143], v[222:225], v[156:159], v[128:143]
	v_add_u32_e32 v222, s98, v198
	ds_read_b128 v[222:225], v222 offset:8192
	s_waitcnt lgkmcnt(7)
	v_mfma_f32_32x32x16_bf16 v[128:143], v[226:229], v[160:163], v[128:143]
	v_add_u32_e32 v226, s98, v199
	ds_read_b128 v[226:229], v226 offset:8192
	s_waitcnt lgkmcnt(7)
	v_mfma_f32_32x32x16_bf16 v[128:143], v[230:233], v[164:167], v[128:143]
	v_add_u32_e32 v230, s98, v200
	ds_read_b128 v[230:233], v230 offset:8192
	s_waitcnt lgkmcnt(7)
	v_mfma_f32_32x32x16_bf16 v[128:143], v[234:237], v[168:171], v[128:143]
	v_add_u32_e32 v234, s98, v201
	ds_read_b128 v[234:237], v234 offset:8192
	s_waitcnt lgkmcnt(7)
	v_mfma_f32_32x32x16_bf16 v[128:143], v[238:241], v[172:175], v[128:143]
	v_add_u32_e32 v238, s98, v202
	ds_read_b128 v[238:241], v238 offset:8192
	s_nop 9
	v_max3_f32 v246, v128, v129, v130
	v_max3_f32 v247, v131, v132, v133
	v_max3_f32 v246, v246, v134, v135
	v_max3_f32 v247, v247, v136, v137
	v_max3_f32 v246, v246, v138, v139
	v_max3_f32 v247, v247, v140, v141
	v_max3_f32 v246, v246, v142, v143
	v_max_f32_e32 v246, v246, v247
	v_mov_b32_e32 v247, v246
	v_add_f32_e32 v249, 0x41000000, v190
	s_nop 1
	v_permlane32_swap_b32_e32 v246, v247
	v_max_f32_e32 v246, v246, v247
	v_cmp_gt_f32_e32 vcc, v246, v249
	s_cbranch_vccz .Latt_nr0_2
	v_max_f32_e32 v246, v190, v246
	v_sub_f32_e32 v190, v190, v246
	v_exp_f32_e32 v190, v190
	s_nop 0
	v_pk_mul_f32 v[126:127], v[126:127], v[190:191] op_sel_hi:[1,0]
	v_pk_mul_f32 v[124:125], v[124:125], v[190:191] op_sel_hi:[1,0]
	v_pk_mul_f32 v[122:123], v[122:123], v[190:191] op_sel_hi:[1,0]
	v_pk_mul_f32 v[120:121], v[120:121], v[190:191] op_sel_hi:[1,0]
	v_pk_mul_f32 v[118:119], v[118:119], v[190:191] op_sel_hi:[1,0]
	v_pk_mul_f32 v[116:117], v[116:117], v[190:191] op_sel_hi:[1,0]
	v_pk_mul_f32 v[114:115], v[114:115], v[190:191] op_sel_hi:[1,0]
	v_pk_mul_f32 v[112:113], v[112:113], v[190:191] op_sel_hi:[1,0]
	v_pk_mul_f32 v[110:111], v[110:111], v[190:191] op_sel_hi:[1,0]
	v_pk_mul_f32 v[108:109], v[108:109], v[190:191] op_sel_hi:[1,0]
	v_pk_mul_f32 v[106:107], v[106:107], v[190:191] op_sel_hi:[1,0]
	v_pk_mul_f32 v[104:105], v[104:105], v[190:191] op_sel_hi:[1,0]
	v_pk_mul_f32 v[102:103], v[102:103], v[190:191] op_sel_hi:[1,0]
	v_pk_mul_f32 v[100:101], v[100:101], v[190:191] op_sel_hi:[1,0]
	v_pk_mul_f32 v[98:99], v[98:99], v[190:191] op_sel_hi:[1,0]
	v_pk_mul_f32 v[96:97], v[96:97], v[190:191] op_sel_hi:[1,0]
	v_pk_mul_f32 v[94:95], v[94:95], v[190:191] op_sel_hi:[1,0]
	v_pk_mul_f32 v[92:93], v[92:93], v[190:191] op_sel_hi:[1,0]
	v_pk_mul_f32 v[90:91], v[90:91], v[190:191] op_sel_hi:[1,0]
	v_pk_mul_f32 v[88:89], v[88:89], v[190:191] op_sel_hi:[1,0]
	v_pk_mul_f32 v[86:87], v[86:87], v[190:191] op_sel_hi:[1,0]
	v_pk_mul_f32 v[84:85], v[84:85], v[190:191] op_sel_hi:[1,0]
	v_pk_mul_f32 v[82:83], v[82:83], v[190:191] op_sel_hi:[1,0]
	v_pk_mul_f32 v[80:81], v[80:81], v[190:191] op_sel_hi:[1,0]
	v_pk_mul_f32 v[78:79], v[78:79], v[190:191] op_sel_hi:[1,0]
	v_pk_mul_f32 v[76:77], v[76:77], v[190:191] op_sel_hi:[1,0]
	v_pk_mul_f32 v[74:75], v[74:75], v[190:191] op_sel_hi:[1,0]
	v_pk_mul_f32 v[72:73], v[72:73], v[190:191] op_sel_hi:[1,0]
	v_pk_mul_f32 v[70:71], v[70:71], v[190:191] op_sel_hi:[1,0]
	v_pk_mul_f32 v[68:69], v[68:69], v[190:191] op_sel_hi:[1,0]
	v_pk_mul_f32 v[66:67], v[66:67], v[190:191] op_sel_hi:[1,0]
	v_pk_mul_f32 v[64:65], v[64:65], v[190:191] op_sel_hi:[1,0]
	v_pk_mul_f32 v[62:63], v[62:63], v[190:191] op_sel_hi:[1,0]
	v_pk_mul_f32 v[60:61], v[60:61], v[190:191] op_sel_hi:[1,0]
	v_pk_mul_f32 v[58:59], v[58:59], v[190:191] op_sel_hi:[1,0]
	v_pk_mul_f32 v[56:57], v[56:57], v[190:191] op_sel_hi:[1,0]
	v_pk_mul_f32 v[54:55], v[54:55], v[190:191] op_sel_hi:[1,0]
	v_pk_mul_f32 v[52:53], v[52:53], v[190:191] op_sel_hi:[1,0]
	v_pk_mul_f32 v[50:51], v[50:51], v[190:191] op_sel_hi:[1,0]
	v_pk_mul_f32 v[48:49], v[48:49], v[190:191] op_sel_hi:[1,0]
	v_pk_mul_f32 v[46:47], v[46:47], v[190:191] op_sel_hi:[1,0]
	v_pk_mul_f32 v[44:45], v[44:45], v[190:191] op_sel_hi:[1,0]
	v_pk_mul_f32 v[42:43], v[42:43], v[190:191] op_sel_hi:[1,0]
	v_pk_mul_f32 v[40:41], v[40:41], v[190:191] op_sel_hi:[1,0]
	v_pk_mul_f32 v[38:39], v[38:39], v[190:191] op_sel_hi:[1,0]
	v_pk_mul_f32 v[36:37], v[36:37], v[190:191] op_sel_hi:[1,0]
	v_pk_mul_f32 v[34:35], v[34:35], v[190:191] op_sel_hi:[1,0]
	v_pk_mul_f32 v[32:33], v[32:33], v[190:191] op_sel_hi:[1,0]
	v_pk_mul_f32 v[30:31], v[30:31], v[190:191] op_sel_hi:[1,0]
	v_pk_mul_f32 v[28:29], v[28:29], v[190:191] op_sel_hi:[1,0]
	v_pk_mul_f32 v[26:27], v[26:27], v[190:191] op_sel_hi:[1,0]
	v_pk_mul_f32 v[24:25], v[24:25], v[190:191] op_sel_hi:[1,0]
	v_pk_mul_f32 v[22:23], v[22:23], v[190:191] op_sel_hi:[1,0]
	v_pk_mul_f32 v[20:21], v[20:21], v[190:191] op_sel_hi:[1,0]
	v_pk_mul_f32 v[18:19], v[18:19], v[190:191] op_sel_hi:[1,0]
	v_pk_mul_f32 v[16:17], v[16:17], v[190:191] op_sel_hi:[1,0]
	v_pk_mul_f32 v[14:15], v[14:15], v[190:191] op_sel_hi:[1,0]
	v_pk_mul_f32 v[12:13], v[12:13], v[190:191] op_sel_hi:[1,0]
	v_pk_mul_f32 v[10:11], v[10:11], v[190:191] op_sel_hi:[1,0]
	v_pk_mul_f32 v[8:9], v[8:9], v[190:191] op_sel_hi:[1,0]
	v_pk_mul_f32 v[6:7], v[6:7], v[190:191] op_sel_hi:[1,0]
	v_pk_mul_f32 v[4:5], v[4:5], v[190:191] op_sel_hi:[1,0]
	v_pk_mul_f32 v[2:3], v[2:3], v[190:191] op_sel_hi:[1,0]
	v_pk_mul_f32 v[0:1], v[0:1], v[190:191] op_sel_hi:[1,0]
	v_mul_f32_e32 v203, v203, v190
	v_mov_b32_e32 v190, v246
.Latt_nr0_2:
	v_sub_f32_e32 v128, v128, v190
	v_exp_f32_e32 v128, v128
	v_sub_f32_e32 v129, v129, v190
	v_exp_f32_e32 v129, v129
	v_sub_f32_e32 v130, v130, v190
	v_add_f32_e32 v254, 0, v128
	v_exp_f32_e32 v130, v130
	v_sub_f32_e32 v131, v131, v190
	v_add_f32_e32 v254, v129, v254
	v_exp_f32_e32 v131, v131
	v_sub_f32_e32 v132, v132, v190
	v_add_f32_e32 v254, v130, v254
	v_exp_f32_e32 v132, v132
	v_sub_f32_e32 v133, v133, v190
	v_add_f32_e32 v254, v131, v254
	v_exp_f32_e32 v133, v133
	v_sub_f32_e32 v134, v134, v190
	v_add_f32_e32 v254, v132, v254
	v_exp_f32_e32 v134, v134
	v_sub_f32_e32 v135, v135, v190
	v_add_f32_e32 v254, v133, v254
	v_exp_f32_e32 v135, v135
	v_sub_f32_e32 v136, v136, v190
	v_add_f32_e32 v254, v134, v254
	v_exp_f32_e32 v136, v136
	v_sub_f32_e32 v137, v137, v190
	v_add_f32_e32 v254, v135, v254
	v_exp_f32_e32 v137, v137
	v_sub_f32_e32 v138, v138, v190
	v_add_f32_e32 v254, v136, v254
	v_exp_f32_e32 v138, v138
	v_sub_f32_e32 v139, v139, v190
	v_add_f32_e32 v254, v137, v254
	v_exp_f32_e32 v139, v139
	v_sub_f32_e32 v140, v140, v190
	v_add_f32_e32 v254, v138, v254
	v_exp_f32_e32 v140, v140
	v_sub_f32_e32 v141, v141, v190
	v_add_f32_e32 v254, v139, v254
	v_exp_f32_e32 v141, v141
	v_sub_f32_e32 v142, v142, v190
	v_add_f32_e32 v254, v140, v254
	v_exp_f32_e32 v142, v142
	v_sub_f32_e32 v143, v143, v190
	v_add_f32_e32 v254, v141, v254
	v_exp_f32_e32 v143, v143
	v_add_f32_e32 v254, v142, v254
	v_add_f32_e32 v254, v143, v254
	v_cvt_pk_bf16_f32 v242, v128, v129
	v_cvt_pk_bf16_f32 v243, v130, v131
	v_cvt_pk_bf16_f32 v244, v132, v133
	v_cvt_pk_bf16_f32 v245, v134, v135
	v_cvt_pk_bf16_f32 v250, v136, v137
	v_cvt_pk_bf16_f32 v251, v138, v139
	v_cvt_pk_bf16_f32 v252, v140, v141
	v_cvt_pk_bf16_f32 v253, v142, v143
	v_add_f32_e32 v203, v203, v254
	s_nop 1
	s_waitcnt lgkmcnt(7)
	v_mfma_f32_32x32x16_bf16 v[128:143], v[206:209], v[144:147], 0
	ds_read_b64_tr_b16 v[206:207], v205
	ds_read_b64_tr_b16 v[208:209], v205 offset:4096
	s_waitcnt lgkmcnt(8)
	v_mfma_f32_32x32x16_bf16 v[128:143], v[210:213], v[148:151], v[128:143]
	ds_read_b64_tr_b16 v[210:211], v218
	ds_read_b64_tr_b16 v[212:213], v218 offset:4096
	s_waitcnt lgkmcnt(9)
	v_mfma_f32_32x32x16_bf16 v[128:143], v[214:217], v[152:155], v[128:143]
	ds_read_b64_tr_b16 v[214:215], v219
	ds_read_b64_tr_b16 v[216:217], v219 offset:4096
	s_waitcnt lgkmcnt(10)
	v_mfma_f32_32x32x16_bf16 v[128:143], v[222:225], v[156:159], v[128:143]
	ds_read_b64_tr_b16 v[222:223], v221
	ds_read_b64_tr_b16 v[224:225], v221 offset:4096
	s_waitcnt lgkmcnt(11)
	v_mfma_f32_32x32x16_bf16 v[128:143], v[226:229], v[160:163], v[128:143]
	ds_read_b64_tr_b16 v[226:227], v205 offset:256
	ds_read_b64_tr_b16 v[228:229], v205 offset:4352
	s_waitcnt lgkmcnt(12)
	v_mfma_f32_32x32x16_bf16 v[128:143], v[230:233], v[164:167], v[128:143]
	ds_read_b64_tr_b16 v[230:231], v218 offset:256
	ds_read_b64_tr_b16 v[232:233], v218 offset:4352
	s_waitcnt lgkmcnt(13)
	v_mfma_f32_32x32x16_bf16 v[128:143], v[234:237], v[168:171], v[128:143]
	s_waitcnt lgkmcnt(12)
	v_mfma_f32_32x32x16_bf16 v[128:143], v[238:241], v[172:175], v[128:143]
	ds_read_b64_tr_b16 v[234:235], v219 offset:256
	ds_read_b64_tr_b16 v[236:237], v219 offset:4352
	s_waitcnt lgkmcnt(12)
	v_mfma_f32_32x32x16_bf16 v[112:127], v[206:209], v[242:245], v[112:127]
	ds_read_b64_tr_b16 v[238:239], v221 offset:256
	ds_read_b64_tr_b16 v[240:241], v221 offset:4352
	s_waitcnt lgkmcnt(12)
	v_mfma_f32_32x32x16_bf16 v[96:111], v[210:213], v[242:245], v[96:111]
	ds_read_b64_tr_b16 v[206:207], v205 offset:8192
	ds_read_b64_tr_b16 v[208:209], v205 offset:12288
	s_waitcnt lgkmcnt(12)
	v_mfma_f32_32x32x16_bf16 v[80:95], v[214:217], v[242:245], v[80:95]
	ds_read_b64_tr_b16 v[210:211], v218 offset:8192
	ds_read_b64_tr_b16 v[212:213], v218 offset:12288
	v_max3_f32 v246, v128, v129, v130
	v_max3_f32 v247, v131, v132, v133
	v_max3_f32 v246, v246, v134, v135
	v_max3_f32 v247, v247, v136, v137
	v_max3_f32 v246, v246, v138, v139
	v_max3_f32 v247, v247, v140, v141
	s_waitcnt lgkmcnt(12)
	v_mfma_f32_32x32x16_bf16 v[64:79], v[222:225], v[242:245], v[64:79]
	ds_read_b64_tr_b16 v[214:215], v219 offset:8192
	ds_read_b64_tr_b16 v[216:217], v219 offset:12288
	v_max3_f32 v246, v246, v142, v143
	v_max_f32_e32 v246, v246, v247
	v_mov_b32_e32 v247, v246
	v_add_f32_e32 v249, 0x41000000, v190
	s_nop 1
	s_waitcnt lgkmcnt(12)
	v_mfma_f32_32x32x16_bf16 v[48:63], v[226:229], v[242:245], v[48:63]
	ds_read_b64_tr_b16 v[222:223], v221 offset:8192
	ds_read_b64_tr_b16 v[224:225], v221 offset:12288
	v_permlane32_swap_b32_e32 v246, v247
	v_max_f32_e32 v246, v246, v247
	v_cmp_gt_f32_e32 vcc, v246, v249
	s_cbranch_vccnz .Latt_rs1_2
	s_waitcnt lgkmcnt(12)
	v_mfma_f32_32x32x16_bf16 v[32:47], v[230:233], v[242:245], v[32:47]
	ds_read_b64_tr_b16 v[226:227], v205 offset:8448
	ds_read_b64_tr_b16 v[228:229], v205 offset:12544
	v_sub_f32_e32 v128, v128, v190
	v_exp_f32_e32 v128, v128
	v_sub_f32_e32 v129, v129, v190
	v_exp_f32_e32 v129, v129
	v_sub_f32_e32 v130, v130, v190
	s_waitcnt lgkmcnt(12)
	v_mfma_f32_32x32x16_bf16 v[16:31], v[234:237], v[242:245], v[16:31]
	ds_read_b64_tr_b16 v[230:231], v218 offset:8448
	ds_read_b64_tr_b16 v[232:233], v218 offset:12544
	v_add_f32_e32 v254, 0, v128
	v_exp_f32_e32 v130, v130
	v_sub_f32_e32 v131, v131, v190
	v_add_f32_e32 v254, v129, v254
	v_exp_f32_e32 v131, v131
	s_waitcnt lgkmcnt(12)
	v_mfma_f32_32x32x16_bf16 v[0:15], v[238:241], v[242:245], v[0:15]
	ds_read_b64_tr_b16 v[234:235], v219 offset:8448
	ds_read_b64_tr_b16 v[236:237], v219 offset:12544
	v_sub_f32_e32 v132, v132, v190
	v_add_f32_e32 v254, v130, v254
	v_exp_f32_e32 v132, v132
	v_sub_f32_e32 v133, v133, v190
	v_add_f32_e32 v254, v131, v254
	s_waitcnt lgkmcnt(12)
	v_mfma_f32_32x32x16_bf16 v[112:127], v[206:209], v[250:253], v[112:127]
	ds_read_b64_tr_b16 v[238:239], v221 offset:8448
	ds_read_b64_tr_b16 v[240:241], v221 offset:12544
	v_exp_f32_e32 v133, v133
	v_sub_f32_e32 v134, v134, v190
	v_add_f32_e32 v254, v132, v254
	v_exp_f32_e32 v134, v134
	v_sub_f32_e32 v135, v135, v190
	s_waitcnt lgkmcnt(12)
	v_mfma_f32_32x32x16_bf16 v[96:111], v[210:213], v[250:253], v[96:111]
	ds_read_b64_tr_b16 v[206:207], v205 offset:16384
	ds_read_b64_tr_b16 v[208:209], v205 offset:20480
	v_add_f32_e32 v254, v133, v254
	v_exp_f32_e32 v135, v135
	v_sub_f32_e32 v136, v136, v190
	v_add_f32_e32 v254, v134, v254
	s_waitcnt lgkmcnt(12)
	v_mfma_f32_32x32x16_bf16 v[80:95], v[214:217], v[250:253], v[80:95]
	ds_read_b64_tr_b16 v[210:211], v218 offset:16384
	ds_read_b64_tr_b16 v[212:213], v218 offset:20480
	v_exp_f32_e32 v136, v136
	v_sub_f32_e32 v137, v137, v190
	v_add_f32_e32 v254, v135, v254
	v_exp_f32_e32 v137, v137
	s_waitcnt lgkmcnt(12)
	v_mfma_f32_32x32x16_bf16 v[64:79], v[222:225], v[250:253], v[64:79]
	ds_read_b64_tr_b16 v[214:215], v219 offset:16384
	ds_read_b64_tr_b16 v[216:217], v219 offset:20480
	v_sub_f32_e32 v138, v138, v190
	v_add_f32_e32 v254, v136, v254
	v_exp_f32_e32 v138, v138
	v_sub_f32_e32 v139, v139, v190
	s_waitcnt lgkmcnt(12)
	v_mfma_f32_32x32x16_bf16 v[48:63], v[226:229], v[250:253], v[48:63]
	ds_read_b64_tr_b16 v[222:223], v221 offset:16384
	ds_read_b64_tr_b16 v[224:225], v221 offset:20480
	v_add_f32_e32 v254, v137, v254
	v_exp_f32_e32 v139, v139
	v_sub_f32_e32 v140, v140, v190
	v_add_f32_e32 v254, v138, v254
	s_waitcnt lgkmcnt(12)
	v_mfma_f32_32x32x16_bf16 v[32:47], v[230:233], v[250:253], v[32:47]
	ds_read_b64_tr_b16 v[226:227], v205 offset:16640
	ds_read_b64_tr_b16 v[228:229], v205 offset:20736
	v_exp_f32_e32 v140, v140
	v_sub_f32_e32 v141, v141, v190
	v_add_f32_e32 v254, v139, v254
	v_exp_f32_e32 v141, v141
	s_waitcnt lgkmcnt(12)
	v_mfma_f32_32x32x16_bf16 v[16:31], v[234:237], v[250:253], v[16:31]
	ds_read_b64_tr_b16 v[230:231], v218 offset:16640
	ds_read_b64_tr_b16 v[232:233], v218 offset:20736
	v_sub_f32_e32 v142, v142, v190
	v_add_f32_e32 v254, v140, v254
	v_exp_f32_e32 v142, v142
	v_sub_f32_e32 v143, v143, v190
	s_waitcnt lgkmcnt(12)
	v_mfma_f32_32x32x16_bf16 v[0:15], v[238:241], v[250:253], v[0:15]
	ds_read_b64_tr_b16 v[234:235], v219 offset:16640
	ds_read_b64_tr_b16 v[236:237], v219 offset:20736
	v_add_f32_e32 v254, v141, v254
	v_exp_f32_e32 v143, v143
	v_add_f32_e32 v254, v142, v254
	v_add_f32_e32 v254, v143, v254
	v_cvt_pk_bf16_f32 v242, v128, v129
	v_cvt_pk_bf16_f32 v243, v130, v131
	v_cvt_pk_bf16_f32 v244, v132, v133
	v_cvt_pk_bf16_f32 v245, v134, v135
	v_cvt_pk_bf16_f32 v250, v136, v137
	v_cvt_pk_bf16_f32 v251, v138, v139
	v_cvt_pk_bf16_f32 v252, v140, v141
	v_cvt_pk_bf16_f32 v253, v142, v143
	v_add_f32_e32 v203, v203, v254
	s_nop 1
.Latt_pv1_2:
	s_waitcnt lgkmcnt(12)
	v_mfma_f32_32x32x16_bf16 v[112:127], v[206:209], v[242:245], v[112:127]
	ds_read_b64_tr_b16 v[238:239], v221 offset:16640
	ds_read_b64_tr_b16 v[240:241], v221 offset:20736
	s_waitcnt lgkmcnt(12)
	v_mfma_f32_32x32x16_bf16 v[96:111], v[210:213], v[242:245], v[96:111]
	ds_read_b64_tr_b16 v[206:207], v205 offset:24576
	ds_read_b64_tr_b16 v[208:209], v205 offset:28672
	s_cmp_lg_u64 s[12:13], 0
	s_cbranch_scc1 .Latt_nd0_2
	s_sub_i32 s100, s38, 1
	s_cmp_eq_u32 s38, 0
	s_cselect_b32 s100, 2, s100
	s_lshl_b32 s101, s100, 14
	s_add_i32 m0, s40, s101
	s_nop 0
	global_load_lds_dwordx4 v178, s[22:23]
.Latt_nd0_2:
	s_waitcnt lgkmcnt(12)
	v_mfma_f32_32x32x16_bf16 v[80:95], v[214:217], v[242:245], v[80:95]
	ds_read_b64_tr_b16 v[210:211], v218 offset:24576
	ds_read_b64_tr_b16 v[212:213], v218 offset:28672
	s_waitcnt lgkmcnt(12)
	v_mfma_f32_32x32x16_bf16 v[64:79], v[222:225], v[242:245], v[64:79]
	ds_read_b64_tr_b16 v[214:215], v219 offset:24576
	ds_read_b64_tr_b16 v[216:217], v219 offset:28672
	s_cmp_lg_u64 s[12:13], 0
	s_cbranch_scc1 .Latt_nd1_2
	s_add_i32 m0, m0, 0x400
	s_nop 0
	global_load_lds_dwordx4 v180, s[22:23]
.Latt_nd1_2:
	s_waitcnt lgkmcnt(12)
	v_mfma_f32_32x32x16_bf16 v[48:63], v[226:229], v[242:245], v[48:63]
	ds_read_b64_tr_b16 v[222:223], v221 offset:24576
	ds_read_b64_tr_b16 v[224:225], v221 offset:28672
	s_waitcnt lgkmcnt(12)
	v_mfma_f32_32x32x16_bf16 v[32:47], v[230:233], v[242:245], v[32:47]
	ds_read_b64_tr_b16 v[226:227], v205 offset:24832
	ds_read_b64_tr_b16 v[228:229], v205 offset:28928
	s_cmp_lg_u64 s[12:13], 0
	s_cbranch_scc1 .Latt_nd2_2
	s_lshl_b32 s101, s100, 15
	s_add_i32 m0, s41, s101
	s_add_u32 s100, s22, 0x1000
	s_addc_u32 s101, s23, 0
	global_load_lds_dwordx4 v182, s[100:101]
.Latt_nd2_2:
	s_waitcnt lgkmcnt(12)
	v_mfma_f32_32x32x16_bf16 v[16:31], v[234:237], v[242:245], v[16:31]
	ds_read_b64_tr_b16 v[230:231], v218 offset:24832
	ds_read_b64_tr_b16 v[232:233], v218 offset:28928
	s_waitcnt lgkmcnt(12)
	v_mfma_f32_32x32x16_bf16 v[0:15], v[238:241], v[242:245], v[0:15]
	ds_read_b64_tr_b16 v[234:235], v219 offset:24832
	ds_read_b64_tr_b16 v[236:237], v219 offset:28928
	s_cmp_lg_u64 s[12:13], 0
	s_cbranch_scc1 .Latt_nd3_2
	s_add_i32 m0, m0, 0x400
	s_nop 0
	global_load_lds_dwordx4 v184, s[100:101]
.Latt_nd3_2:
	s_waitcnt lgkmcnt(12)
	v_mfma_f32_32x32x16_bf16 v[112:127], v[206:209], v[250:253], v[112:127]
	ds_read_b64_tr_b16 v[238:239], v221 offset:24832
	ds_read_b64_tr_b16 v[240:241], v221 offset:28928
	s_waitcnt lgkmcnt(12)
	v_mfma_f32_32x32x16_bf16 v[96:111], v[210:213], v[250:253], v[96:111]
	s_cmp_lg_u64 s[12:13], 0
	s_cbranch_scc1 .Latt_nd4_2
	s_add_i32 m0, m0, 0x400
	s_nop 0
	global_load_lds_dwordx4 v186, s[100:101]
.Latt_nd4_2:
	s_waitcnt lgkmcnt(10)
	v_mfma_f32_32x32x16_bf16 v[80:95], v[214:217], v[250:253], v[80:95]
	s_waitcnt lgkmcnt(8)
	v_mfma_f32_32x32x16_bf16 v[64:79], v[222:225], v[250:253], v[64:79]
	s_cmp_lg_u64 s[12:13], 0
	s_cbranch_scc1 .Latt_nd5_2
	s_add_i32 m0, m0, 0x400
	s_nop 0
	global_load_lds_dwordx4 v188, s[100:101]

.Latt_rs1_2:
	s_waitcnt lgkmcnt(12)
	v_mfma_f32_32x32x16_bf16 v[32:47], v[230:233], v[242:245], v[32:47]
	ds_read_b64_tr_b16 v[226:227], v205 offset:8448
	ds_read_b64_tr_b16 v[228:229], v205 offset:12544
	s_waitcnt lgkmcnt(12)
	v_mfma_f32_32x32x16_bf16 v[16:31], v[234:237], v[242:245], v[16:31]
	ds_read_b64_tr_b16 v[230:231], v218 offset:8448
	ds_read_b64_tr_b16 v[232:233], v218 offset:12544
	s_waitcnt lgkmcnt(12)
	v_mfma_f32_32x32x16_bf16 v[0:15], v[238:241], v[242:245], v[0:15]
	ds_read_b64_tr_b16 v[234:235], v219 offset:8448
	ds_read_b64_tr_b16 v[236:237], v219 offset:12544
	s_waitcnt lgkmcnt(12)
	v_mfma_f32_32x32x16_bf16 v[112:127], v[206:209], v[250:253], v[112:127]
	ds_read_b64_tr_b16 v[238:239], v221 offset:8448
	ds_read_b64_tr_b16 v[240:241], v221 offset:12544
	s_waitcnt lgkmcnt(12)
	v_mfma_f32_32x32x16_bf16 v[96:111], v[210:213], v[250:253], v[96:111]
	ds_read_b64_tr_b16 v[206:207], v205 offset:16384
	ds_read_b64_tr_b16 v[208:209], v205 offset:20480
	s_waitcnt lgkmcnt(12)
	v_mfma_f32_32x32x16_bf16 v[80:95], v[214:217], v[250:253], v[80:95]
	ds_read_b64_tr_b16 v[210:211], v218 offset:16384
	ds_read_b64_tr_b16 v[212:213], v218 offset:20480
	s_waitcnt lgkmcnt(12)
	v_mfma_f32_32x32x16_bf16 v[64:79], v[222:225], v[250:253], v[64:79]
	ds_read_b64_tr_b16 v[214:215], v219 offset:16384
	ds_read_b64_tr_b16 v[216:217], v219 offset:20480
	s_waitcnt lgkmcnt(12)
	v_mfma_f32_32x32x16_bf16 v[48:63], v[226:229], v[250:253], v[48:63]
	ds_read_b64_tr_b16 v[222:223], v221 offset:16384
	ds_read_b64_tr_b16 v[224:225], v221 offset:20480
	s_waitcnt lgkmcnt(12)
	v_mfma_f32_32x32x16_bf16 v[32:47], v[230:233], v[250:253], v[32:47]
	ds_read_b64_tr_b16 v[226:227], v205 offset:16640
	ds_read_b64_tr_b16 v[228:229], v205 offset:20736
	s_waitcnt lgkmcnt(12)
	v_mfma_f32_32x32x16_bf16 v[16:31], v[234:237], v[250:253], v[16:31]
	ds_read_b64_tr_b16 v[230:231], v218 offset:16640
	ds_read_b64_tr_b16 v[232:233], v218 offset:20736
	s_waitcnt lgkmcnt(12)
	v_mfma_f32_32x32x16_bf16 v[0:15], v[238:241], v[250:253], v[0:15]
	ds_read_b64_tr_b16 v[234:235], v219 offset:16640
	ds_read_b64_tr_b16 v[236:237], v219 offset:20736
	s_nop 11
	v_max_f32_e32 v246, v190, v246
	v_sub_f32_e32 v190, v190, v246
	v_exp_f32_e32 v190, v190
	s_nop 0
	v_pk_mul_f32 v[126:127], v[126:127], v[190:191] op_sel_hi:[1,0]
	v_pk_mul_f32 v[124:125], v[124:125], v[190:191] op_sel_hi:[1,0]
	v_pk_mul_f32 v[122:123], v[122:123], v[190:191] op_sel_hi:[1,0]
	v_pk_mul_f32 v[120:121], v[120:121], v[190:191] op_sel_hi:[1,0]
	v_pk_mul_f32 v[118:119], v[118:119], v[190:191] op_sel_hi:[1,0]
	v_pk_mul_f32 v[116:117], v[116:117], v[190:191] op_sel_hi:[1,0]
	v_pk_mul_f32 v[114:115], v[114:115], v[190:191] op_sel_hi:[1,0]
	v_pk_mul_f32 v[112:113], v[112:113], v[190:191] op_sel_hi:[1,0]
	v_pk_mul_f32 v[110:111], v[110:111], v[190:191] op_sel_hi:[1,0]
	v_pk_mul_f32 v[108:109], v[108:109], v[190:191] op_sel_hi:[1,0]
	v_pk_mul_f32 v[106:107], v[106:107], v[190:191] op_sel_hi:[1,0]
	v_pk_mul_f32 v[104:105], v[104:105], v[190:191] op_sel_hi:[1,0]
	v_pk_mul_f32 v[102:103], v[102:103], v[190:191] op_sel_hi:[1,0]
	v_pk_mul_f32 v[100:101], v[100:101], v[190:191] op_sel_hi:[1,0]
	v_pk_mul_f32 v[98:99], v[98:99], v[190:191] op_sel_hi:[1,0]
	v_pk_mul_f32 v[96:97], v[96:97], v[190:191] op_sel_hi:[1,0]
	v_pk_mul_f32 v[94:95], v[94:95], v[190:191] op_sel_hi:[1,0]
	v_pk_mul_f32 v[92:93], v[92:93], v[190:191] op_sel_hi:[1,0]
	v_pk_mul_f32 v[90:91], v[90:91], v[190:191] op_sel_hi:[1,0]
	v_pk_mul_f32 v[88:89], v[88:89], v[190:191] op_sel_hi:[1,0]
	v_pk_mul_f32 v[86:87], v[86:87], v[190:191] op_sel_hi:[1,0]
	v_pk_mul_f32 v[84:85], v[84:85], v[190:191] op_sel_hi:[1,0]
	v_pk_mul_f32 v[82:83], v[82:83], v[190:191] op_sel_hi:[1,0]
	v_pk_mul_f32 v[80:81], v[80:81], v[190:191] op_sel_hi:[1,0]
	v_pk_mul_f32 v[78:79], v[78:79], v[190:191] op_sel_hi:[1,0]
	v_pk_mul_f32 v[76:77], v[76:77], v[190:191] op_sel_hi:[1,0]
	v_pk_mul_f32 v[74:75], v[74:75], v[190:191] op_sel_hi:[1,0]
	v_pk_mul_f32 v[72:73], v[72:73], v[190:191] op_sel_hi:[1,0]
	v_pk_mul_f32 v[70:71], v[70:71], v[190:191] op_sel_hi:[1,0]
	v_pk_mul_f32 v[68:69], v[68:69], v[190:191] op_sel_hi:[1,0]
	v_pk_mul_f32 v[66:67], v[66:67], v[190:191] op_sel_hi:[1,0]
	v_pk_mul_f32 v[64:65], v[64:65], v[190:191] op_sel_hi:[1,0]
	v_pk_mul_f32 v[62:63], v[62:63], v[190:191] op_sel_hi:[1,0]
	v_pk_mul_f32 v[60:61], v[60:61], v[190:191] op_sel_hi:[1,0]
	v_pk_mul_f32 v[58:59], v[58:59], v[190:191] op_sel_hi:[1,0]
	v_pk_mul_f32 v[56:57], v[56:57], v[190:191] op_sel_hi:[1,0]
	v_pk_mul_f32 v[54:55], v[54:55], v[190:191] op_sel_hi:[1,0]
	v_pk_mul_f32 v[52:53], v[52:53], v[190:191] op_sel_hi:[1,0]
	v_pk_mul_f32 v[50:51], v[50:51], v[190:191] op_sel_hi:[1,0]
	v_pk_mul_f32 v[48:49], v[48:49], v[190:191] op_sel_hi:[1,0]
	v_pk_mul_f32 v[46:47], v[46:47], v[190:191] op_sel_hi:[1,0]
	v_pk_mul_f32 v[44:45], v[44:45], v[190:191] op_sel_hi:[1,0]
	v_pk_mul_f32 v[42:43], v[42:43], v[190:191] op_sel_hi:[1,0]
	v_pk_mul_f32 v[40:41], v[40:41], v[190:191] op_sel_hi:[1,0]
	v_pk_mul_f32 v[38:39], v[38:39], v[190:191] op_sel_hi:[1,0]
	v_pk_mul_f32 v[36:37], v[36:37], v[190:191] op_sel_hi:[1,0]
	v_pk_mul_f32 v[34:35], v[34:35], v[190:191] op_sel_hi:[1,0]
	v_pk_mul_f32 v[32:33], v[32:33], v[190:191] op_sel_hi:[1,0]
	v_pk_mul_f32 v[30:31], v[30:31], v[190:191] op_sel_hi:[1,0]
	v_pk_mul_f32 v[28:29], v[28:29], v[190:191] op_sel_hi:[1,0]
	v_pk_mul_f32 v[26:27], v[26:27], v[190:191] op_sel_hi:[1,0]
	v_pk_mul_f32 v[24:25], v[24:25], v[190:191] op_sel_hi:[1,0]
	v_pk_mul_f32 v[22:23], v[22:23], v[190:191] op_sel_hi:[1,0]
	v_pk_mul_f32 v[20:21], v[20:21], v[190:191] op_sel_hi:[1,0]
	v_pk_mul_f32 v[18:19], v[18:19], v[190:191] op_sel_hi:[1,0]
	v_pk_mul_f32 v[16:17], v[16:17], v[190:191] op_sel_hi:[1,0]
	v_pk_mul_f32 v[14:15], v[14:15], v[190:191] op_sel_hi:[1,0]
	v_pk_mul_f32 v[12:13], v[12:13], v[190:191] op_sel_hi:[1,0]
	v_pk_mul_f32 v[10:11], v[10:11], v[190:191] op_sel_hi:[1,0]
	v_pk_mul_f32 v[8:9], v[8:9], v[190:191] op_sel_hi:[1,0]
	v_pk_mul_f32 v[6:7], v[6:7], v[190:191] op_sel_hi:[1,0]
	v_pk_mul_f32 v[4:5], v[4:5], v[190:191] op_sel_hi:[1,0]
	v_pk_mul_f32 v[2:3], v[2:3], v[190:191] op_sel_hi:[1,0]
	v_pk_mul_f32 v[0:1], v[0:1], v[190:191] op_sel_hi:[1,0]
	v_mul_f32_e32 v203, v203, v190
	v_mov_b32_e32 v190, v246
	v_sub_f32_e32 v128, v128, v190
	v_exp_f32_e32 v128, v128
	v_sub_f32_e32 v129, v129, v190
	v_exp_f32_e32 v129, v129
	v_sub_f32_e32 v130, v130, v190
	v_add_f32_e32 v254, 0, v128
	v_exp_f32_e32 v130, v130
	v_sub_f32_e32 v131, v131, v190
	v_add_f32_e32 v254, v129, v254
	v_exp_f32_e32 v131, v131
	v_sub_f32_e32 v132, v132, v190
	v_add_f32_e32 v254, v130, v254
	v_exp_f32_e32 v132, v132
	v_sub_f32_e32 v133, v133, v190
	v_add_f32_e32 v254, v131, v254
	v_exp_f32_e32 v133, v133
	v_sub_f32_e32 v134, v134, v190
	v_add_f32_e32 v254, v132, v254
	v_exp_f32_e32 v134, v134
	v_sub_f32_e32 v135, v135, v190
	v_add_f32_e32 v254, v133, v254
	v_exp_f32_e32 v135, v135
	v_sub_f32_e32 v136, v136, v190
	v_add_f32_e32 v254, v134, v254
	v_exp_f32_e32 v136, v136
	v_sub_f32_e32 v137, v137, v190
	v_add_f32_e32 v254, v135, v254
	v_exp_f32_e32 v137, v137
	v_sub_f32_e32 v138, v138, v190
	v_add_f32_e32 v254, v136, v254
	v_exp_f32_e32 v138, v138
	v_sub_f32_e32 v139, v139, v190
	v_add_f32_e32 v254, v137, v254
	v_exp_f32_e32 v139, v139
	v_sub_f32_e32 v140, v140, v190
	v_add_f32_e32 v254, v138, v254
	v_exp_f32_e32 v140, v140
	v_sub_f32_e32 v141, v141, v190
	v_add_f32_e32 v254, v139, v254
	v_exp_f32_e32 v141, v141
	v_sub_f32_e32 v142, v142, v190
	v_add_f32_e32 v254, v140, v254
	v_exp_f32_e32 v142, v142
	v_sub_f32_e32 v143, v143, v190
	v_add_f32_e32 v254, v141, v254
	v_exp_f32_e32 v143, v143
	v_add_f32_e32 v254, v142, v254
	v_add_f32_e32 v254, v143, v254
	v_cvt_pk_bf16_f32 v242, v128, v129
	v_cvt_pk_bf16_f32 v243, v130, v131
	v_cvt_pk_bf16_f32 v244, v132, v133
	v_cvt_pk_bf16_f32 v245, v134, v135
	v_cvt_pk_bf16_f32 v250, v136, v137
	v_cvt_pk_bf16_f32 v251, v138, v139
	v_cvt_pk_bf16_f32 v252, v140, v141
	v_cvt_pk_bf16_f32 v253, v142, v143
	v_add_f32_e32 v203, v203, v254
	s_nop 1
	s_branch .Latt_pv1_2
.Latt_slow_2:
	s_lshl_b32 s14, s38, 14
	s_add_i32 s15, s14, 0
	v_add_u32_e32 v207, s15, v195
	ds_read_b128 v[128:131], v207
	v_add_u32_e32 v208, s15, v196
	ds_read_b128 v[210:213], v208
	v_add_u32_e32 v209, s15, v197
	v_lshrrev_b32_e32 v205, 3, v204
	s_add_i32 s39, s84, 31
	v_and_or_b32 v206, v204, 31, s80
	s_cmp_le_i32 s39, s80
	s_waitcnt lgkmcnt(1)
	v_mfma_f32_32x32x16_bf16 v[128:143], v[128:131], v[144:147], 0
	s_waitcnt lgkmcnt(0)
	v_mfma_f32_32x32x16_bf16 v[128:143], v[210:213], v[148:151], v[128:143]
	ds_read_b128 v[212:215], v209
	v_add_u32_e32 v210, s15, v198
	ds_read_b128 v[216:219], v210
	v_add_u32_e32 v211, s15, v199
	s_waitcnt lgkmcnt(1)
	v_mfma_f32_32x32x16_bf16 v[128:143], v[212:215], v[152:155], v[128:143]
	v_add_u32_e32 v213, s15, v200
	v_and_b32_e32 v212, 4, v205
	ds_read_b128 v[222:225], v213
	s_waitcnt lgkmcnt(1)
	v_mfma_f32_32x32x16_bf16 v[128:143], v[216:219], v[156:159], v[128:143]
	ds_read_b128 v[214:217], v211
	s_waitcnt lgkmcnt(0)
	v_mfma_f32_32x32x16_bf16 v[128:143], v[214:217], v[160:163], v[128:143]
	v_add_u32_e32 v214, s15, v201
	ds_read_b128 v[216:219], v214
	v_add_u32_e32 v215, s15, v202
	v_mfma_f32_32x32x16_bf16 v[128:143], v[222:225], v[164:167], v[128:143]
	ds_read_b128 v[222:225], v215
	s_waitcnt lgkmcnt(1)
	v_mfma_f32_32x32x16_bf16 v[128:143], v[216:219], v[168:171], v[128:143]
	s_waitcnt lgkmcnt(0)
	v_mfma_f32_32x32x16_bf16 v[128:143], v[222:225], v[172:175], v[128:143]
	s_cbranch_scc1 .LBB0_888
	v_add_u32_e32 v205, s84, v212
	v_cmp_lt_i32_e32 vcc, v205, v206
	v_add_u32_e32 v216, 2, v205
	s_nop 7
	v_cndmask_b32_e32 v129, v192, v129, vcc
	v_cmp_le_i32_e32 vcc, v205, v206
	s_nop 1
	v_cndmask_b32_e32 v128, v192, v128, vcc
	v_cmp_le_i32_e32 vcc, v216, v206
	v_add_u32_e32 v216, 3, v205
	s_nop 0
	v_cndmask_b32_e32 v130, v192, v130, vcc
	v_cmp_le_i32_e32 vcc, v216, v206
	v_add_u32_e32 v216, 8, v205
	s_nop 0
	v_cndmask_b32_e32 v131, v192, v131, vcc
	v_cmp_le_i32_e32 vcc, v216, v206
	v_add_u32_e32 v216, 9, v205
	s_nop 0
	v_cndmask_b32_e32 v132, v192, v132, vcc
	v_cmp_le_i32_e32 vcc, v216, v206
	v_add_u32_e32 v216, 10, v205
	s_nop 0
	v_cndmask_b32_e32 v133, v192, v133, vcc
	v_cmp_le_i32_e32 vcc, v216, v206
	v_add_u32_e32 v216, 11, v205
	s_nop 0
	v_cndmask_b32_e32 v134, v192, v134, vcc
	v_cmp_le_i32_e32 vcc, v216, v206
	v_add_u32_e32 v216, 16, v205
	s_nop 0
	v_cndmask_b32_e32 v135, v192, v135, vcc
	v_cmp_le_i32_e32 vcc, v216, v206
	v_add_u32_e32 v216, 17, v205
	s_nop 0
	v_cndmask_b32_e32 v136, v192, v136, vcc
	v_cmp_le_i32_e32 vcc, v216, v206
	v_add_u32_e32 v216, 18, v205
	s_nop 0
	v_cndmask_b32_e32 v137, v192, v137, vcc
	v_cmp_le_i32_e32 vcc, v216, v206
	v_add_u32_e32 v216, 19, v205
	s_nop 0
	v_cndmask_b32_e32 v138, v192, v138, vcc
	v_cmp_le_i32_e32 vcc, v216, v206
	v_add_u32_e32 v216, 24, v205
	s_nop 0
	v_cndmask_b32_e32 v139, v192, v139, vcc
	v_cmp_le_i32_e32 vcc, v216, v206
	v_add_u32_e32 v216, 25, v205
	s_nop 0
	v_cndmask_b32_e32 v140, v192, v140, vcc
	v_cmp_le_i32_e32 vcc, v216, v206
	v_add_u32_e32 v216, 26, v205
	v_add_u32_e32 v205, 27, v205
	v_cndmask_b32_e32 v141, v192, v141, vcc
	v_cmp_le_i32_e32 vcc, v216, v206
	s_nop 1
	v_cndmask_b32_e32 v142, v192, v142, vcc
	v_cmp_le_i32_e32 vcc, v205, v206
	s_nop 1
	v_cndmask_b32_e32 v143, v192, v143, vcc

.LBB0_902:
	s_cmp_ge_u32 s10, s78
	s_cselect_b64 s[8:9], -1, 0
	v_mov_b32_e32 v204, v176
	s_and_b64 vcc, exec, s[8:9]
	s_cbranch_vccnz .LBB0_904
	s_add_i32 s100, s14, 63
	s_cmp_le_i32 s100, s80
	s_cbranch_scc1 .LBB0_904
	v_sub_co_u32_e64 v128, s[16:17], s11, 1
	s_nop 1
	v_cndmask_b32_e64 v130, v128, 2, s[16:17]
	v_lshlrev_b32_e32 v128, 14, v130
	v_add_u32_e32 v131, s40, v128
	v_lshl_add_u64 v[128:129], s[34:35], 0, v[178:179]
	s_add_u32 s16, s34, 0xf00
	v_readfirstlane_b32 s15, v131
	s_mov_b32 s22, m0
	s_mov_b32 m0, s15
	s_nop 0
	global_load_lds_dwordx4 v[128:129], off
	s_mov_b32 m0, s22
	v_lshl_add_u64 v[128:129], s[34:35], 0, v[180:181]
	s_addc_u32 s17, s35, 0
	s_addk_i32 s15, 0x400
	s_mov_b32 s22, m0
	s_mov_b32 m0, s15
	s_nop 0
	global_load_lds_dwordx4 v[128:129], off
	s_mov_b32 m0, s22
	v_lshlrev_b32_e32 v128, 15, v130
	v_add_u32_e32 v130, s41, v128
	v_lshl_add_u64 v[128:129], s[16:17], 0, v[182:183]
	v_readfirstlane_b32 s15, v130
	s_mov_b32 s22, m0
	s_mov_b32 m0, s15
	s_nop 0
	global_load_lds_dwordx4 v[128:129], off
	s_mov_b32 m0, s22
	v_lshl_add_u64 v[128:129], s[16:17], 0, v[184:185]
	s_add_i32 s22, s15, 0x400
	s_mov_b32 s23, m0
	s_mov_b32 m0, s22
	s_nop 0
	global_load_lds_dwordx4 v[128:129], off
	s_mov_b32 m0, s23
	v_lshl_add_u64 v[128:129], s[16:17], 0, v[186:187]
	s_add_i32 s22, s15, 0x800
	s_mov_b32 s23, m0
	s_mov_b32 m0, s22
	s_nop 0
	global_load_lds_dwordx4 v[128:129], off
	s_mov_b32 m0, s23
	v_lshl_add_u64 v[128:129], s[16:17], 0, v[188:189]
	s_addk_i32 s15, 0xc00
	s_mov_b32 s16, m0
	s_mov_b32 m0, s15
	s_nop 0
	global_load_lds_dwordx4 v[128:129], off
	s_mov_b32 m0, s16
.LBB0_904:
	s_cmp_gt_i32 s14, s81
	s_cbranch_scc1 .LBB0_915
	s_add_i32 s100, s14, 63
	s_cmp_le_i32 s100, s80
	s_cbranch_scc0 .Latt_slow_3
	s_lshl_b32 s98, s11, 14
	s_lshl_b32 s99, s11, 15
	s_add_i32 s99, s99, 0xc000
	v_add_u32_e32 v206, s98, v196
	ds_read_b128 v[206:209], v206
	v_add_u32_e32 v210, s98, v197
	ds_read_b128 v[210:213], v210
	v_add_u32_e32 v214, s98, v198
	ds_read_b128 v[214:217], v214
	v_add_u32_e32 v222, s98, v199
	ds_read_b128 v[222:225], v222
	v_add_u32_e32 v226, s98, v200
	ds_read_b128 v[226:229], v226
	v_add_u32_e32 v230, s98, v201
	ds_read_b128 v[230:233], v230
	v_add_u32_e32 v234, s98, v202
	ds_read_b128 v[234:237], v234
	v_add_u32_e32 v238, s98, v203
	ds_read_b128 v[238:241], v238
	v_bfe_u32 v246, v204, 2, 2
	v_bfe_u32 v247, v204, 5, 1
	v_lshl_or_b32 v247, v247, 2, v246
	v_and_b32_e32 v249, 3, v204
	v_and_b32_e32 v254, 16, v204
	v_lshl_or_b32 v249, v249, 2, v254
	v_lshlrev_b32_e32 v249, 1, v249
	v_lshl_add_u32 v247, v247, 9, v249
	v_add_u32_e32 v247, s99, v247
	v_lshlrev_b32_e32 v246, 6, v246
	v_add_u32_e32 v205, v247, v246
	v_xor_b32_e32 v249, 64, v246
	v_add_u32_e32 v218, v247, v249
	v_xor_b32_e32 v249, 0x80, v246
	v_add_u32_e32 v219, v247, v249
	v_xor_b32_e32 v249, 0xc0, v246
	v_add_u32_e32 v221, v247, v249
	s_waitcnt lgkmcnt(7)
	v_mfma_f32_32x32x16_bf16 v[128:143], v[206:209], v[144:147], 0
	v_add_u32_e32 v206, s98, v196
	ds_read_b128 v[206:209], v206 offset:8192
	s_waitcnt lgkmcnt(7)
	v_mfma_f32_32x32x16_bf16 v[128:143], v[210:213], v[148:151], v[128:143]
	v_add_u32_e32 v210, s98, v197
	ds_read_b128 v[210:213], v210 offset:8192
	s_waitcnt lgkmcnt(7)
	v_mfma_f32_32x32x16_bf16 v[128:143], v[214:217], v[152:155], v[128:143]
	v_add_u32_e32 v214, s98, v198
	ds_read_b128 v[214:217], v214 offset:8192
	s_waitcnt lgkmcnt(7)
	v_mfma_f32_32x32x16_bf16 v[128:143], v[222:225], v[156:159], v[128:143]
	v_add_u32_e32 v222, s98, v199
	ds_read_b128 v[222:225], v222 offset:8192
	s_waitcnt lgkmcnt(7)
	v_mfma_f32_32x32x16_bf16 v[128:143], v[226:229], v[160:163], v[128:143]
	v_add_u32_e32 v226, s98, v200
	ds_read_b128 v[226:229], v226 offset:8192
	s_waitcnt lgkmcnt(7)
	v_mfma_f32_32x32x16_bf16 v[128:143], v[230:233], v[164:167], v[128:143]
	v_add_u32_e32 v230, s98, v201
	ds_read_b128 v[230:233], v230 offset:8192
	s_waitcnt lgkmcnt(7)
	v_mfma_f32_32x32x16_bf16 v[128:143], v[234:237], v[168:171], v[128:143]
	v_add_u32_e32 v234, s98, v202
	ds_read_b128 v[234:237], v234 offset:8192
	s_waitcnt lgkmcnt(7)
	v_mfma_f32_32x32x16_bf16 v[128:143], v[238:241], v[172:175], v[128:143]
	v_add_u32_e32 v238, s98, v203
	ds_read_b128 v[238:241], v238 offset:8192
	s_nop 9
	v_max3_f32 v246, v128, v129, v130
	v_max3_f32 v247, v131, v132, v133
	v_max3_f32 v246, v246, v134, v135
	v_max3_f32 v247, v247, v136, v137
	v_max3_f32 v246, v246, v138, v139
	v_max3_f32 v247, v247, v140, v141
	v_max3_f32 v246, v246, v142, v143
	v_max_f32_e32 v246, v246, v247
	v_mov_b32_e32 v247, v246
	v_add_f32_e32 v249, 0x41000000, v190
	s_nop 1
	v_permlane32_swap_b32_e32 v246, v247
	v_max_f32_e32 v246, v246, v247
	v_cmp_gt_f32_e32 vcc, v246, v249
	s_cbranch_vccz .Latt_nr0_3
	v_max_f32_e32 v246, v190, v246
	v_sub_f32_e32 v190, v190, v246
	v_exp_f32_e32 v190, v190
	s_nop 0
	v_pk_mul_f32 v[126:127], v[126:127], v[190:191] op_sel_hi:[1,0]
	v_pk_mul_f32 v[124:125], v[124:125], v[190:191] op_sel_hi:[1,0]
	v_pk_mul_f32 v[122:123], v[122:123], v[190:191] op_sel_hi:[1,0]
	v_pk_mul_f32 v[120:121], v[120:121], v[190:191] op_sel_hi:[1,0]
	v_pk_mul_f32 v[118:119], v[118:119], v[190:191] op_sel_hi:[1,0]
	v_pk_mul_f32 v[116:117], v[116:117], v[190:191] op_sel_hi:[1,0]
	v_pk_mul_f32 v[114:115], v[114:115], v[190:191] op_sel_hi:[1,0]
	v_pk_mul_f32 v[112:113], v[112:113], v[190:191] op_sel_hi:[1,0]
	v_pk_mul_f32 v[110:111], v[110:111], v[190:191] op_sel_hi:[1,0]
	v_pk_mul_f32 v[108:109], v[108:109], v[190:191] op_sel_hi:[1,0]
	v_pk_mul_f32 v[106:107], v[106:107], v[190:191] op_sel_hi:[1,0]
	v_pk_mul_f32 v[104:105], v[104:105], v[190:191] op_sel_hi:[1,0]
	v_pk_mul_f32 v[102:103], v[102:103], v[190:191] op_sel_hi:[1,0]
	v_pk_mul_f32 v[100:101], v[100:101], v[190:191] op_sel_hi:[1,0]
	v_pk_mul_f32 v[98:99], v[98:99], v[190:191] op_sel_hi:[1,0]
	v_pk_mul_f32 v[96:97], v[96:97], v[190:191] op_sel_hi:[1,0]
	v_pk_mul_f32 v[94:95], v[94:95], v[190:191] op_sel_hi:[1,0]
	v_pk_mul_f32 v[92:93], v[92:93], v[190:191] op_sel_hi:[1,0]
	v_pk_mul_f32 v[90:91], v[90:91], v[190:191] op_sel_hi:[1,0]
	v_pk_mul_f32 v[88:89], v[88:89], v[190:191] op_sel_hi:[1,0]
	v_pk_mul_f32 v[86:87], v[86:87], v[190:191] op_sel_hi:[1,0]
	v_pk_mul_f32 v[84:85], v[84:85], v[190:191] op_sel_hi:[1,0]
	v_pk_mul_f32 v[82:83], v[82:83], v[190:191] op_sel_hi:[1,0]
	v_pk_mul_f32 v[80:81], v[80:81], v[190:191] op_sel_hi:[1,0]
	v_pk_mul_f32 v[78:79], v[78:79], v[190:191] op_sel_hi:[1,0]
	v_pk_mul_f32 v[76:77], v[76:77], v[190:191] op_sel_hi:[1,0]
	v_pk_mul_f32 v[74:75], v[74:75], v[190:191] op_sel_hi:[1,0]
	v_pk_mul_f32 v[72:73], v[72:73], v[190:191] op_sel_hi:[1,0]
	v_pk_mul_f32 v[70:71], v[70:71], v[190:191] op_sel_hi:[1,0]
	v_pk_mul_f32 v[68:69], v[68:69], v[190:191] op_sel_hi:[1,0]
	v_pk_mul_f32 v[66:67], v[66:67], v[190:191] op_sel_hi:[1,0]
	v_pk_mul_f32 v[64:65], v[64:65], v[190:191] op_sel_hi:[1,0]
	v_pk_mul_f32 v[62:63], v[62:63], v[190:191] op_sel_hi:[1,0]
	v_pk_mul_f32 v[60:61], v[60:61], v[190:191] op_sel_hi:[1,0]
	v_pk_mul_f32 v[58:59], v[58:59], v[190:191] op_sel_hi:[1,0]
	v_pk_mul_f32 v[56:57], v[56:57], v[190:191] op_sel_hi:[1,0]
	v_pk_mul_f32 v[54:55], v[54:55], v[190:191] op_sel_hi:[1,0]
	v_pk_mul_f32 v[52:53], v[52:53], v[190:191] op_sel_hi:[1,0]
	v_pk_mul_f32 v[50:51], v[50:51], v[190:191] op_sel_hi:[1,0]
	v_pk_mul_f32 v[48:49], v[48:49], v[190:191] op_sel_hi:[1,0]
	v_pk_mul_f32 v[46:47], v[46:47], v[190:191] op_sel_hi:[1,0]
	v_pk_mul_f32 v[44:45], v[44:45], v[190:191] op_sel_hi:[1,0]
	v_pk_mul_f32 v[42:43], v[42:43], v[190:191] op_sel_hi:[1,0]
	v_pk_mul_f32 v[40:41], v[40:41], v[190:191] op_sel_hi:[1,0]
	v_pk_mul_f32 v[38:39], v[38:39], v[190:191] op_sel_hi:[1,0]
	v_pk_mul_f32 v[36:37], v[36:37], v[190:191] op_sel_hi:[1,0]
	v_pk_mul_f32 v[34:35], v[34:35], v[190:191] op_sel_hi:[1,0]
	v_pk_mul_f32 v[32:33], v[32:33], v[190:191] op_sel_hi:[1,0]
	v_pk_mul_f32 v[30:31], v[30:31], v[190:191] op_sel_hi:[1,0]
	v_pk_mul_f32 v[28:29], v[28:29], v[190:191] op_sel_hi:[1,0]
	v_pk_mul_f32 v[26:27], v[26:27], v[190:191] op_sel_hi:[1,0]
	v_pk_mul_f32 v[24:25], v[24:25], v[190:191] op_sel_hi:[1,0]
	v_pk_mul_f32 v[22:23], v[22:23], v[190:191] op_sel_hi:[1,0]
	v_pk_mul_f32 v[20:21], v[20:21], v[190:191] op_sel_hi:[1,0]
	v_pk_mul_f32 v[18:19], v[18:19], v[190:191] op_sel_hi:[1,0]
	v_pk_mul_f32 v[16:17], v[16:17], v[190:191] op_sel_hi:[1,0]
	v_pk_mul_f32 v[14:15], v[14:15], v[190:191] op_sel_hi:[1,0]
	v_pk_mul_f32 v[12:13], v[12:13], v[190:191] op_sel_hi:[1,0]
	v_pk_mul_f32 v[10:11], v[10:11], v[190:191] op_sel_hi:[1,0]
	v_pk_mul_f32 v[8:9], v[8:9], v[190:191] op_sel_hi:[1,0]
	v_pk_mul_f32 v[6:7], v[6:7], v[190:191] op_sel_hi:[1,0]
	v_pk_mul_f32 v[4:5], v[4:5], v[190:191] op_sel_hi:[1,0]
	v_pk_mul_f32 v[2:3], v[2:3], v[190:191] op_sel_hi:[1,0]
	v_pk_mul_f32 v[0:1], v[0:1], v[190:191] op_sel_hi:[1,0]
	v_mul_f32_e32 v195, v195, v190
	v_mov_b32_e32 v190, v246

.Latt_pv1_3:
	s_waitcnt lgkmcnt(12)
	v_mfma_f32_32x32x16_bf16 v[112:127], v[206:209], v[242:245], v[112:127]
	ds_read_b64_tr_b16 v[238:239], v221 offset:16640
	ds_read_b64_tr_b16 v[240:241], v221 offset:20736
	s_waitcnt lgkmcnt(12)
	v_mfma_f32_32x32x16_bf16 v[96:111], v[210:213], v[242:245], v[96:111]
	ds_read_b64_tr_b16 v[206:207], v205 offset:24576
	ds_read_b64_tr_b16 v[208:209], v205 offset:28672
	s_cmp_lg_u64 s[8:9], 0
	s_cbranch_scc1 .Latt_nd0_3
	s_sub_i32 s100, s11, 1
	s_cmp_eq_u32 s11, 0
	s_cselect_b32 s100, 2, s100
	s_lshl_b32 s101, s100, 14
	s_add_i32 m0, s40, s101
	s_nop 0
	global_load_lds_dwordx4 v178, s[34:35]
.Latt_nd0_3:
	s_waitcnt lgkmcnt(12)
	v_mfma_f32_32x32x16_bf16 v[80:95], v[214:217], v[242:245], v[80:95]
	ds_read_b64_tr_b16 v[210:211], v218 offset:24576
	ds_read_b64_tr_b16 v[212:213], v218 offset:28672
	s_waitcnt lgkmcnt(12)
	v_mfma_f32_32x32x16_bf16 v[64:79], v[222:225], v[242:245], v[64:79]
	ds_read_b64_tr_b16 v[214:215], v219 offset:24576
	ds_read_b64_tr_b16 v[216:217], v219 offset:28672
	s_cmp_lg_u64 s[8:9], 0
	s_cbranch_scc1 .Latt_nd1_3
	s_add_i32 m0, m0, 0x400
	s_nop 0
	global_load_lds_dwordx4 v180, s[34:35]
.Latt_nd1_3:
	s_waitcnt lgkmcnt(12)
	v_mfma_f32_32x32x16_bf16 v[48:63], v[226:229], v[242:245], v[48:63]
	ds_read_b64_tr_b16 v[222:223], v221 offset:24576
	ds_read_b64_tr_b16 v[224:225], v221 offset:28672
	s_waitcnt lgkmcnt(12)
	v_mfma_f32_32x32x16_bf16 v[32:47], v[230:233], v[242:245], v[32:47]
	ds_read_b64_tr_b16 v[226:227], v205 offset:24832
	ds_read_b64_tr_b16 v[228:229], v205 offset:28928
	s_cmp_lg_u64 s[8:9], 0
	s_cbranch_scc1 .Latt_nd2_3
	s_lshl_b32 s101, s100, 15
	s_add_i32 m0, s41, s101
	s_add_u32 s100, s34, 0xf00
	s_addc_u32 s101, s35, 0
	global_load_lds_dwordx4 v182, s[100:101]
.Latt_nd2_3:
	s_waitcnt lgkmcnt(12)
	v_mfma_f32_32x32x16_bf16 v[16:31], v[234:237], v[242:245], v[16:31]
	ds_read_b64_tr_b16 v[230:231], v218 offset:24832
	ds_read_b64_tr_b16 v[232:233], v218 offset:28928
	s_waitcnt lgkmcnt(12)
	v_mfma_f32_32x32x16_bf16 v[0:15], v[238:241], v[242:245], v[0:15]
	ds_read_b64_tr_b16 v[234:235], v219 offset:24832
	ds_read_b64_tr_b16 v[236:237], v219 offset:28928
	s_cmp_lg_u64 s[8:9], 0
	s_cbranch_scc1 .Latt_nd3_3
	s_add_i32 m0, m0, 0x400
	s_nop 0
	global_load_lds_dwordx4 v184, s[100:101]
.Latt_nd3_3:
	s_waitcnt lgkmcnt(12)
	v_mfma_f32_32x32x16_bf16 v[112:127], v[206:209], v[250:253], v[112:127]
	ds_read_b64_tr_b16 v[238:239], v221 offset:24832
	ds_read_b64_tr_b16 v[240:241], v221 offset:28928
	s_waitcnt lgkmcnt(12)
	v_mfma_f32_32x32x16_bf16 v[96:111], v[210:213], v[250:253], v[96:111]
	s_cmp_lg_u64 s[8:9], 0
	s_cbranch_scc1 .Latt_nd4_3
	s_add_i32 m0, m0, 0x400
	s_nop 0
	global_load_lds_dwordx4 v186, s[100:101]
.Latt_nd4_3:
	s_waitcnt lgkmcnt(10)
	v_mfma_f32_32x32x16_bf16 v[80:95], v[214:217], v[250:253], v[80:95]
	s_waitcnt lgkmcnt(8)
	v_mfma_f32_32x32x16_bf16 v[64:79], v[222:225], v[250:253], v[64:79]
	s_cmp_lg_u64 s[8:9], 0
	s_cbranch_scc1 .Latt_nd5_3
	s_add_i32 m0, m0, 0x400
	s_nop 0
	global_load_lds_dwordx4 v188, s[100:101]

.Latt_slow_3:
	s_lshl_b32 s15, s11, 14
	s_add_i32 s16, s15, 0
	v_add_u32_e32 v207, s16, v196
	ds_read_b128 v[128:131], v207
	v_add_u32_e32 v208, s16, v197
	ds_read_b128 v[210:213], v208
	v_add_u32_e32 v209, s16, v198
	v_lshrrev_b32_e32 v205, 3, v204
	s_add_i32 s17, s14, 31
	v_and_or_b32 v206, v204, 31, s80
	s_cmp_le_i32 s17, s80
	s_waitcnt lgkmcnt(1)
	v_mfma_f32_32x32x16_bf16 v[128:143], v[128:131], v[144:147], 0
	s_waitcnt lgkmcnt(0)
	v_mfma_f32_32x32x16_bf16 v[128:143], v[210:213], v[148:151], v[128:143]
	ds_read_b128 v[212:215], v209
	v_add_u32_e32 v210, s16, v199
	ds_read_b128 v[216:219], v210
	v_add_u32_e32 v211, s16, v200
	s_waitcnt lgkmcnt(1)
	v_mfma_f32_32x32x16_bf16 v[128:143], v[212:215], v[152:155], v[128:143]
	v_add_u32_e32 v213, s16, v201
	v_and_b32_e32 v212, 4, v205
	ds_read_b128 v[222:225], v213
	s_waitcnt lgkmcnt(1)
	v_mfma_f32_32x32x16_bf16 v[128:143], v[216:219], v[156:159], v[128:143]
	ds_read_b128 v[214:217], v211
	s_waitcnt lgkmcnt(0)
	v_mfma_f32_32x32x16_bf16 v[128:143], v[214:217], v[160:163], v[128:143]
	v_add_u32_e32 v214, s16, v202
	ds_read_b128 v[216:219], v214
	v_add_u32_e32 v215, s16, v203
	v_mfma_f32_32x32x16_bf16 v[128:143], v[222:225], v[164:167], v[128:143]
	ds_read_b128 v[222:225], v215
	s_waitcnt lgkmcnt(1)
	v_mfma_f32_32x32x16_bf16 v[128:143], v[216:219], v[168:171], v[128:143]
	s_waitcnt lgkmcnt(0)
	v_mfma_f32_32x32x16_bf16 v[128:143], v[222:225], v[172:175], v[128:143]
	s_cbranch_scc1 .LBB0_907
	v_add_u32_e32 v205, s14, v212
	v_cmp_lt_i32_e32 vcc, v205, v206
	v_add_u32_e32 v216, 2, v205
	s_nop 7
	v_cndmask_b32_e32 v129, v192, v129, vcc
	v_cmp_le_i32_e32 vcc, v205, v206
	s_nop 1
	v_cndmask_b32_e32 v128, v192, v128, vcc
	v_cmp_le_i32_e32 vcc, v216, v206
	v_add_u32_e32 v216, 3, v205
	s_nop 0
	v_cndmask_b32_e32 v130, v192, v130, vcc
	v_cmp_le_i32_e32 vcc, v216, v206
	v_add_u32_e32 v216, 8, v205
	s_nop 0
	v_cndmask_b32_e32 v131, v192, v131, vcc
	v_cmp_le_i32_e32 vcc, v216, v206
	v_add_u32_e32 v216, 9, v205
	s_nop 0
	v_cndmask_b32_e32 v132, v192, v132, vcc
	v_cmp_le_i32_e32 vcc, v216, v206
	v_add_u32_e32 v216, 10, v205
	s_nop 0
	v_cndmask_b32_e32 v133, v192, v133, vcc
	v_cmp_le_i32_e32 vcc, v216, v206
	v_add_u32_e32 v216, 11, v205
	s_nop 0
	v_cndmask_b32_e32 v134, v192, v134, vcc
	v_cmp_le_i32_e32 vcc, v216, v206
	v_add_u32_e32 v216, 16, v205
	s_nop 0
	v_cndmask_b32_e32 v135, v192, v135, vcc
	v_cmp_le_i32_e32 vcc, v216, v206
	v_add_u32_e32 v216, 17, v205
	s_nop 0
	v_cndmask_b32_e32 v136, v192, v136, vcc
	v_cmp_le_i32_e32 vcc, v216, v206
	v_add_u32_e32 v216, 18, v205
	s_nop 0
	v_cndmask_b32_e32 v137, v192, v137, vcc
	v_cmp_le_i32_e32 vcc, v216, v206
	v_add_u32_e32 v216, 19, v205
	s_nop 0
	v_cndmask_b32_e32 v138, v192, v138, vcc
	v_cmp_le_i32_e32 vcc, v216, v206
	v_add_u32_e32 v216, 24, v205
	s_nop 0
	v_cndmask_b32_e32 v139, v192, v139, vcc
	v_cmp_le_i32_e32 vcc, v216, v206
	v_add_u32_e32 v216, 25, v205
	s_nop 0
	v_cndmask_b32_e32 v140, v192, v140, vcc
	v_cmp_le_i32_e32 vcc, v216, v206
	v_add_u32_e32 v216, 26, v205
	v_add_u32_e32 v205, 27, v205
	v_cndmask_b32_e32 v141, v192, v141, vcc
	v_cmp_le_i32_e32 vcc, v216, v206
	s_nop 1
	v_cndmask_b32_e32 v142, v192, v142, vcc
	v_cmp_le_i32_e32 vcc, v205, v206
	s_nop 1
	v_cndmask_b32_e32 v143, v192, v143, vcc

.LBB0_1799:
	s_cmp_ge_u32 s38, s70
	s_cselect_b64 s[18:19], -1, 0
	v_mov_b32_e32 v203, v176
	s_and_b64 vcc, exec, s[18:19]
	s_cbranch_vccnz .LBB0_1801
	s_add_i32 s100, s39, 63
	s_cmp_le_i32 s100, s71
	s_cbranch_scc1 .LBB0_1801
	v_sub_co_u32_e64 v128, s[22:23], s76, 1
	s_nop 1
	v_cndmask_b32_e64 v130, v128, 2, s[22:23]
	v_lshlrev_b32_e32 v128, 14, v130
	v_add_u32_e32 v131, s73, v128
	v_lshl_add_u64 v[128:129], s[14:15], 0, v[178:179]
	s_add_u32 s22, s14, 0x1000
	v_readfirstlane_b32 s77, v131
	s_mov_b32 s78, m0
	s_mov_b32 m0, s77
	s_nop 0
	global_load_lds_dwordx4 v[128:129], off
	s_mov_b32 m0, s78
	v_lshl_add_u64 v[128:129], s[14:15], 0, v[180:181]
	s_addc_u32 s23, s15, 0
	s_addk_i32 s77, 0x400
	s_mov_b32 s78, m0
	s_mov_b32 m0, s77
	s_nop 0
	global_load_lds_dwordx4 v[128:129], off
	s_mov_b32 m0, s78
	v_lshlrev_b32_e32 v128, 15, v130
	v_add_u32_e32 v130, s74, v128
	v_lshl_add_u64 v[128:129], s[22:23], 0, v[182:183]
	v_readfirstlane_b32 s77, v130
	s_mov_b32 s78, m0
	s_mov_b32 m0, s77
	s_nop 0
	global_load_lds_dwordx4 v[128:129], off
	s_mov_b32 m0, s78
	v_lshl_add_u64 v[128:129], s[22:23], 0, v[184:185]
	s_add_i32 s78, s77, 0x400
	s_mov_b32 s79, m0
	s_mov_b32 m0, s78
	s_nop 0
	global_load_lds_dwordx4 v[128:129], off
	s_mov_b32 m0, s79
	v_lshl_add_u64 v[128:129], s[22:23], 0, v[186:187]
	s_add_i32 s78, s77, 0x800
	s_mov_b32 s79, m0
	s_mov_b32 m0, s78
	s_nop 0
	global_load_lds_dwordx4 v[128:129], off
	s_mov_b32 m0, s79
	v_lshl_add_u64 v[128:129], s[22:23], 0, v[188:189]
	s_add_i32 s22, s77, 0xc00
	s_mov_b32 s23, m0
	s_mov_b32 m0, s22
	s_nop 0
	global_load_lds_dwordx4 v[128:129], off
	s_mov_b32 m0, s23
.LBB0_1801:
	s_cmp_gt_i32 s39, s72
	s_cbranch_scc1 .LBB0_1812
	s_add_i32 s100, s39, 63
	s_cmp_le_i32 s100, s71
	s_cbranch_scc0 .Latt_slow_4
	s_lshl_b32 s98, s76, 14
	s_lshl_b32 s99, s76, 15
	s_add_i32 s99, s99, 0xc000
	v_add_u32_e32 v206, s98, v194
	ds_read_b128 v[206:209], v206
	v_add_u32_e32 v210, s98, v195
	ds_read_b128 v[210:213], v210
	v_add_u32_e32 v214, s98, v196
	ds_read_b128 v[214:217], v214
	v_add_u32_e32 v222, s98, v197
	ds_read_b128 v[222:225], v222
	v_add_u32_e32 v226, s98, v198
	ds_read_b128 v[226:229], v226
	v_add_u32_e32 v230, s98, v199
	ds_read_b128 v[230:233], v230
	v_add_u32_e32 v234, s98, v200
	ds_read_b128 v[234:237], v234
	v_add_u32_e32 v238, s98, v201
	ds_read_b128 v[238:241], v238
	v_bfe_u32 v246, v203, 2, 2
	v_bfe_u32 v247, v203, 5, 1
	v_lshl_or_b32 v247, v247, 2, v246
	v_and_b32_e32 v249, 3, v203
	v_and_b32_e32 v254, 16, v203
	v_lshl_or_b32 v249, v249, 2, v254
	v_lshlrev_b32_e32 v249, 1, v249
	v_lshl_add_u32 v247, v247, 9, v249
	v_add_u32_e32 v247, s99, v247
	v_lshlrev_b32_e32 v246, 6, v246
	v_add_u32_e32 v205, v247, v246
	v_xor_b32_e32 v249, 64, v246
	v_add_u32_e32 v218, v247, v249
	v_xor_b32_e32 v249, 0x80, v246
	v_add_u32_e32 v219, v247, v249
	v_xor_b32_e32 v249, 0xc0, v246
	v_add_u32_e32 v221, v247, v249
	s_waitcnt lgkmcnt(7)
	v_mfma_f32_32x32x16_bf16 v[128:143], v[206:209], v[144:147], 0
	v_add_u32_e32 v206, s98, v194
	ds_read_b128 v[206:209], v206 offset:8192
	s_waitcnt lgkmcnt(7)
	v_mfma_f32_32x32x16_bf16 v[128:143], v[210:213], v[148:151], v[128:143]
	v_add_u32_e32 v210, s98, v195
	ds_read_b128 v[210:213], v210 offset:8192
	s_waitcnt lgkmcnt(7)
	v_mfma_f32_32x32x16_bf16 v[128:143], v[214:217], v[152:155], v[128:143]
	v_add_u32_e32 v214, s98, v196
	ds_read_b128 v[214:217], v214 offset:8192
	s_waitcnt lgkmcnt(7)
	v_mfma_f32_32x32x16_bf16 v[128:143], v[222:225], v[156:159], v[128:143]
	v_add_u32_e32 v222, s98, v197
	ds_read_b128 v[222:225], v222 offset:8192
	s_waitcnt lgkmcnt(7)
	v_mfma_f32_32x32x16_bf16 v[128:143], v[226:229], v[160:163], v[128:143]
	v_add_u32_e32 v226, s98, v198
	ds_read_b128 v[226:229], v226 offset:8192
	s_waitcnt lgkmcnt(7)
	v_mfma_f32_32x32x16_bf16 v[128:143], v[230:233], v[164:167], v[128:143]
	v_add_u32_e32 v230, s98, v199
	ds_read_b128 v[230:233], v230 offset:8192
	s_waitcnt lgkmcnt(7)
	v_mfma_f32_32x32x16_bf16 v[128:143], v[234:237], v[168:171], v[128:143]
	v_add_u32_e32 v234, s98, v200
	ds_read_b128 v[234:237], v234 offset:8192
	s_waitcnt lgkmcnt(7)
	v_mfma_f32_32x32x16_bf16 v[128:143], v[238:241], v[172:175], v[128:143]
	v_add_u32_e32 v238, s98, v201
	ds_read_b128 v[238:241], v238 offset:8192
	s_nop 9
	v_max3_f32 v246, v128, v129, v130
	v_max3_f32 v247, v131, v132, v133
	v_max3_f32 v246, v246, v134, v135
	v_max3_f32 v247, v247, v136, v137
	v_max3_f32 v246, v246, v138, v139
	v_max3_f32 v247, v247, v140, v141
	v_max3_f32 v246, v246, v142, v143
	v_max_f32_e32 v246, v246, v247
	v_mov_b32_e32 v247, v246
	v_add_f32_e32 v249, 0x41000000, v190
	s_nop 1
	v_permlane32_swap_b32_e32 v246, v247
	v_max_f32_e32 v246, v246, v247
	v_cmp_gt_f32_e32 vcc, v246, v249
	s_cbranch_vccz .Latt_nr0_4
	v_max_f32_e32 v246, v190, v246
	v_sub_f32_e32 v190, v190, v246
	v_exp_f32_e32 v190, v190
	s_nop 0
	v_pk_mul_f32 v[126:127], v[126:127], v[190:191] op_sel_hi:[1,0]
	v_pk_mul_f32 v[124:125], v[124:125], v[190:191] op_sel_hi:[1,0]
	v_pk_mul_f32 v[122:123], v[122:123], v[190:191] op_sel_hi:[1,0]
	v_pk_mul_f32 v[120:121], v[120:121], v[190:191] op_sel_hi:[1,0]
	v_pk_mul_f32 v[118:119], v[118:119], v[190:191] op_sel_hi:[1,0]
	v_pk_mul_f32 v[116:117], v[116:117], v[190:191] op_sel_hi:[1,0]
	v_pk_mul_f32 v[114:115], v[114:115], v[190:191] op_sel_hi:[1,0]
	v_pk_mul_f32 v[112:113], v[112:113], v[190:191] op_sel_hi:[1,0]
	v_pk_mul_f32 v[110:111], v[110:111], v[190:191] op_sel_hi:[1,0]
	v_pk_mul_f32 v[108:109], v[108:109], v[190:191] op_sel_hi:[1,0]
	v_pk_mul_f32 v[106:107], v[106:107], v[190:191] op_sel_hi:[1,0]
	v_pk_mul_f32 v[104:105], v[104:105], v[190:191] op_sel_hi:[1,0]
	v_pk_mul_f32 v[102:103], v[102:103], v[190:191] op_sel_hi:[1,0]
	v_pk_mul_f32 v[100:101], v[100:101], v[190:191] op_sel_hi:[1,0]
	v_pk_mul_f32 v[98:99], v[98:99], v[190:191] op_sel_hi:[1,0]
	v_pk_mul_f32 v[96:97], v[96:97], v[190:191] op_sel_hi:[1,0]
	v_pk_mul_f32 v[94:95], v[94:95], v[190:191] op_sel_hi:[1,0]
	v_pk_mul_f32 v[92:93], v[92:93], v[190:191] op_sel_hi:[1,0]
	v_pk_mul_f32 v[90:91], v[90:91], v[190:191] op_sel_hi:[1,0]
	v_pk_mul_f32 v[88:89], v[88:89], v[190:191] op_sel_hi:[1,0]
	v_pk_mul_f32 v[86:87], v[86:87], v[190:191] op_sel_hi:[1,0]
	v_pk_mul_f32 v[84:85], v[84:85], v[190:191] op_sel_hi:[1,0]
	v_pk_mul_f32 v[82:83], v[82:83], v[190:191] op_sel_hi:[1,0]
	v_pk_mul_f32 v[80:81], v[80:81], v[190:191] op_sel_hi:[1,0]
	v_pk_mul_f32 v[78:79], v[78:79], v[190:191] op_sel_hi:[1,0]
	v_pk_mul_f32 v[76:77], v[76:77], v[190:191] op_sel_hi:[1,0]
	v_pk_mul_f32 v[74:75], v[74:75], v[190:191] op_sel_hi:[1,0]
	v_pk_mul_f32 v[72:73], v[72:73], v[190:191] op_sel_hi:[1,0]
	v_pk_mul_f32 v[70:71], v[70:71], v[190:191] op_sel_hi:[1,0]
	v_pk_mul_f32 v[68:69], v[68:69], v[190:191] op_sel_hi:[1,0]
	v_pk_mul_f32 v[66:67], v[66:67], v[190:191] op_sel_hi:[1,0]
	v_pk_mul_f32 v[64:65], v[64:65], v[190:191] op_sel_hi:[1,0]
	v_pk_mul_f32 v[62:63], v[62:63], v[190:191] op_sel_hi:[1,0]
	v_pk_mul_f32 v[60:61], v[60:61], v[190:191] op_sel_hi:[1,0]
	v_pk_mul_f32 v[58:59], v[58:59], v[190:191] op_sel_hi:[1,0]
	v_pk_mul_f32 v[56:57], v[56:57], v[190:191] op_sel_hi:[1,0]
	v_pk_mul_f32 v[54:55], v[54:55], v[190:191] op_sel_hi:[1,0]
	v_pk_mul_f32 v[52:53], v[52:53], v[190:191] op_sel_hi:[1,0]
	v_pk_mul_f32 v[50:51], v[50:51], v[190:191] op_sel_hi:[1,0]
	v_pk_mul_f32 v[48:49], v[48:49], v[190:191] op_sel_hi:[1,0]
	v_pk_mul_f32 v[46:47], v[46:47], v[190:191] op_sel_hi:[1,0]
	v_pk_mul_f32 v[44:45], v[44:45], v[190:191] op_sel_hi:[1,0]
	v_pk_mul_f32 v[42:43], v[42:43], v[190:191] op_sel_hi:[1,0]
	v_pk_mul_f32 v[40:41], v[40:41], v[190:191] op_sel_hi:[1,0]
	v_pk_mul_f32 v[38:39], v[38:39], v[190:191] op_sel_hi:[1,0]
	v_pk_mul_f32 v[36:37], v[36:37], v[190:191] op_sel_hi:[1,0]
	v_pk_mul_f32 v[34:35], v[34:35], v[190:191] op_sel_hi:[1,0]
	v_pk_mul_f32 v[32:33], v[32:33], v[190:191] op_sel_hi:[1,0]
	v_pk_mul_f32 v[30:31], v[30:31], v[190:191] op_sel_hi:[1,0]
	v_pk_mul_f32 v[28:29], v[28:29], v[190:191] op_sel_hi:[1,0]
	v_pk_mul_f32 v[26:27], v[26:27], v[190:191] op_sel_hi:[1,0]
	v_pk_mul_f32 v[24:25], v[24:25], v[190:191] op_sel_hi:[1,0]
	v_pk_mul_f32 v[22:23], v[22:23], v[190:191] op_sel_hi:[1,0]
	v_pk_mul_f32 v[20:21], v[20:21], v[190:191] op_sel_hi:[1,0]
	v_pk_mul_f32 v[18:19], v[18:19], v[190:191] op_sel_hi:[1,0]
	v_pk_mul_f32 v[16:17], v[16:17], v[190:191] op_sel_hi:[1,0]
	v_pk_mul_f32 v[14:15], v[14:15], v[190:191] op_sel_hi:[1,0]
	v_pk_mul_f32 v[12:13], v[12:13], v[190:191] op_sel_hi:[1,0]
	v_pk_mul_f32 v[10:11], v[10:11], v[190:191] op_sel_hi:[1,0]
	v_pk_mul_f32 v[8:9], v[8:9], v[190:191] op_sel_hi:[1,0]
	v_pk_mul_f32 v[6:7], v[6:7], v[190:191] op_sel_hi:[1,0]
	v_pk_mul_f32 v[4:5], v[4:5], v[190:191] op_sel_hi:[1,0]
	v_pk_mul_f32 v[2:3], v[2:3], v[190:191] op_sel_hi:[1,0]
	v_pk_mul_f32 v[0:1], v[0:1], v[190:191] op_sel_hi:[1,0]
	v_mul_f32_e32 v202, v202, v190
	v_mov_b32_e32 v190, v246

.Latt_pv1_4:
	s_waitcnt lgkmcnt(12)
	v_mfma_f32_32x32x16_bf16 v[112:127], v[206:209], v[242:245], v[112:127]
	ds_read_b64_tr_b16 v[238:239], v221 offset:16640
	ds_read_b64_tr_b16 v[240:241], v221 offset:20736
	s_waitcnt lgkmcnt(12)
	v_mfma_f32_32x32x16_bf16 v[96:111], v[210:213], v[242:245], v[96:111]
	ds_read_b64_tr_b16 v[206:207], v205 offset:24576
	ds_read_b64_tr_b16 v[208:209], v205 offset:28672
	s_cmp_lg_u64 s[18:19], 0
	s_cbranch_scc1 .Latt_nd0_4
	s_sub_i32 s100, s76, 1
	s_cmp_eq_u32 s76, 0
	s_cselect_b32 s100, 2, s100
	s_lshl_b32 s101, s100, 14
	s_add_i32 m0, s73, s101
	s_nop 0
	global_load_lds_dwordx4 v178, s[14:15]

.Latt_nd1_4:
	s_waitcnt lgkmcnt(12)
	v_mfma_f32_32x32x16_bf16 v[48:63], v[226:229], v[242:245], v[48:63]
	ds_read_b64_tr_b16 v[222:223], v221 offset:24576
	ds_read_b64_tr_b16 v[224:225], v221 offset:28672
	s_waitcnt lgkmcnt(12)
	v_mfma_f32_32x32x16_bf16 v[32:47], v[230:233], v[242:245], v[32:47]
	ds_read_b64_tr_b16 v[226:227], v205 offset:24832
	ds_read_b64_tr_b16 v[228:229], v205 offset:28928
	s_cmp_lg_u64 s[18:19], 0
	s_cbranch_scc1 .Latt_nd2_4
	s_lshl_b32 s101, s100, 15
	s_add_i32 m0, s74, s101
	s_add_u32 s100, s14, 0x1000
	s_addc_u32 s101, s15, 0
	global_load_lds_dwordx4 v182, s[100:101]

.Latt_slow_4:
	s_lshl_b32 s22, s76, 14
	s_add_i32 s23, s22, 0
	v_add_u32_e32 v206, s23, v194
	ds_read_b128 v[128:131], v206
	v_add_u32_e32 v207, s23, v195
	ds_read_b128 v[210:213], v207
	v_add_u32_e32 v208, s23, v196
	v_add_u32_e32 v209, s23, v197
	v_lshrrev_b32_e32 v204, 3, v203
	s_add_i32 s77, s39, 31
	v_and_or_b32 v205, v203, 31, s71
	s_cmp_le_i32 s77, s71
	s_waitcnt lgkmcnt(1)
	v_mfma_f32_32x32x16_bf16 v[128:143], v[128:131], v[144:147], 0
	ds_read_b128 v[214:217], v209
	s_waitcnt lgkmcnt(1)
	v_mfma_f32_32x32x16_bf16 v[128:143], v[210:213], v[148:151], v[128:143]
	ds_read_b128 v[210:213], v208
	s_waitcnt lgkmcnt(0)
	v_mfma_f32_32x32x16_bf16 v[128:143], v[210:213], v[152:155], v[128:143]
	v_add_u32_e32 v210, s23, v198
	v_add_u32_e32 v212, s23, v199
	v_add_u32_e32 v213, s23, v200
	v_and_b32_e32 v211, 4, v204
	ds_read_b128 v[222:225], v212
	v_mfma_f32_32x32x16_bf16 v[128:143], v[214:217], v[156:159], v[128:143]
	ds_read_b128 v[214:217], v210
	s_waitcnt lgkmcnt(0)
	v_mfma_f32_32x32x16_bf16 v[128:143], v[214:217], v[160:163], v[128:143]
	ds_read_b128 v[216:219], v213
	v_add_u32_e32 v214, s23, v201
	v_mfma_f32_32x32x16_bf16 v[128:143], v[222:225], v[164:167], v[128:143]
	ds_read_b128 v[222:225], v214
	s_waitcnt lgkmcnt(1)
	v_mfma_f32_32x32x16_bf16 v[128:143], v[216:219], v[168:171], v[128:143]
	s_waitcnt lgkmcnt(0)
	v_mfma_f32_32x32x16_bf16 v[128:143], v[222:225], v[172:175], v[128:143]
	s_cbranch_scc1 .LBB0_1804
	v_add_u32_e32 v204, s39, v211
	v_cmp_lt_i32_e32 vcc, v204, v205
	v_add_u32_e32 v215, 2, v204
	s_nop 7
	v_cndmask_b32_e32 v129, v192, v129, vcc
	v_cmp_le_i32_e32 vcc, v204, v205
	s_nop 1
	v_cndmask_b32_e32 v128, v192, v128, vcc
	v_cmp_le_i32_e32 vcc, v215, v205
	v_add_u32_e32 v215, 3, v204
	s_nop 0
	v_cndmask_b32_e32 v130, v192, v130, vcc
	v_cmp_le_i32_e32 vcc, v215, v205
	v_add_u32_e32 v215, 8, v204
	s_nop 0
	v_cndmask_b32_e32 v131, v192, v131, vcc
	v_cmp_le_i32_e32 vcc, v215, v205
	v_add_u32_e32 v215, 9, v204
	s_nop 0
	v_cndmask_b32_e32 v132, v192, v132, vcc
	v_cmp_le_i32_e32 vcc, v215, v205
	v_add_u32_e32 v215, 10, v204
	s_nop 0
	v_cndmask_b32_e32 v133, v192, v133, vcc
	v_cmp_le_i32_e32 vcc, v215, v205
	v_add_u32_e32 v215, 11, v204
	s_nop 0
	v_cndmask_b32_e32 v134, v192, v134, vcc
	v_cmp_le_i32_e32 vcc, v215, v205
	v_add_u32_e32 v215, 16, v204
	s_nop 0
	v_cndmask_b32_e32 v135, v192, v135, vcc
	v_cmp_le_i32_e32 vcc, v215, v205
	v_add_u32_e32 v215, 17, v204
	s_nop 0
	v_cndmask_b32_e32 v136, v192, v136, vcc
	v_cmp_le_i32_e32 vcc, v215, v205
	v_add_u32_e32 v215, 18, v204
	s_nop 0
	v_cndmask_b32_e32 v137, v192, v137, vcc
	v_cmp_le_i32_e32 vcc, v215, v205
	v_add_u32_e32 v215, 19, v204
	s_nop 0
	v_cndmask_b32_e32 v138, v192, v138, vcc
	v_cmp_le_i32_e32 vcc, v215, v205
	v_add_u32_e32 v215, 24, v204
	s_nop 0
	v_cndmask_b32_e32 v139, v192, v139, vcc
	v_cmp_le_i32_e32 vcc, v215, v205
	v_add_u32_e32 v215, 25, v204
	s_nop 0
	v_cndmask_b32_e32 v140, v192, v140, vcc
	v_cmp_le_i32_e32 vcc, v215, v205
	v_add_u32_e32 v215, 26, v204
	v_add_u32_e32 v204, 27, v204
	v_cndmask_b32_e32 v141, v192, v141, vcc
	v_cmp_le_i32_e32 vcc, v215, v205
	s_nop 1
	v_cndmask_b32_e32 v142, v192, v142, vcc
	v_cmp_le_i32_e32 vcc, v204, v205
	s_nop 1
	v_cndmask_b32_e32 v143, v192, v143, vcc

.LBB0_1818:
	s_cmp_ge_u32 s76, s70
	s_cselect_b64 s[18:19], -1, 0
	v_mov_b32_e32 v204, v176
	s_and_b64 vcc, exec, s[18:19]
	s_cbranch_vccnz .LBB0_1820
	s_add_i32 s100, s4, 63
	s_cmp_le_i32 s100, s71
	s_cbranch_scc1 .LBB0_1820
	v_sub_co_u32_e64 v128, s[78:79], s33, 1
	s_nop 1
	v_cndmask_b32_e64 v130, v128, 2, s[78:79]
	v_lshlrev_b32_e32 v128, 14, v130
	v_add_u32_e32 v131, s73, v128
	v_lshl_add_u64 v[128:129], s[12:13], 0, v[178:179]
	s_add_u32 s78, s12, 0xf00
	v_readfirstlane_b32 s77, v131
	s_mov_b32 s80, m0
	s_mov_b32 m0, s77
	s_nop 0
	global_load_lds_dwordx4 v[128:129], off
	s_mov_b32 m0, s80
	v_lshl_add_u64 v[128:129], s[12:13], 0, v[180:181]
	s_addc_u32 s79, s13, 0
	s_addk_i32 s77, 0x400
	s_mov_b32 s80, m0
	s_mov_b32 m0, s77
	s_nop 0
	global_load_lds_dwordx4 v[128:129], off
	s_mov_b32 m0, s80
	v_lshlrev_b32_e32 v128, 15, v130
	v_add_u32_e32 v130, s74, v128
	v_lshl_add_u64 v[128:129], s[78:79], 0, v[182:183]
	v_readfirstlane_b32 s77, v130
	s_mov_b32 s80, m0
	s_mov_b32 m0, s77
	s_nop 0
	global_load_lds_dwordx4 v[128:129], off
	s_mov_b32 m0, s80
	v_lshl_add_u64 v[128:129], s[78:79], 0, v[184:185]
	s_add_i32 s80, s77, 0x400
	s_mov_b32 s81, m0
	s_mov_b32 m0, s80
	s_nop 0
	global_load_lds_dwordx4 v[128:129], off
	s_mov_b32 m0, s81
	v_lshl_add_u64 v[128:129], s[78:79], 0, v[186:187]
	s_add_i32 s80, s77, 0x800
	s_mov_b32 s81, m0
	s_mov_b32 m0, s80
	s_nop 0
	global_load_lds_dwordx4 v[128:129], off
	s_mov_b32 m0, s81
	v_lshl_add_u64 v[128:129], s[78:79], 0, v[188:189]
	s_addk_i32 s77, 0xc00
	s_mov_b32 s78, m0
	s_mov_b32 m0, s77
	s_nop 0
	global_load_lds_dwordx4 v[128:129], off
	s_mov_b32 m0, s78
.LBB0_1820:
	s_cmp_gt_i32 s4, s72
	s_cbranch_scc1 .LBB0_1831
	s_add_i32 s100, s4, 63
	s_cmp_le_i32 s100, s71
	s_cbranch_scc0 .Latt_slow_5
	s_lshl_b32 s98, s33, 14
	s_lshl_b32 s99, s33, 15
	s_add_i32 s99, s99, 0xc000
	v_add_u32_e32 v206, s98, v196
	ds_read_b128 v[206:209], v206
	v_add_u32_e32 v210, s98, v197
	ds_read_b128 v[210:213], v210
	v_add_u32_e32 v214, s98, v198
	ds_read_b128 v[214:217], v214
	v_add_u32_e32 v222, s98, v199
	ds_read_b128 v[222:225], v222
	v_add_u32_e32 v226, s98, v200
	ds_read_b128 v[226:229], v226
	v_add_u32_e32 v230, s98, v201
	ds_read_b128 v[230:233], v230
	v_add_u32_e32 v234, s98, v202
	ds_read_b128 v[234:237], v234
	v_add_u32_e32 v238, s98, v203
	ds_read_b128 v[238:241], v238
	v_bfe_u32 v246, v204, 2, 2
	v_bfe_u32 v247, v204, 5, 1
	v_lshl_or_b32 v247, v247, 2, v246
	v_and_b32_e32 v249, 3, v204
	v_and_b32_e32 v254, 16, v204
	v_lshl_or_b32 v249, v249, 2, v254
	v_lshlrev_b32_e32 v249, 1, v249
	v_lshl_add_u32 v247, v247, 9, v249
	v_add_u32_e32 v247, s99, v247
	v_lshlrev_b32_e32 v246, 6, v246
	v_add_u32_e32 v205, v247, v246
	v_xor_b32_e32 v249, 64, v246
	v_add_u32_e32 v218, v247, v249
	v_xor_b32_e32 v249, 0x80, v246
	v_add_u32_e32 v219, v247, v249
	v_xor_b32_e32 v249, 0xc0, v246
	v_add_u32_e32 v221, v247, v249
	s_waitcnt lgkmcnt(7)
	v_mfma_f32_32x32x16_bf16 v[128:143], v[206:209], v[144:147], 0
	v_add_u32_e32 v206, s98, v196
	ds_read_b128 v[206:209], v206 offset:8192
	s_waitcnt lgkmcnt(7)
	v_mfma_f32_32x32x16_bf16 v[128:143], v[210:213], v[148:151], v[128:143]
	v_add_u32_e32 v210, s98, v197
	ds_read_b128 v[210:213], v210 offset:8192
	s_waitcnt lgkmcnt(7)
	v_mfma_f32_32x32x16_bf16 v[128:143], v[214:217], v[152:155], v[128:143]
	v_add_u32_e32 v214, s98, v198
	ds_read_b128 v[214:217], v214 offset:8192
	s_waitcnt lgkmcnt(7)
	v_mfma_f32_32x32x16_bf16 v[128:143], v[222:225], v[156:159], v[128:143]
	v_add_u32_e32 v222, s98, v199
	ds_read_b128 v[222:225], v222 offset:8192
	s_waitcnt lgkmcnt(7)
	v_mfma_f32_32x32x16_bf16 v[128:143], v[226:229], v[160:163], v[128:143]
	v_add_u32_e32 v226, s98, v200
	ds_read_b128 v[226:229], v226 offset:8192
	s_waitcnt lgkmcnt(7)
	v_mfma_f32_32x32x16_bf16 v[128:143], v[230:233], v[164:167], v[128:143]
	v_add_u32_e32 v230, s98, v201
	ds_read_b128 v[230:233], v230 offset:8192
	s_waitcnt lgkmcnt(7)
	v_mfma_f32_32x32x16_bf16 v[128:143], v[234:237], v[168:171], v[128:143]
	v_add_u32_e32 v234, s98, v202
	ds_read_b128 v[234:237], v234 offset:8192
	s_waitcnt lgkmcnt(7)
	v_mfma_f32_32x32x16_bf16 v[128:143], v[238:241], v[172:175], v[128:143]
	v_add_u32_e32 v238, s98, v203
	ds_read_b128 v[238:241], v238 offset:8192
	s_nop 9
	v_max3_f32 v246, v128, v129, v130
	v_max3_f32 v247, v131, v132, v133
	v_max3_f32 v246, v246, v134, v135
	v_max3_f32 v247, v247, v136, v137
	v_max3_f32 v246, v246, v138, v139
	v_max3_f32 v247, v247, v140, v141
	v_max3_f32 v246, v246, v142, v143
	v_max_f32_e32 v246, v246, v247
	v_mov_b32_e32 v247, v246
	v_add_f32_e32 v249, 0x41000000, v190
	s_nop 1
	v_permlane32_swap_b32_e32 v246, v247
	v_max_f32_e32 v246, v246, v247
	v_cmp_gt_f32_e32 vcc, v246, v249
	s_cbranch_vccz .Latt_nr0_5
	v_max_f32_e32 v246, v190, v246
	v_sub_f32_e32 v190, v190, v246
	v_exp_f32_e32 v190, v190
	s_nop 0
	v_pk_mul_f32 v[126:127], v[126:127], v[190:191] op_sel_hi:[1,0]
	v_pk_mul_f32 v[124:125], v[124:125], v[190:191] op_sel_hi:[1,0]
	v_pk_mul_f32 v[122:123], v[122:123], v[190:191] op_sel_hi:[1,0]
	v_pk_mul_f32 v[120:121], v[120:121], v[190:191] op_sel_hi:[1,0]
	v_pk_mul_f32 v[118:119], v[118:119], v[190:191] op_sel_hi:[1,0]
	v_pk_mul_f32 v[116:117], v[116:117], v[190:191] op_sel_hi:[1,0]
	v_pk_mul_f32 v[114:115], v[114:115], v[190:191] op_sel_hi:[1,0]
	v_pk_mul_f32 v[112:113], v[112:113], v[190:191] op_sel_hi:[1,0]
	v_pk_mul_f32 v[110:111], v[110:111], v[190:191] op_sel_hi:[1,0]
	v_pk_mul_f32 v[108:109], v[108:109], v[190:191] op_sel_hi:[1,0]
	v_pk_mul_f32 v[106:107], v[106:107], v[190:191] op_sel_hi:[1,0]
	v_pk_mul_f32 v[104:105], v[104:105], v[190:191] op_sel_hi:[1,0]
	v_pk_mul_f32 v[102:103], v[102:103], v[190:191] op_sel_hi:[1,0]
	v_pk_mul_f32 v[100:101], v[100:101], v[190:191] op_sel_hi:[1,0]
	v_pk_mul_f32 v[98:99], v[98:99], v[190:191] op_sel_hi:[1,0]
	v_pk_mul_f32 v[96:97], v[96:97], v[190:191] op_sel_hi:[1,0]
	v_pk_mul_f32 v[94:95], v[94:95], v[190:191] op_sel_hi:[1,0]
	v_pk_mul_f32 v[92:93], v[92:93], v[190:191] op_sel_hi:[1,0]
	v_pk_mul_f32 v[90:91], v[90:91], v[190:191] op_sel_hi:[1,0]
	v_pk_mul_f32 v[88:89], v[88:89], v[190:191] op_sel_hi:[1,0]
	v_pk_mul_f32 v[86:87], v[86:87], v[190:191] op_sel_hi:[1,0]
	v_pk_mul_f32 v[84:85], v[84:85], v[190:191] op_sel_hi:[1,0]
	v_pk_mul_f32 v[82:83], v[82:83], v[190:191] op_sel_hi:[1,0]
	v_pk_mul_f32 v[80:81], v[80:81], v[190:191] op_sel_hi:[1,0]
	v_pk_mul_f32 v[78:79], v[78:79], v[190:191] op_sel_hi:[1,0]
	v_pk_mul_f32 v[76:77], v[76:77], v[190:191] op_sel_hi:[1,0]
	v_pk_mul_f32 v[74:75], v[74:75], v[190:191] op_sel_hi:[1,0]
	v_pk_mul_f32 v[72:73], v[72:73], v[190:191] op_sel_hi:[1,0]
	v_pk_mul_f32 v[70:71], v[70:71], v[190:191] op_sel_hi:[1,0]
	v_pk_mul_f32 v[68:69], v[68:69], v[190:191] op_sel_hi:[1,0]
	v_pk_mul_f32 v[66:67], v[66:67], v[190:191] op_sel_hi:[1,0]
	v_pk_mul_f32 v[64:65], v[64:65], v[190:191] op_sel_hi:[1,0]
	v_pk_mul_f32 v[62:63], v[62:63], v[190:191] op_sel_hi:[1,0]
	v_pk_mul_f32 v[60:61], v[60:61], v[190:191] op_sel_hi:[1,0]
	v_pk_mul_f32 v[58:59], v[58:59], v[190:191] op_sel_hi:[1,0]
	v_pk_mul_f32 v[56:57], v[56:57], v[190:191] op_sel_hi:[1,0]
	v_pk_mul_f32 v[54:55], v[54:55], v[190:191] op_sel_hi:[1,0]
	v_pk_mul_f32 v[52:53], v[52:53], v[190:191] op_sel_hi:[1,0]
	v_pk_mul_f32 v[50:51], v[50:51], v[190:191] op_sel_hi:[1,0]
	v_pk_mul_f32 v[48:49], v[48:49], v[190:191] op_sel_hi:[1,0]
	v_pk_mul_f32 v[46:47], v[46:47], v[190:191] op_sel_hi:[1,0]
	v_pk_mul_f32 v[44:45], v[44:45], v[190:191] op_sel_hi:[1,0]
	v_pk_mul_f32 v[42:43], v[42:43], v[190:191] op_sel_hi:[1,0]
	v_pk_mul_f32 v[40:41], v[40:41], v[190:191] op_sel_hi:[1,0]
	v_pk_mul_f32 v[38:39], v[38:39], v[190:191] op_sel_hi:[1,0]
	v_pk_mul_f32 v[36:37], v[36:37], v[190:191] op_sel_hi:[1,0]
	v_pk_mul_f32 v[34:35], v[34:35], v[190:191] op_sel_hi:[1,0]
	v_pk_mul_f32 v[32:33], v[32:33], v[190:191] op_sel_hi:[1,0]
	v_pk_mul_f32 v[30:31], v[30:31], v[190:191] op_sel_hi:[1,0]
	v_pk_mul_f32 v[28:29], v[28:29], v[190:191] op_sel_hi:[1,0]
	v_pk_mul_f32 v[26:27], v[26:27], v[190:191] op_sel_hi:[1,0]
	v_pk_mul_f32 v[24:25], v[24:25], v[190:191] op_sel_hi:[1,0]
	v_pk_mul_f32 v[22:23], v[22:23], v[190:191] op_sel_hi:[1,0]
	v_pk_mul_f32 v[20:21], v[20:21], v[190:191] op_sel_hi:[1,0]
	v_pk_mul_f32 v[18:19], v[18:19], v[190:191] op_sel_hi:[1,0]
	v_pk_mul_f32 v[16:17], v[16:17], v[190:191] op_sel_hi:[1,0]
	v_pk_mul_f32 v[14:15], v[14:15], v[190:191] op_sel_hi:[1,0]
	v_pk_mul_f32 v[12:13], v[12:13], v[190:191] op_sel_hi:[1,0]
	v_pk_mul_f32 v[10:11], v[10:11], v[190:191] op_sel_hi:[1,0]
	v_pk_mul_f32 v[8:9], v[8:9], v[190:191] op_sel_hi:[1,0]
	v_pk_mul_f32 v[6:7], v[6:7], v[190:191] op_sel_hi:[1,0]
	v_pk_mul_f32 v[4:5], v[4:5], v[190:191] op_sel_hi:[1,0]
	v_pk_mul_f32 v[2:3], v[2:3], v[190:191] op_sel_hi:[1,0]
	v_pk_mul_f32 v[0:1], v[0:1], v[190:191] op_sel_hi:[1,0]
	v_mul_f32_e32 v195, v195, v190
	v_mov_b32_e32 v190, v246

.Latt_pv1_5:
	s_waitcnt lgkmcnt(12)
	v_mfma_f32_32x32x16_bf16 v[112:127], v[206:209], v[242:245], v[112:127]
	ds_read_b64_tr_b16 v[238:239], v221 offset:16640
	ds_read_b64_tr_b16 v[240:241], v221 offset:20736
	s_waitcnt lgkmcnt(12)
	v_mfma_f32_32x32x16_bf16 v[96:111], v[210:213], v[242:245], v[96:111]
	ds_read_b64_tr_b16 v[206:207], v205 offset:24576
	ds_read_b64_tr_b16 v[208:209], v205 offset:28672
	s_cmp_lg_u64 s[18:19], 0
	s_cbranch_scc1 .Latt_nd0_5
	s_sub_i32 s100, s33, 1
	s_cmp_eq_u32 s33, 0
	s_cselect_b32 s100, 2, s100
	s_lshl_b32 s101, s100, 14
	s_add_i32 m0, s73, s101
	s_nop 0
	global_load_lds_dwordx4 v178, s[12:13]

.Latt_nd1_5:
	s_waitcnt lgkmcnt(12)
	v_mfma_f32_32x32x16_bf16 v[48:63], v[226:229], v[242:245], v[48:63]
	ds_read_b64_tr_b16 v[222:223], v221 offset:24576
	ds_read_b64_tr_b16 v[224:225], v221 offset:28672
	s_waitcnt lgkmcnt(12)
	v_mfma_f32_32x32x16_bf16 v[32:47], v[230:233], v[242:245], v[32:47]
	ds_read_b64_tr_b16 v[226:227], v205 offset:24832
	ds_read_b64_tr_b16 v[228:229], v205 offset:28928
	s_cmp_lg_u64 s[18:19], 0
	s_cbranch_scc1 .Latt_nd2_5
	s_lshl_b32 s101, s100, 15
	s_add_i32 m0, s74, s101
	s_add_u32 s100, s12, 0xf00
	s_addc_u32 s101, s13, 0
	global_load_lds_dwordx4 v182, s[100:101]

.Latt_slow_5:
	s_lshl_b32 s77, s33, 14
	s_add_i32 s78, s77, 0
	v_add_u32_e32 v207, s78, v196
	ds_read_b128 v[128:131], v207
	v_add_u32_e32 v208, s78, v197
	ds_read_b128 v[210:213], v208
	v_add_u32_e32 v209, s78, v198
	v_lshrrev_b32_e32 v205, 3, v204
	s_add_i32 s79, s4, 31
	v_and_or_b32 v206, v204, 31, s71
	s_cmp_le_i32 s79, s71
	s_waitcnt lgkmcnt(1)
	v_mfma_f32_32x32x16_bf16 v[128:143], v[128:131], v[144:147], 0
	s_waitcnt lgkmcnt(0)
	v_mfma_f32_32x32x16_bf16 v[128:143], v[210:213], v[148:151], v[128:143]
	ds_read_b128 v[212:215], v209
	v_add_u32_e32 v210, s78, v199
	ds_read_b128 v[216:219], v210
	v_add_u32_e32 v211, s78, v200
	s_waitcnt lgkmcnt(1)
	v_mfma_f32_32x32x16_bf16 v[128:143], v[212:215], v[152:155], v[128:143]
	v_add_u32_e32 v213, s78, v201
	v_and_b32_e32 v212, 4, v205
	ds_read_b128 v[222:225], v213
	s_waitcnt lgkmcnt(1)
	v_mfma_f32_32x32x16_bf16 v[128:143], v[216:219], v[156:159], v[128:143]
	ds_read_b128 v[214:217], v211
	s_waitcnt lgkmcnt(0)
	v_mfma_f32_32x32x16_bf16 v[128:143], v[214:217], v[160:163], v[128:143]
	v_add_u32_e32 v214, s78, v202
	ds_read_b128 v[216:219], v214
	v_add_u32_e32 v215, s78, v203
	v_mfma_f32_32x32x16_bf16 v[128:143], v[222:225], v[164:167], v[128:143]
	ds_read_b128 v[222:225], v215
	s_waitcnt lgkmcnt(1)
	v_mfma_f32_32x32x16_bf16 v[128:143], v[216:219], v[168:171], v[128:143]
	s_waitcnt lgkmcnt(0)
	v_mfma_f32_32x32x16_bf16 v[128:143], v[222:225], v[172:175], v[128:143]
	s_cbranch_scc1 .LBB0_1823
	v_add_u32_e32 v205, s4, v212
	v_cmp_lt_i32_e32 vcc, v205, v206
	v_add_u32_e32 v216, 2, v205
	s_nop 7
	v_cndmask_b32_e32 v129, v192, v129, vcc
	v_cmp_le_i32_e32 vcc, v205, v206
	s_nop 1
	v_cndmask_b32_e32 v128, v192, v128, vcc
	v_cmp_le_i32_e32 vcc, v216, v206
	v_add_u32_e32 v216, 3, v205
	s_nop 0
	v_cndmask_b32_e32 v130, v192, v130, vcc
	v_cmp_le_i32_e32 vcc, v216, v206
	v_add_u32_e32 v216, 8, v205
	s_nop 0
	v_cndmask_b32_e32 v131, v192, v131, vcc
	v_cmp_le_i32_e32 vcc, v216, v206
	v_add_u32_e32 v216, 9, v205
	s_nop 0
	v_cndmask_b32_e32 v132, v192, v132, vcc
	v_cmp_le_i32_e32 vcc, v216, v206
	v_add_u32_e32 v216, 10, v205
	s_nop 0
	v_cndmask_b32_e32 v133, v192, v133, vcc
	v_cmp_le_i32_e32 vcc, v216, v206
	v_add_u32_e32 v216, 11, v205
	s_nop 0
	v_cndmask_b32_e32 v134, v192, v134, vcc
	v_cmp_le_i32_e32 vcc, v216, v206
	v_add_u32_e32 v216, 16, v205
	s_nop 0
	v_cndmask_b32_e32 v135, v192, v135, vcc
	v_cmp_le_i32_e32 vcc, v216, v206
	v_add_u32_e32 v216, 17, v205
	s_nop 0
	v_cndmask_b32_e32 v136, v192, v136, vcc
	v_cmp_le_i32_e32 vcc, v216, v206
	v_add_u32_e32 v216, 18, v205
	s_nop 0
	v_cndmask_b32_e32 v137, v192, v137, vcc
	v_cmp_le_i32_e32 vcc, v216, v206
	v_add_u32_e32 v216, 19, v205
	s_nop 0
	v_cndmask_b32_e32 v138, v192, v138, vcc
	v_cmp_le_i32_e32 vcc, v216, v206
	v_add_u32_e32 v216, 24, v205
	s_nop 0
	v_cndmask_b32_e32 v139, v192, v139, vcc
	v_cmp_le_i32_e32 vcc, v216, v206
	v_add_u32_e32 v216, 25, v205
	s_nop 0
	v_cndmask_b32_e32 v140, v192, v140, vcc
	v_cmp_le_i32_e32 vcc, v216, v206
	v_add_u32_e32 v216, 26, v205
	v_add_u32_e32 v205, 27, v205
	v_cndmask_b32_e32 v141, v192, v141, vcc
	v_cmp_le_i32_e32 vcc, v216, v206
	s_nop 1
	v_cndmask_b32_e32 v142, v192, v142, vcc
	v_cmp_le_i32_e32 vcc, v205, v206
	s_nop 1
	v_cndmask_b32_e32 v143, v192, v143, vcc

.LBB0_1837:
	s_cmp_ge_u32 s73, s66
	s_cselect_b64 s[12:13], -1, 0
	v_mov_b32_e32 v204, v176
	s_and_b64 vcc, exec, s[12:13]
	s_cbranch_vccnz .LBB0_1839
	s_add_i32 s100, s72, 63
	s_cmp_le_i32 s100, s68
	s_cbranch_scc1 .LBB0_1839
	v_sub_co_u32_e64 v128, s[14:15], s34, 1
	s_nop 1
	v_cndmask_b32_e64 v130, v128, 2, s[14:15]
	v_lshlrev_b32_e32 v128, 14, v130
	v_add_u32_e32 v131, s36, v128
	v_lshl_add_u64 v[128:129], s[20:21], 0, v[178:179]
	s_add_u32 s14, s20, 0x1000
	v_readfirstlane_b32 s35, v131
	s_mov_b32 s40, m0
	s_mov_b32 m0, s35
	s_nop 0
	global_load_lds_dwordx4 v[128:129], off
	s_mov_b32 m0, s40
	v_lshl_add_u64 v[128:129], s[20:21], 0, v[180:181]
	s_addc_u32 s15, s21, 0
	s_addk_i32 s35, 0x400
	s_mov_b32 s40, m0
	s_mov_b32 m0, s35
	s_nop 0
	global_load_lds_dwordx4 v[128:129], off
	s_mov_b32 m0, s40
	v_lshlrev_b32_e32 v128, 15, v130
	v_add_u32_e32 v130, s37, v128
	v_lshl_add_u64 v[128:129], s[14:15], 0, v[182:183]
	v_readfirstlane_b32 s35, v130
	s_mov_b32 s40, m0
	s_mov_b32 m0, s35
	s_nop 0
	global_load_lds_dwordx4 v[128:129], off
	s_mov_b32 m0, s40
	v_lshl_add_u64 v[128:129], s[14:15], 0, v[184:185]
	s_add_i32 s40, s35, 0x400
	s_mov_b32 s41, m0
	s_mov_b32 m0, s40
	s_nop 0
	global_load_lds_dwordx4 v[128:129], off
	s_mov_b32 m0, s41
	v_lshl_add_u64 v[128:129], s[14:15], 0, v[186:187]
	s_add_i32 s40, s35, 0x800
	s_mov_b32 s41, m0
	s_mov_b32 m0, s40
	s_nop 0
	global_load_lds_dwordx4 v[128:129], off
	s_mov_b32 m0, s41
	v_lshl_add_u64 v[128:129], s[14:15], 0, v[188:189]
	s_add_i32 s14, s35, 0xc00
	s_mov_b32 s15, m0
	s_mov_b32 m0, s14
	s_nop 0
	global_load_lds_dwordx4 v[128:129], off
	s_mov_b32 m0, s15
.LBB0_1839:
	s_cmp_gt_i32 s72, s69
	s_cbranch_scc1 .LBB0_1850
	s_add_i32 s100, s72, 63
	s_cmp_le_i32 s100, s68
	s_cbranch_scc0 .Latt_slow_6
	s_lshl_b32 s98, s34, 14
	s_lshl_b32 s99, s34, 15
	s_add_i32 s99, s99, 0xc000
	v_add_u32_e32 v206, s98, v195
	ds_read_b128 v[206:209], v206
	v_add_u32_e32 v210, s98, v196
	ds_read_b128 v[210:213], v210
	v_add_u32_e32 v214, s98, v197
	ds_read_b128 v[214:217], v214
	v_add_u32_e32 v222, s98, v198
	ds_read_b128 v[222:225], v222
	v_add_u32_e32 v226, s98, v199
	ds_read_b128 v[226:229], v226
	v_add_u32_e32 v230, s98, v200
	ds_read_b128 v[230:233], v230
	v_add_u32_e32 v234, s98, v201
	ds_read_b128 v[234:237], v234
	v_add_u32_e32 v238, s98, v202
	ds_read_b128 v[238:241], v238
	v_bfe_u32 v246, v204, 2, 2
	v_bfe_u32 v247, v204, 5, 1
	v_lshl_or_b32 v247, v247, 2, v246
	v_and_b32_e32 v249, 3, v204
	v_and_b32_e32 v254, 16, v204
	v_lshl_or_b32 v249, v249, 2, v254
	v_lshlrev_b32_e32 v249, 1, v249
	v_lshl_add_u32 v247, v247, 9, v249
	v_add_u32_e32 v247, s99, v247
	v_lshlrev_b32_e32 v246, 6, v246
	v_add_u32_e32 v205, v247, v246
	v_xor_b32_e32 v249, 64, v246
	v_add_u32_e32 v218, v247, v249
	v_xor_b32_e32 v249, 0x80, v246
	v_add_u32_e32 v219, v247, v249
	v_xor_b32_e32 v249, 0xc0, v246
	v_add_u32_e32 v221, v247, v249
	s_waitcnt lgkmcnt(7)
	v_mfma_f32_32x32x16_bf16 v[128:143], v[206:209], v[144:147], 0
	v_add_u32_e32 v206, s98, v195
	ds_read_b128 v[206:209], v206 offset:8192
	s_waitcnt lgkmcnt(7)
	v_mfma_f32_32x32x16_bf16 v[128:143], v[210:213], v[148:151], v[128:143]
	v_add_u32_e32 v210, s98, v196
	ds_read_b128 v[210:213], v210 offset:8192
	s_waitcnt lgkmcnt(7)
	v_mfma_f32_32x32x16_bf16 v[128:143], v[214:217], v[152:155], v[128:143]
	v_add_u32_e32 v214, s98, v197
	ds_read_b128 v[214:217], v214 offset:8192
	s_waitcnt lgkmcnt(7)
	v_mfma_f32_32x32x16_bf16 v[128:143], v[222:225], v[156:159], v[128:143]
	v_add_u32_e32 v222, s98, v198
	ds_read_b128 v[222:225], v222 offset:8192
	s_waitcnt lgkmcnt(7)
	v_mfma_f32_32x32x16_bf16 v[128:143], v[226:229], v[160:163], v[128:143]
	v_add_u32_e32 v226, s98, v199
	ds_read_b128 v[226:229], v226 offset:8192
	s_waitcnt lgkmcnt(7)
	v_mfma_f32_32x32x16_bf16 v[128:143], v[230:233], v[164:167], v[128:143]
	v_add_u32_e32 v230, s98, v200
	ds_read_b128 v[230:233], v230 offset:8192
	s_waitcnt lgkmcnt(7)
	v_mfma_f32_32x32x16_bf16 v[128:143], v[234:237], v[168:171], v[128:143]
	v_add_u32_e32 v234, s98, v201
	ds_read_b128 v[234:237], v234 offset:8192
	s_waitcnt lgkmcnt(7)
	v_mfma_f32_32x32x16_bf16 v[128:143], v[238:241], v[172:175], v[128:143]
	v_add_u32_e32 v238, s98, v202
	ds_read_b128 v[238:241], v238 offset:8192
	s_nop 9
	v_max3_f32 v246, v128, v129, v130
	v_max3_f32 v247, v131, v132, v133
	v_max3_f32 v246, v246, v134, v135
	v_max3_f32 v247, v247, v136, v137
	v_max3_f32 v246, v246, v138, v139
	v_max3_f32 v247, v247, v140, v141
	v_max3_f32 v246, v246, v142, v143
	v_max_f32_e32 v246, v246, v247
	v_mov_b32_e32 v247, v246
	v_add_f32_e32 v249, 0x41000000, v190
	s_nop 1
	v_permlane32_swap_b32_e32 v246, v247
	v_max_f32_e32 v246, v246, v247
	v_cmp_gt_f32_e32 vcc, v246, v249
	s_cbranch_vccz .Latt_nr0_6
	v_max_f32_e32 v246, v190, v246
	v_sub_f32_e32 v190, v190, v246
	v_exp_f32_e32 v190, v190
	s_nop 0
	v_pk_mul_f32 v[126:127], v[126:127], v[190:191] op_sel_hi:[1,0]
	v_pk_mul_f32 v[124:125], v[124:125], v[190:191] op_sel_hi:[1,0]
	v_pk_mul_f32 v[122:123], v[122:123], v[190:191] op_sel_hi:[1,0]
	v_pk_mul_f32 v[120:121], v[120:121], v[190:191] op_sel_hi:[1,0]
	v_pk_mul_f32 v[118:119], v[118:119], v[190:191] op_sel_hi:[1,0]
	v_pk_mul_f32 v[116:117], v[116:117], v[190:191] op_sel_hi:[1,0]
	v_pk_mul_f32 v[114:115], v[114:115], v[190:191] op_sel_hi:[1,0]
	v_pk_mul_f32 v[112:113], v[112:113], v[190:191] op_sel_hi:[1,0]
	v_pk_mul_f32 v[110:111], v[110:111], v[190:191] op_sel_hi:[1,0]
	v_pk_mul_f32 v[108:109], v[108:109], v[190:191] op_sel_hi:[1,0]
	v_pk_mul_f32 v[106:107], v[106:107], v[190:191] op_sel_hi:[1,0]
	v_pk_mul_f32 v[104:105], v[104:105], v[190:191] op_sel_hi:[1,0]
	v_pk_mul_f32 v[102:103], v[102:103], v[190:191] op_sel_hi:[1,0]
	v_pk_mul_f32 v[100:101], v[100:101], v[190:191] op_sel_hi:[1,0]
	v_pk_mul_f32 v[98:99], v[98:99], v[190:191] op_sel_hi:[1,0]
	v_pk_mul_f32 v[96:97], v[96:97], v[190:191] op_sel_hi:[1,0]
	v_pk_mul_f32 v[94:95], v[94:95], v[190:191] op_sel_hi:[1,0]
	v_pk_mul_f32 v[92:93], v[92:93], v[190:191] op_sel_hi:[1,0]
	v_pk_mul_f32 v[90:91], v[90:91], v[190:191] op_sel_hi:[1,0]
	v_pk_mul_f32 v[88:89], v[88:89], v[190:191] op_sel_hi:[1,0]
	v_pk_mul_f32 v[86:87], v[86:87], v[190:191] op_sel_hi:[1,0]
	v_pk_mul_f32 v[84:85], v[84:85], v[190:191] op_sel_hi:[1,0]
	v_pk_mul_f32 v[82:83], v[82:83], v[190:191] op_sel_hi:[1,0]
	v_pk_mul_f32 v[80:81], v[80:81], v[190:191] op_sel_hi:[1,0]
	v_pk_mul_f32 v[78:79], v[78:79], v[190:191] op_sel_hi:[1,0]
	v_pk_mul_f32 v[76:77], v[76:77], v[190:191] op_sel_hi:[1,0]
	v_pk_mul_f32 v[74:75], v[74:75], v[190:191] op_sel_hi:[1,0]
	v_pk_mul_f32 v[72:73], v[72:73], v[190:191] op_sel_hi:[1,0]
	v_pk_mul_f32 v[70:71], v[70:71], v[190:191] op_sel_hi:[1,0]
	v_pk_mul_f32 v[68:69], v[68:69], v[190:191] op_sel_hi:[1,0]
	v_pk_mul_f32 v[66:67], v[66:67], v[190:191] op_sel_hi:[1,0]
	v_pk_mul_f32 v[64:65], v[64:65], v[190:191] op_sel_hi:[1,0]
	v_pk_mul_f32 v[62:63], v[62:63], v[190:191] op_sel_hi:[1,0]
	v_pk_mul_f32 v[60:61], v[60:61], v[190:191] op_sel_hi:[1,0]
	v_pk_mul_f32 v[58:59], v[58:59], v[190:191] op_sel_hi:[1,0]
	v_pk_mul_f32 v[56:57], v[56:57], v[190:191] op_sel_hi:[1,0]
	v_pk_mul_f32 v[54:55], v[54:55], v[190:191] op_sel_hi:[1,0]
	v_pk_mul_f32 v[52:53], v[52:53], v[190:191] op_sel_hi:[1,0]
	v_pk_mul_f32 v[50:51], v[50:51], v[190:191] op_sel_hi:[1,0]
	v_pk_mul_f32 v[48:49], v[48:49], v[190:191] op_sel_hi:[1,0]
	v_pk_mul_f32 v[46:47], v[46:47], v[190:191] op_sel_hi:[1,0]
	v_pk_mul_f32 v[44:45], v[44:45], v[190:191] op_sel_hi:[1,0]
	v_pk_mul_f32 v[42:43], v[42:43], v[190:191] op_sel_hi:[1,0]
	v_pk_mul_f32 v[40:41], v[40:41], v[190:191] op_sel_hi:[1,0]
	v_pk_mul_f32 v[38:39], v[38:39], v[190:191] op_sel_hi:[1,0]
	v_pk_mul_f32 v[36:37], v[36:37], v[190:191] op_sel_hi:[1,0]
	v_pk_mul_f32 v[34:35], v[34:35], v[190:191] op_sel_hi:[1,0]
	v_pk_mul_f32 v[32:33], v[32:33], v[190:191] op_sel_hi:[1,0]
	v_pk_mul_f32 v[30:31], v[30:31], v[190:191] op_sel_hi:[1,0]
	v_pk_mul_f32 v[28:29], v[28:29], v[190:191] op_sel_hi:[1,0]
	v_pk_mul_f32 v[26:27], v[26:27], v[190:191] op_sel_hi:[1,0]
	v_pk_mul_f32 v[24:25], v[24:25], v[190:191] op_sel_hi:[1,0]
	v_pk_mul_f32 v[22:23], v[22:23], v[190:191] op_sel_hi:[1,0]
	v_pk_mul_f32 v[20:21], v[20:21], v[190:191] op_sel_hi:[1,0]
	v_pk_mul_f32 v[18:19], v[18:19], v[190:191] op_sel_hi:[1,0]
	v_pk_mul_f32 v[16:17], v[16:17], v[190:191] op_sel_hi:[1,0]
	v_pk_mul_f32 v[14:15], v[14:15], v[190:191] op_sel_hi:[1,0]
	v_pk_mul_f32 v[12:13], v[12:13], v[190:191] op_sel_hi:[1,0]
	v_pk_mul_f32 v[10:11], v[10:11], v[190:191] op_sel_hi:[1,0]
	v_pk_mul_f32 v[8:9], v[8:9], v[190:191] op_sel_hi:[1,0]
	v_pk_mul_f32 v[6:7], v[6:7], v[190:191] op_sel_hi:[1,0]
	v_pk_mul_f32 v[4:5], v[4:5], v[190:191] op_sel_hi:[1,0]
	v_pk_mul_f32 v[2:3], v[2:3], v[190:191] op_sel_hi:[1,0]
	v_pk_mul_f32 v[0:1], v[0:1], v[190:191] op_sel_hi:[1,0]
	v_mul_f32_e32 v203, v203, v190
	v_mov_b32_e32 v190, v246

.Latt_pv1_6:
	s_waitcnt lgkmcnt(12)
	v_mfma_f32_32x32x16_bf16 v[112:127], v[206:209], v[242:245], v[112:127]
	ds_read_b64_tr_b16 v[238:239], v221 offset:16640
	ds_read_b64_tr_b16 v[240:241], v221 offset:20736
	s_waitcnt lgkmcnt(12)
	v_mfma_f32_32x32x16_bf16 v[96:111], v[210:213], v[242:245], v[96:111]
	ds_read_b64_tr_b16 v[206:207], v205 offset:24576
	ds_read_b64_tr_b16 v[208:209], v205 offset:28672
	s_cmp_lg_u64 s[12:13], 0
	s_cbranch_scc1 .Latt_nd0_6
	s_sub_i32 s100, s34, 1
	s_cmp_eq_u32 s34, 0
	s_cselect_b32 s100, 2, s100
	s_lshl_b32 s101, s100, 14
	s_add_i32 m0, s36, s101
	s_nop 0
	global_load_lds_dwordx4 v178, s[20:21]
.Latt_nd0_6:
	s_waitcnt lgkmcnt(12)
	v_mfma_f32_32x32x16_bf16 v[80:95], v[214:217], v[242:245], v[80:95]
	ds_read_b64_tr_b16 v[210:211], v218 offset:24576
	ds_read_b64_tr_b16 v[212:213], v218 offset:28672
	s_waitcnt lgkmcnt(12)
	v_mfma_f32_32x32x16_bf16 v[64:79], v[222:225], v[242:245], v[64:79]
	ds_read_b64_tr_b16 v[214:215], v219 offset:24576
	ds_read_b64_tr_b16 v[216:217], v219 offset:28672
	s_cmp_lg_u64 s[12:13], 0
	s_cbranch_scc1 .Latt_nd1_6
	s_add_i32 m0, m0, 0x400
	s_nop 0
	global_load_lds_dwordx4 v180, s[20:21]
.Latt_nd1_6:
	s_waitcnt lgkmcnt(12)
	v_mfma_f32_32x32x16_bf16 v[48:63], v[226:229], v[242:245], v[48:63]
	ds_read_b64_tr_b16 v[222:223], v221 offset:24576
	ds_read_b64_tr_b16 v[224:225], v221 offset:28672
	s_waitcnt lgkmcnt(12)
	v_mfma_f32_32x32x16_bf16 v[32:47], v[230:233], v[242:245], v[32:47]
	ds_read_b64_tr_b16 v[226:227], v205 offset:24832
	ds_read_b64_tr_b16 v[228:229], v205 offset:28928
	s_cmp_lg_u64 s[12:13], 0
	s_cbranch_scc1 .Latt_nd2_6
	s_lshl_b32 s101, s100, 15
	s_add_i32 m0, s37, s101
	s_add_u32 s100, s20, 0x1000
	s_addc_u32 s101, s21, 0
	global_load_lds_dwordx4 v182, s[100:101]

.Latt_slow_6:
	s_lshl_b32 s14, s34, 14
	s_add_i32 s15, s14, 0
	v_add_u32_e32 v207, s15, v195
	ds_read_b128 v[128:131], v207
	v_add_u32_e32 v208, s15, v196
	ds_read_b128 v[210:213], v208
	v_add_u32_e32 v209, s15, v197
	v_lshrrev_b32_e32 v205, 3, v204
	s_add_i32 s35, s72, 31
	v_and_or_b32 v206, v204, 31, s68
	s_cmp_le_i32 s35, s68
	s_waitcnt lgkmcnt(1)
	v_mfma_f32_32x32x16_bf16 v[128:143], v[128:131], v[144:147], 0
	s_waitcnt lgkmcnt(0)
	v_mfma_f32_32x32x16_bf16 v[128:143], v[210:213], v[148:151], v[128:143]
	ds_read_b128 v[212:215], v209
	v_add_u32_e32 v210, s15, v198
	ds_read_b128 v[216:219], v210
	v_add_u32_e32 v211, s15, v199
	s_waitcnt lgkmcnt(1)
	v_mfma_f32_32x32x16_bf16 v[128:143], v[212:215], v[152:155], v[128:143]
	v_add_u32_e32 v213, s15, v200
	v_and_b32_e32 v212, 4, v205
	ds_read_b128 v[222:225], v213
	s_waitcnt lgkmcnt(1)
	v_mfma_f32_32x32x16_bf16 v[128:143], v[216:219], v[156:159], v[128:143]
	ds_read_b128 v[214:217], v211
	s_waitcnt lgkmcnt(0)
	v_mfma_f32_32x32x16_bf16 v[128:143], v[214:217], v[160:163], v[128:143]
	v_add_u32_e32 v214, s15, v201
	ds_read_b128 v[216:219], v214
	v_add_u32_e32 v215, s15, v202
	v_mfma_f32_32x32x16_bf16 v[128:143], v[222:225], v[164:167], v[128:143]
	ds_read_b128 v[222:225], v215
	s_waitcnt lgkmcnt(1)
	v_mfma_f32_32x32x16_bf16 v[128:143], v[216:219], v[168:171], v[128:143]
	s_waitcnt lgkmcnt(0)
	v_mfma_f32_32x32x16_bf16 v[128:143], v[222:225], v[172:175], v[128:143]
	s_cbranch_scc1 .LBB0_1842
	v_add_u32_e32 v205, s72, v212
	v_cmp_lt_i32_e32 vcc, v205, v206
	v_add_u32_e32 v216, 2, v205
	s_nop 7
	v_cndmask_b32_e32 v129, v192, v129, vcc
	v_cmp_le_i32_e32 vcc, v205, v206
	s_nop 1
	v_cndmask_b32_e32 v128, v192, v128, vcc
	v_cmp_le_i32_e32 vcc, v216, v206
	v_add_u32_e32 v216, 3, v205
	s_nop 0
	v_cndmask_b32_e32 v130, v192, v130, vcc
	v_cmp_le_i32_e32 vcc, v216, v206
	v_add_u32_e32 v216, 8, v205
	s_nop 0
	v_cndmask_b32_e32 v131, v192, v131, vcc
	v_cmp_le_i32_e32 vcc, v216, v206
	v_add_u32_e32 v216, 9, v205
	s_nop 0
	v_cndmask_b32_e32 v132, v192, v132, vcc
	v_cmp_le_i32_e32 vcc, v216, v206
	v_add_u32_e32 v216, 10, v205
	s_nop 0
	v_cndmask_b32_e32 v133, v192, v133, vcc
	v_cmp_le_i32_e32 vcc, v216, v206
	v_add_u32_e32 v216, 11, v205
	s_nop 0
	v_cndmask_b32_e32 v134, v192, v134, vcc
	v_cmp_le_i32_e32 vcc, v216, v206
	v_add_u32_e32 v216, 16, v205
	s_nop 0
	v_cndmask_b32_e32 v135, v192, v135, vcc
	v_cmp_le_i32_e32 vcc, v216, v206
	v_add_u32_e32 v216, 17, v205
	s_nop 0
	v_cndmask_b32_e32 v136, v192, v136, vcc
	v_cmp_le_i32_e32 vcc, v216, v206
	v_add_u32_e32 v216, 18, v205
	s_nop 0
	v_cndmask_b32_e32 v137, v192, v137, vcc
	v_cmp_le_i32_e32 vcc, v216, v206
	v_add_u32_e32 v216, 19, v205
	s_nop 0
	v_cndmask_b32_e32 v138, v192, v138, vcc
	v_cmp_le_i32_e32 vcc, v216, v206
	v_add_u32_e32 v216, 24, v205
	s_nop 0
	v_cndmask_b32_e32 v139, v192, v139, vcc
	v_cmp_le_i32_e32 vcc, v216, v206
	v_add_u32_e32 v216, 25, v205
	s_nop 0
	v_cndmask_b32_e32 v140, v192, v140, vcc
	v_cmp_le_i32_e32 vcc, v216, v206
	v_add_u32_e32 v216, 26, v205
	v_add_u32_e32 v205, 27, v205
	v_cndmask_b32_e32 v141, v192, v141, vcc
	v_cmp_le_i32_e32 vcc, v216, v206
	s_nop 1
	v_cndmask_b32_e32 v142, v192, v142, vcc
	v_cmp_le_i32_e32 vcc, v205, v206
	s_nop 1
	v_cndmask_b32_e32 v143, v192, v143, vcc

.LBB0_1856:
	s_cmp_ge_u32 s10, s66
	s_cselect_b64 s[8:9], -1, 0
	v_mov_b32_e32 v204, v176
	s_and_b64 vcc, exec, s[8:9]
	s_cbranch_vccnz .LBB0_1858
	s_add_i32 s100, s14, 63
	s_cmp_le_i32 s100, s68
	s_cbranch_scc1 .LBB0_1858
	v_sub_co_u32_e64 v128, s[16:17], s11, 1
	s_nop 1
	v_cndmask_b32_e64 v130, v128, 2, s[16:17]
	v_lshlrev_b32_e32 v128, 14, v130
	v_add_u32_e32 v131, s36, v128
	v_lshl_add_u64 v[128:129], s[22:23], 0, v[178:179]
	s_add_u32 s16, s22, 0xf00
	v_readfirstlane_b32 s15, v131
	s_mov_b32 s20, m0
	s_mov_b32 m0, s15
	s_nop 0
	global_load_lds_dwordx4 v[128:129], off
	s_mov_b32 m0, s20
	v_lshl_add_u64 v[128:129], s[22:23], 0, v[180:181]
	s_addc_u32 s17, s23, 0
	s_addk_i32 s15, 0x400
	s_mov_b32 s20, m0
	s_mov_b32 m0, s15
	s_nop 0
	global_load_lds_dwordx4 v[128:129], off
	s_mov_b32 m0, s20
	v_lshlrev_b32_e32 v128, 15, v130
	v_add_u32_e32 v130, s37, v128
	v_lshl_add_u64 v[128:129], s[16:17], 0, v[182:183]
	v_readfirstlane_b32 s15, v130
	s_mov_b32 s20, m0
	s_mov_b32 m0, s15
	s_nop 0
	global_load_lds_dwordx4 v[128:129], off
	s_mov_b32 m0, s20
	v_lshl_add_u64 v[128:129], s[16:17], 0, v[184:185]
	s_add_i32 s20, s15, 0x400
	s_mov_b32 s21, m0
	s_mov_b32 m0, s20
	s_nop 0
	global_load_lds_dwordx4 v[128:129], off
	s_mov_b32 m0, s21
	v_lshl_add_u64 v[128:129], s[16:17], 0, v[186:187]
	s_add_i32 s20, s15, 0x800
	s_mov_b32 s21, m0
	s_mov_b32 m0, s20
	s_nop 0
	global_load_lds_dwordx4 v[128:129], off
	s_mov_b32 m0, s21
	v_lshl_add_u64 v[128:129], s[16:17], 0, v[188:189]
	s_addk_i32 s15, 0xc00
	s_mov_b32 s16, m0
	s_mov_b32 m0, s15
	s_nop 0
	global_load_lds_dwordx4 v[128:129], off
	s_mov_b32 m0, s16
.LBB0_1858:
	s_cmp_gt_i32 s14, s69
	s_cbranch_scc1 .LBB0_1869
	s_add_i32 s100, s14, 63
	s_cmp_le_i32 s100, s68
	s_cbranch_scc0 .Latt_slow_7
	s_lshl_b32 s98, s11, 14
	s_lshl_b32 s99, s11, 15
	s_add_i32 s99, s99, 0xc000
	v_add_u32_e32 v206, s98, v196
	ds_read_b128 v[206:209], v206
	v_add_u32_e32 v210, s98, v197
	ds_read_b128 v[210:213], v210
	v_add_u32_e32 v214, s98, v198
	ds_read_b128 v[214:217], v214
	v_add_u32_e32 v222, s98, v199
	ds_read_b128 v[222:225], v222
	v_add_u32_e32 v226, s98, v200
	ds_read_b128 v[226:229], v226
	v_add_u32_e32 v230, s98, v201
	ds_read_b128 v[230:233], v230
	v_add_u32_e32 v234, s98, v202
	ds_read_b128 v[234:237], v234
	v_add_u32_e32 v238, s98, v203
	ds_read_b128 v[238:241], v238
	v_bfe_u32 v246, v204, 2, 2
	v_bfe_u32 v247, v204, 5, 1
	v_lshl_or_b32 v247, v247, 2, v246
	v_and_b32_e32 v249, 3, v204
	v_and_b32_e32 v254, 16, v204
	v_lshl_or_b32 v249, v249, 2, v254
	v_lshlrev_b32_e32 v249, 1, v249
	v_lshl_add_u32 v247, v247, 9, v249
	v_add_u32_e32 v247, s99, v247
	v_lshlrev_b32_e32 v246, 6, v246
	v_add_u32_e32 v205, v247, v246
	v_xor_b32_e32 v249, 64, v246
	v_add_u32_e32 v218, v247, v249
	v_xor_b32_e32 v249, 0x80, v246
	v_add_u32_e32 v219, v247, v249
	v_xor_b32_e32 v249, 0xc0, v246
	v_add_u32_e32 v221, v247, v249
	s_waitcnt lgkmcnt(7)
	v_mfma_f32_32x32x16_bf16 v[128:143], v[206:209], v[144:147], 0
	v_add_u32_e32 v206, s98, v196
	ds_read_b128 v[206:209], v206 offset:8192
	s_waitcnt lgkmcnt(7)
	v_mfma_f32_32x32x16_bf16 v[128:143], v[210:213], v[148:151], v[128:143]
	v_add_u32_e32 v210, s98, v197
	ds_read_b128 v[210:213], v210 offset:8192
	s_waitcnt lgkmcnt(7)
	v_mfma_f32_32x32x16_bf16 v[128:143], v[214:217], v[152:155], v[128:143]
	v_add_u32_e32 v214, s98, v198
	ds_read_b128 v[214:217], v214 offset:8192
	s_waitcnt lgkmcnt(7)
	v_mfma_f32_32x32x16_bf16 v[128:143], v[222:225], v[156:159], v[128:143]
	v_add_u32_e32 v222, s98, v199
	ds_read_b128 v[222:225], v222 offset:8192
	s_waitcnt lgkmcnt(7)
	v_mfma_f32_32x32x16_bf16 v[128:143], v[226:229], v[160:163], v[128:143]
	v_add_u32_e32 v226, s98, v200
	ds_read_b128 v[226:229], v226 offset:8192
	s_waitcnt lgkmcnt(7)
	v_mfma_f32_32x32x16_bf16 v[128:143], v[230:233], v[164:167], v[128:143]
	v_add_u32_e32 v230, s98, v201
	ds_read_b128 v[230:233], v230 offset:8192
	s_waitcnt lgkmcnt(7)
	v_mfma_f32_32x32x16_bf16 v[128:143], v[234:237], v[168:171], v[128:143]
	v_add_u32_e32 v234, s98, v202
	ds_read_b128 v[234:237], v234 offset:8192
	s_waitcnt lgkmcnt(7)
	v_mfma_f32_32x32x16_bf16 v[128:143], v[238:241], v[172:175], v[128:143]
	v_add_u32_e32 v238, s98, v203
	ds_read_b128 v[238:241], v238 offset:8192
	s_nop 9
	v_max3_f32 v246, v128, v129, v130
	v_max3_f32 v247, v131, v132, v133
	v_max3_f32 v246, v246, v134, v135
	v_max3_f32 v247, v247, v136, v137
	v_max3_f32 v246, v246, v138, v139
	v_max3_f32 v247, v247, v140, v141
	v_max3_f32 v246, v246, v142, v143
	v_max_f32_e32 v246, v246, v247
	v_mov_b32_e32 v247, v246
	v_add_f32_e32 v249, 0x41000000, v190
	s_nop 1
	v_permlane32_swap_b32_e32 v246, v247
	v_max_f32_e32 v246, v246, v247
	v_cmp_gt_f32_e32 vcc, v246, v249
	s_cbranch_vccz .Latt_nr0_7
	v_max_f32_e32 v246, v190, v246
	v_sub_f32_e32 v190, v190, v246
	v_exp_f32_e32 v190, v190
	s_nop 0
	v_pk_mul_f32 v[126:127], v[126:127], v[190:191] op_sel_hi:[1,0]
	v_pk_mul_f32 v[124:125], v[124:125], v[190:191] op_sel_hi:[1,0]
	v_pk_mul_f32 v[122:123], v[122:123], v[190:191] op_sel_hi:[1,0]
	v_pk_mul_f32 v[120:121], v[120:121], v[190:191] op_sel_hi:[1,0]
	v_pk_mul_f32 v[118:119], v[118:119], v[190:191] op_sel_hi:[1,0]
	v_pk_mul_f32 v[116:117], v[116:117], v[190:191] op_sel_hi:[1,0]
	v_pk_mul_f32 v[114:115], v[114:115], v[190:191] op_sel_hi:[1,0]
	v_pk_mul_f32 v[112:113], v[112:113], v[190:191] op_sel_hi:[1,0]
	v_pk_mul_f32 v[110:111], v[110:111], v[190:191] op_sel_hi:[1,0]
	v_pk_mul_f32 v[108:109], v[108:109], v[190:191] op_sel_hi:[1,0]
	v_pk_mul_f32 v[106:107], v[106:107], v[190:191] op_sel_hi:[1,0]
	v_pk_mul_f32 v[104:105], v[104:105], v[190:191] op_sel_hi:[1,0]
	v_pk_mul_f32 v[102:103], v[102:103], v[190:191] op_sel_hi:[1,0]
	v_pk_mul_f32 v[100:101], v[100:101], v[190:191] op_sel_hi:[1,0]
	v_pk_mul_f32 v[98:99], v[98:99], v[190:191] op_sel_hi:[1,0]
	v_pk_mul_f32 v[96:97], v[96:97], v[190:191] op_sel_hi:[1,0]
	v_pk_mul_f32 v[94:95], v[94:95], v[190:191] op_sel_hi:[1,0]
	v_pk_mul_f32 v[92:93], v[92:93], v[190:191] op_sel_hi:[1,0]
	v_pk_mul_f32 v[90:91], v[90:91], v[190:191] op_sel_hi:[1,0]
	v_pk_mul_f32 v[88:89], v[88:89], v[190:191] op_sel_hi:[1,0]
	v_pk_mul_f32 v[86:87], v[86:87], v[190:191] op_sel_hi:[1,0]
	v_pk_mul_f32 v[84:85], v[84:85], v[190:191] op_sel_hi:[1,0]
	v_pk_mul_f32 v[82:83], v[82:83], v[190:191] op_sel_hi:[1,0]
	v_pk_mul_f32 v[80:81], v[80:81], v[190:191] op_sel_hi:[1,0]
	v_pk_mul_f32 v[78:79], v[78:79], v[190:191] op_sel_hi:[1,0]
	v_pk_mul_f32 v[76:77], v[76:77], v[190:191] op_sel_hi:[1,0]
	v_pk_mul_f32 v[74:75], v[74:75], v[190:191] op_sel_hi:[1,0]
	v_pk_mul_f32 v[72:73], v[72:73], v[190:191] op_sel_hi:[1,0]
	v_pk_mul_f32 v[70:71], v[70:71], v[190:191] op_sel_hi:[1,0]
	v_pk_mul_f32 v[68:69], v[68:69], v[190:191] op_sel_hi:[1,0]
	v_pk_mul_f32 v[66:67], v[66:67], v[190:191] op_sel_hi:[1,0]
	v_pk_mul_f32 v[64:65], v[64:65], v[190:191] op_sel_hi:[1,0]
	v_pk_mul_f32 v[62:63], v[62:63], v[190:191] op_sel_hi:[1,0]
	v_pk_mul_f32 v[60:61], v[60:61], v[190:191] op_sel_hi:[1,0]
	v_pk_mul_f32 v[58:59], v[58:59], v[190:191] op_sel_hi:[1,0]
	v_pk_mul_f32 v[56:57], v[56:57], v[190:191] op_sel_hi:[1,0]
	v_pk_mul_f32 v[54:55], v[54:55], v[190:191] op_sel_hi:[1,0]
	v_pk_mul_f32 v[52:53], v[52:53], v[190:191] op_sel_hi:[1,0]
	v_pk_mul_f32 v[50:51], v[50:51], v[190:191] op_sel_hi:[1,0]
	v_pk_mul_f32 v[48:49], v[48:49], v[190:191] op_sel_hi:[1,0]
	v_pk_mul_f32 v[46:47], v[46:47], v[190:191] op_sel_hi:[1,0]
	v_pk_mul_f32 v[44:45], v[44:45], v[190:191] op_sel_hi:[1,0]
	v_pk_mul_f32 v[42:43], v[42:43], v[190:191] op_sel_hi:[1,0]
	v_pk_mul_f32 v[40:41], v[40:41], v[190:191] op_sel_hi:[1,0]
	v_pk_mul_f32 v[38:39], v[38:39], v[190:191] op_sel_hi:[1,0]
	v_pk_mul_f32 v[36:37], v[36:37], v[190:191] op_sel_hi:[1,0]
	v_pk_mul_f32 v[34:35], v[34:35], v[190:191] op_sel_hi:[1,0]
	v_pk_mul_f32 v[32:33], v[32:33], v[190:191] op_sel_hi:[1,0]
	v_pk_mul_f32 v[30:31], v[30:31], v[190:191] op_sel_hi:[1,0]
	v_pk_mul_f32 v[28:29], v[28:29], v[190:191] op_sel_hi:[1,0]
	v_pk_mul_f32 v[26:27], v[26:27], v[190:191] op_sel_hi:[1,0]
	v_pk_mul_f32 v[24:25], v[24:25], v[190:191] op_sel_hi:[1,0]
	v_pk_mul_f32 v[22:23], v[22:23], v[190:191] op_sel_hi:[1,0]
	v_pk_mul_f32 v[20:21], v[20:21], v[190:191] op_sel_hi:[1,0]
	v_pk_mul_f32 v[18:19], v[18:19], v[190:191] op_sel_hi:[1,0]
	v_pk_mul_f32 v[16:17], v[16:17], v[190:191] op_sel_hi:[1,0]
	v_pk_mul_f32 v[14:15], v[14:15], v[190:191] op_sel_hi:[1,0]
	v_pk_mul_f32 v[12:13], v[12:13], v[190:191] op_sel_hi:[1,0]
	v_pk_mul_f32 v[10:11], v[10:11], v[190:191] op_sel_hi:[1,0]
	v_pk_mul_f32 v[8:9], v[8:9], v[190:191] op_sel_hi:[1,0]
	v_pk_mul_f32 v[6:7], v[6:7], v[190:191] op_sel_hi:[1,0]
	v_pk_mul_f32 v[4:5], v[4:5], v[190:191] op_sel_hi:[1,0]
	v_pk_mul_f32 v[2:3], v[2:3], v[190:191] op_sel_hi:[1,0]
	v_pk_mul_f32 v[0:1], v[0:1], v[190:191] op_sel_hi:[1,0]
	v_mul_f32_e32 v195, v195, v190
	v_mov_b32_e32 v190, v246

.Latt_pv1_7:
	s_waitcnt lgkmcnt(12)
	v_mfma_f32_32x32x16_bf16 v[112:127], v[206:209], v[242:245], v[112:127]
	ds_read_b64_tr_b16 v[238:239], v221 offset:16640
	ds_read_b64_tr_b16 v[240:241], v221 offset:20736
	s_waitcnt lgkmcnt(12)
	v_mfma_f32_32x32x16_bf16 v[96:111], v[210:213], v[242:245], v[96:111]
	ds_read_b64_tr_b16 v[206:207], v205 offset:24576
	ds_read_b64_tr_b16 v[208:209], v205 offset:28672
	s_cmp_lg_u64 s[8:9], 0
	s_cbranch_scc1 .Latt_nd0_7
	s_sub_i32 s100, s11, 1
	s_cmp_eq_u32 s11, 0
	s_cselect_b32 s100, 2, s100
	s_lshl_b32 s101, s100, 14
	s_add_i32 m0, s36, s101
	s_nop 0
	global_load_lds_dwordx4 v178, s[22:23]
.Latt_nd0_7:
	s_waitcnt lgkmcnt(12)
	v_mfma_f32_32x32x16_bf16 v[80:95], v[214:217], v[242:245], v[80:95]
	ds_read_b64_tr_b16 v[210:211], v218 offset:24576
	ds_read_b64_tr_b16 v[212:213], v218 offset:28672
	s_waitcnt lgkmcnt(12)
	v_mfma_f32_32x32x16_bf16 v[64:79], v[222:225], v[242:245], v[64:79]
	ds_read_b64_tr_b16 v[214:215], v219 offset:24576
	ds_read_b64_tr_b16 v[216:217], v219 offset:28672
	s_cmp_lg_u64 s[8:9], 0
	s_cbranch_scc1 .Latt_nd1_7
	s_add_i32 m0, m0, 0x400
	s_nop 0
	global_load_lds_dwordx4 v180, s[22:23]
.Latt_nd1_7:
	s_waitcnt lgkmcnt(12)
	v_mfma_f32_32x32x16_bf16 v[48:63], v[226:229], v[242:245], v[48:63]
	ds_read_b64_tr_b16 v[222:223], v221 offset:24576
	ds_read_b64_tr_b16 v[224:225], v221 offset:28672
	s_waitcnt lgkmcnt(12)
	v_mfma_f32_32x32x16_bf16 v[32:47], v[230:233], v[242:245], v[32:47]
	ds_read_b64_tr_b16 v[226:227], v205 offset:24832
	ds_read_b64_tr_b16 v[228:229], v205 offset:28928
	s_cmp_lg_u64 s[8:9], 0
	s_cbranch_scc1 .Latt_nd2_7
	s_lshl_b32 s101, s100, 15
	s_add_i32 m0, s37, s101
	s_add_u32 s100, s22, 0xf00
	s_addc_u32 s101, s23, 0
	global_load_lds_dwordx4 v182, s[100:101]

.Latt_slow_7:
	s_lshl_b32 s15, s11, 14
	s_add_i32 s16, s15, 0
	v_add_u32_e32 v207, s16, v196
	ds_read_b128 v[128:131], v207
	v_add_u32_e32 v208, s16, v197
	ds_read_b128 v[210:213], v208
	v_add_u32_e32 v209, s16, v198
	v_lshrrev_b32_e32 v205, 3, v204
	s_add_i32 s17, s14, 31
	v_and_or_b32 v206, v204, 31, s68
	s_cmp_le_i32 s17, s68
	s_waitcnt lgkmcnt(1)
	v_mfma_f32_32x32x16_bf16 v[128:143], v[128:131], v[144:147], 0
	s_waitcnt lgkmcnt(0)
	v_mfma_f32_32x32x16_bf16 v[128:143], v[210:213], v[148:151], v[128:143]
	ds_read_b128 v[212:215], v209
	v_add_u32_e32 v210, s16, v199
	ds_read_b128 v[216:219], v210
	v_add_u32_e32 v211, s16, v200
	s_waitcnt lgkmcnt(1)
	v_mfma_f32_32x32x16_bf16 v[128:143], v[212:215], v[152:155], v[128:143]
	v_add_u32_e32 v213, s16, v201
	v_and_b32_e32 v212, 4, v205
	ds_read_b128 v[222:225], v213
	s_waitcnt lgkmcnt(1)
	v_mfma_f32_32x32x16_bf16 v[128:143], v[216:219], v[156:159], v[128:143]
	ds_read_b128 v[214:217], v211
	s_waitcnt lgkmcnt(0)
	v_mfma_f32_32x32x16_bf16 v[128:143], v[214:217], v[160:163], v[128:143]
	v_add_u32_e32 v214, s16, v202
	ds_read_b128 v[216:219], v214
	v_add_u32_e32 v215, s16, v203
	v_mfma_f32_32x32x16_bf16 v[128:143], v[222:225], v[164:167], v[128:143]
	ds_read_b128 v[222:225], v215
	s_waitcnt lgkmcnt(1)
	v_mfma_f32_32x32x16_bf16 v[128:143], v[216:219], v[168:171], v[128:143]
	s_waitcnt lgkmcnt(0)
	v_mfma_f32_32x32x16_bf16 v[128:143], v[222:225], v[172:175], v[128:143]
	s_cbranch_scc1 .LBB0_1861
	v_add_u32_e32 v205, s14, v212
	v_cmp_lt_i32_e32 vcc, v205, v206
	v_add_u32_e32 v216, 2, v205
	s_nop 7
	v_cndmask_b32_e32 v129, v192, v129, vcc
	v_cmp_le_i32_e32 vcc, v205, v206
	s_nop 1
	v_cndmask_b32_e32 v128, v192, v128, vcc
	v_cmp_le_i32_e32 vcc, v216, v206
	v_add_u32_e32 v216, 3, v205
	s_nop 0
	v_cndmask_b32_e32 v130, v192, v130, vcc
	v_cmp_le_i32_e32 vcc, v216, v206
	v_add_u32_e32 v216, 8, v205
	s_nop 0
	v_cndmask_b32_e32 v131, v192, v131, vcc
	v_cmp_le_i32_e32 vcc, v216, v206
	v_add_u32_e32 v216, 9, v205
	s_nop 0
	v_cndmask_b32_e32 v132, v192, v132, vcc
	v_cmp_le_i32_e32 vcc, v216, v206
	v_add_u32_e32 v216, 10, v205
	s_nop 0
	v_cndmask_b32_e32 v133, v192, v133, vcc
	v_cmp_le_i32_e32 vcc, v216, v206
	v_add_u32_e32 v216, 11, v205
	s_nop 0
	v_cndmask_b32_e32 v134, v192, v134, vcc
	v_cmp_le_i32_e32 vcc, v216, v206
	v_add_u32_e32 v216, 16, v205
	s_nop 0
	v_cndmask_b32_e32 v135, v192, v135, vcc
	v_cmp_le_i32_e32 vcc, v216, v206
	v_add_u32_e32 v216, 17, v205
	s_nop 0
	v_cndmask_b32_e32 v136, v192, v136, vcc
	v_cmp_le_i32_e32 vcc, v216, v206
	v_add_u32_e32 v216, 18, v205
	s_nop 0
	v_cndmask_b32_e32 v137, v192, v137, vcc
	v_cmp_le_i32_e32 vcc, v216, v206
	v_add_u32_e32 v216, 19, v205
	s_nop 0
	v_cndmask_b32_e32 v138, v192, v138, vcc
	v_cmp_le_i32_e32 vcc, v216, v206
	v_add_u32_e32 v216, 24, v205
	s_nop 0
	v_cndmask_b32_e32 v139, v192, v139, vcc
	v_cmp_le_i32_e32 vcc, v216, v206
	v_add_u32_e32 v216, 25, v205
	s_nop 0
	v_cndmask_b32_e32 v140, v192, v140, vcc
	v_cmp_le_i32_e32 vcc, v216, v206
	v_add_u32_e32 v216, 26, v205
	v_add_u32_e32 v205, 27, v205
	v_cndmask_b32_e32 v141, v192, v141, vcc
	v_cmp_le_i32_e32 vcc, v216, v206
	s_nop 1
	v_cndmask_b32_e32 v142, v192, v142, vcc
	v_cmp_le_i32_e32 vcc, v205, v206
	s_nop 1
	v_cndmask_b32_e32 v143, v192, v143, vcc

	.amdhsa_kernel _Z8mega_fwd6Params
		.amdhsa_group_segment_fixed_size 0
		.amdhsa_private_segment_fixed_size 0
		.amdhsa_kernarg_size 496
		.amdhsa_user_sgpr_count 2
		.amdhsa_user_sgpr_dispatch_ptr 0
		.amdhsa_user_sgpr_queue_ptr 0
		.amdhsa_user_sgpr_kernarg_segment_ptr 1
		.amdhsa_user_sgpr_dispatch_id 0
		.amdhsa_user_sgpr_kernarg_preload_length 0
		.amdhsa_user_sgpr_kernarg_preload_offset 0
		.amdhsa_user_sgpr_private_segment_size 0
		.amdhsa_uses_dynamic_stack 0
		.amdhsa_enable_private_segment 0
		.amdhsa_system_sgpr_workgroup_id_x 1
		.amdhsa_system_sgpr_workgroup_id_y 0
		.amdhsa_system_sgpr_workgroup_id_z 0
		.amdhsa_system_sgpr_workgroup_info 0
		.amdhsa_system_vgpr_workitem_id 2
		.amdhsa_next_free_vgpr 256
		.amdhsa_next_free_sgpr 102
		.amdhsa_accum_offset 256
		.amdhsa_reserve_vcc 1
		.amdhsa_float_round_mode_32 0
		.amdhsa_float_round_mode_16_64 0
		.amdhsa_float_denorm_mode_32 3
		.amdhsa_float_denorm_mode_16_64 3
		.amdhsa_dx10_clamp 1
		.amdhsa_ieee_mode 1
		.amdhsa_fp16_overflow 0
		.amdhsa_tg_split 0
		.amdhsa_exception_fp_ieee_invalid_op 0
		.amdhsa_exception_fp_denorm_src 0
		.amdhsa_exception_fp_ieee_div_zero 0
		.amdhsa_exception_fp_ieee_overflow 0
		.amdhsa_exception_fp_ieee_underflow 0
		.amdhsa_exception_fp_ieee_inexact 0
		.amdhsa_exception_int_div_zero 0
	.end_amdhsa_kernel

amdhsa.kernels:
  - .agpr_count:     0
    .args:
      - .offset:         0
        .size:           240
        .value_kind:     by_value
      - .offset:         240
        .size:           4
        .value_kind:     hidden_block_count_x
      - .offset:         244
        .size:           4
        .value_kind:     hidden_block_count_y
      - .offset:         248
        .size:           4
        .value_kind:     hidden_block_count_z
      - .offset:         252
        .size:           2
        .value_kind:     hidden_group_size_x
      - .offset:         254
        .size:           2
        .value_kind:     hidden_group_size_y
      - .offset:         256
        .size:           2
        .value_kind:     hidden_group_size_z
      - .offset:         258
        .size:           2
        .value_kind:     hidden_remainder_x
      - .offset:         260
        .size:           2
        .value_kind:     hidden_remainder_y
      - .offset:         262
        .size:           2
        .value_kind:     hidden_remainder_z
      - .offset:         280
        .size:           8
        .value_kind:     hidden_global_offset_x
      - .offset:         288
        .size:           8
        .value_kind:     hidden_global_offset_y
      - .offset:         296
        .size:           8
        .value_kind:     hidden_global_offset_z
      - .offset:         304
        .size:           2
        .value_kind:     hidden_grid_dims
      - .offset:         328
        .size:           8
        .value_kind:     hidden_multigrid_sync_arg
      - .offset:         360
        .size:           4
        .value_kind:     hidden_dynamic_lds_size
    .group_segment_fixed_size: 0
    .kernarg_segment_align: 8
    .kernarg_segment_size: 496
    .language:       OpenCL C
    .language_version:
      - 2
      - 0
    .max_flat_workgroup_size: 512
    .name:           _Z8mega_fwd6Params
    .private_segment_fixed_size: 0
    .sgpr_count:     108
    .sgpr_spill_count: 49
    .symbol:         _Z8mega_fwd6Params.kd
    .uniform_work_group_size: 1
    .uses_dynamic_stack: false
    .vgpr_count:     256
    .vgpr_spill_count: 0
    .wavefront_size: 64
